# batched rowstats loads + software-pipelined residual epilogues (F/I tiles) with load-only counted vmcnt
# speedup vs baseline: 1.0133x; 1.0133x over previous
; DI float bflo(unsigned u) { return __uint_as_float(u << 16); }
; DI float bfhi(unsigned u) { return __uint_as_float(u & 0xffff0000u); }
; DI int otid() { int t = threadIdx.x; asm volatile("" : "+v"(t)); return t; }
; DI void rowstats_item(const Params& p, int item) {
;   const int tid = otid(), lane = tid & 63, w = tid >> 6;
;   const bf16_t* pb = (const bf16_t*)(p.ws + O_PB);
;   float* st = (float*)(p.ws + O_STAT);
; #pragma unroll 1
;   for (int i = 0; i < 2; ++i) {
;     const int row = item * 16 + w * 2 + i;
;     const bf16_t* pr = pb + (size_t)row * PBW;
;     float sq = 0.f, sk = 0.f;
;     {
;       u32x4 u = *(const u32x4*)(pr + lane * 8);
; #pragma unroll
;       for (int j = 0; j < 4; ++j) { float a = bflo(u[j]), b2 = bfhi(u[j]); sq += a * a + b2 * b2; }
;     }
;     if (lane < 32) {
;       u32x4 u = *(const u32x4*)(pr + 512 + lane * 8);
; #pragma unroll
;       for (int j = 0; j < 4; ++j) { float a = bflo(u[j]), b2 = bfhi(u[j]); sq += a * a + b2 * b2; }
;       u32x4 u2 = *(const u32x4*)(pr + 768 + lane * 8);
; #pragma unroll
;       for (int j = 0; j < 4; ++j) { float a = bflo(u2[j]), b2 = bfhi(u2[j]); sk += a * a + b2 * b2; }
;     }
;     sq = wave_sum(sq); sk = wave_sum(sk);
;     if (lane == 0) { st[row * 2] = rsqrtf(sq * (1.f / 768.f) + EPS); st[row * 2 + 1] = rsqrtf(sk * (1.f / 256.f) + EPS); }
;   }
; }
; __global__ void __launch_bounds__(512, 2) fwd_megakernel(Params p) {
;     ...
;     for (int t = blockIdx.x; t < TT / 16; t += G) rowstats_item(p, t);
.LBB0_403:
	v_readlane_b32 s0, v252, 63
	v_readlane_b32 s1, v253, 0
	v_readlane_b32 s26, v250, 57
	v_readlane_b32 s27, v250, 58
	v_and_b32_e32 v122, 63, v149
	v_lshrrev_b32_e32 v123, 6, v149
	v_lshlrev_b32_e32 v123, 1, v123
	v_lshlrev_b32_e32 v124, 4, v122
	v_xor_b32_e32 v126, 32, v122
	v_lshlrev_b32_e32 v126, 2, v126
	v_xor_b32_e32 v127, 16, v122
	v_lshlrev_b32_e32 v127, 2, v127
	v_xor_b32_e32 v128, 8, v122
	v_lshlrev_b32_e32 v128, 2, v128
	v_xor_b32_e32 v129, 4, v122
	v_lshlrev_b32_e32 v129, 2, v129
	v_xor_b32_e32 v130, 2, v122
	v_lshlrev_b32_e32 v130, 2, v130
	v_xor_b32_e32 v131, 1, v122
	v_lshlrev_b32_e32 v131, 2, v131
	s_lshl_b32 s18, s97, 4
	s_cmp_lt_u32 s97, 0x80
	s_movk_i32 s19, 0x3000
	s_movk_i32 s5, 0x4000
	s_cmp_lt_u32 s97, 0x80
	s_cselect_b32 s19, s5, s19
	s_movk_i32 s4, 0x1600
	s_mov_b32 s40, 0x3aaaaaab
	s_mov_b32 s41, 0x3b800000
	v_add_u32_e32 v125, s18, v123
	v_add_u32_e32 v132, 0x0, v125
	v_add_u32_e32 v133, 0x1, v125
	v_add_u32_e32 v134, 0x1000, v125
	v_add_u32_e32 v135, 0x1001, v125
	v_add_u32_e32 v136, 0x2000, v125
	v_add_u32_e32 v137, 0x2001, v125
	v_add_u32_e32 v138, 0x3000, v125
	v_add_u32_e32 v139, 0x3001, v125
	v_add_u32_e32 v140, s19, v125
	v_add_u32_e32 v141, s19, v125
	v_add_u32_e32 v141, 1, v141
	v_mul_u32_u24_e32 v152, s4, v132
	v_add_u32_e32 v152, v152, v124
	v_mul_u32_u24_e32 v153, s4, v133
	v_add_u32_e32 v153, v153, v124
	v_mul_u32_u24_e32 v154, s4, v134
	v_add_u32_e32 v154, v154, v124
	v_mul_u32_u24_e32 v155, s4, v135
	v_add_u32_e32 v155, v155, v124
	v_mul_u32_u24_e32 v156, s4, v136
	v_add_u32_e32 v156, v156, v124
	v_mul_u32_u24_e32 v157, s4, v137
	v_add_u32_e32 v157, v157, v124
	v_mul_u32_u24_e32 v158, s4, v138
	v_add_u32_e32 v158, v158, v124
	v_mul_u32_u24_e32 v159, s4, v139
	v_add_u32_e32 v159, v159, v124
	v_mul_u32_u24_e32 v160, s4, v140
	v_add_u32_e32 v160, v160, v124
	v_mul_u32_u24_e32 v161, s4, v141
	v_add_u32_e32 v161, v161, v124
	global_load_dwordx4 v[2:5], v152, s[0:1]
	global_load_dwordx4 v[14:17], v153, s[0:1]
	global_load_dwordx4 v[26:29], v154, s[0:1]
	global_load_dwordx4 v[38:41], v155, s[0:1]
	global_load_dwordx4 v[50:53], v156, s[0:1]
	global_load_dwordx4 v[62:65], v157, s[0:1]
	global_load_dwordx4 v[74:77], v158, s[0:1]
	global_load_dwordx4 v[86:89], v159, s[0:1]
	global_load_dwordx4 v[98:101], v160, s[0:1]
	global_load_dwordx4 v[110:113], v161, s[0:1]
	s_mov_b64 s[42:43], exec
	s_mov_b32 s44, -1
	s_mov_b32 s45, 0
	s_mov_b64 exec, s[44:45]
	global_load_dwordx4 v[6:9], v152, s[0:1] offset:1024
	global_load_dwordx4 v[10:13], v152, s[0:1] offset:1536
	global_load_dwordx4 v[18:21], v153, s[0:1] offset:1024
	global_load_dwordx4 v[22:25], v153, s[0:1] offset:1536
	global_load_dwordx4 v[30:33], v154, s[0:1] offset:1024
	global_load_dwordx4 v[34:37], v154, s[0:1] offset:1536
	global_load_dwordx4 v[42:45], v155, s[0:1] offset:1024
	global_load_dwordx4 v[46:49], v155, s[0:1] offset:1536
	global_load_dwordx4 v[54:57], v156, s[0:1] offset:1024
	global_load_dwordx4 v[58:61], v156, s[0:1] offset:1536
	global_load_dwordx4 v[66:69], v157, s[0:1] offset:1024
	global_load_dwordx4 v[70:73], v157, s[0:1] offset:1536
	global_load_dwordx4 v[78:81], v158, s[0:1] offset:1024
	global_load_dwordx4 v[82:85], v158, s[0:1] offset:1536
	global_load_dwordx4 v[90:93], v159, s[0:1] offset:1024
	global_load_dwordx4 v[94:97], v159, s[0:1] offset:1536
	global_load_dwordx4 v[102:105], v160, s[0:1] offset:1024
	global_load_dwordx4 v[106:109], v160, s[0:1] offset:1536
	global_load_dwordx4 v[114:117], v161, s[0:1] offset:1024
	global_load_dwordx4 v[118:121], v161, s[0:1] offset:1536
	s_mov_b64 exec, s[42:43]
	s_waitcnt vmcnt(29)
	v_lshlrev_b32_e32 v0, 16, v2
	v_mul_f32_e32 v162, v0, v0
	v_and_b32_e32 v0, 0xffff0000, v2
	v_fmac_f32_e32 v162, v0, v0
	v_lshlrev_b32_e32 v0, 16, v3
	v_fmac_f32_e32 v162, v0, v0
	v_and_b32_e32 v0, 0xffff0000, v3
	v_fmac_f32_e32 v162, v0, v0
	v_lshlrev_b32_e32 v0, 16, v4
	v_fmac_f32_e32 v162, v0, v0
	v_and_b32_e32 v0, 0xffff0000, v4
	v_fmac_f32_e32 v162, v0, v0
	v_lshlrev_b32_e32 v0, 16, v5
	v_fmac_f32_e32 v162, v0, v0
	v_and_b32_e32 v0, 0xffff0000, v5
	v_fmac_f32_e32 v162, v0, v0
	v_mov_b32_e32 v2, v162
	v_mov_b32_e32 v3, 0
	s_waitcnt vmcnt(28)
	v_lshlrev_b32_e32 v0, 16, v14
	v_mul_f32_e32 v162, v0, v0
	v_and_b32_e32 v0, 0xffff0000, v14
	v_fmac_f32_e32 v162, v0, v0
	v_lshlrev_b32_e32 v0, 16, v15
	v_fmac_f32_e32 v162, v0, v0
	v_and_b32_e32 v0, 0xffff0000, v15
	v_fmac_f32_e32 v162, v0, v0
	v_lshlrev_b32_e32 v0, 16, v16
	v_fmac_f32_e32 v162, v0, v0
	v_and_b32_e32 v0, 0xffff0000, v16
	v_fmac_f32_e32 v162, v0, v0
	v_lshlrev_b32_e32 v0, 16, v17
	v_fmac_f32_e32 v162, v0, v0
	v_and_b32_e32 v0, 0xffff0000, v17
	v_fmac_f32_e32 v162, v0, v0
	v_mov_b32_e32 v14, v162
	v_mov_b32_e32 v15, 0
	s_waitcnt vmcnt(27)
	v_lshlrev_b32_e32 v0, 16, v26
	v_mul_f32_e32 v162, v0, v0
	v_and_b32_e32 v0, 0xffff0000, v26
	v_fmac_f32_e32 v162, v0, v0
	v_lshlrev_b32_e32 v0, 16, v27
	v_fmac_f32_e32 v162, v0, v0
	v_and_b32_e32 v0, 0xffff0000, v27
	v_fmac_f32_e32 v162, v0, v0
	v_lshlrev_b32_e32 v0, 16, v28
	v_fmac_f32_e32 v162, v0, v0
	v_and_b32_e32 v0, 0xffff0000, v28
	v_fmac_f32_e32 v162, v0, v0
	v_lshlrev_b32_e32 v0, 16, v29
	v_fmac_f32_e32 v162, v0, v0
	v_and_b32_e32 v0, 0xffff0000, v29
	v_fmac_f32_e32 v162, v0, v0
	v_mov_b32_e32 v26, v162
	v_mov_b32_e32 v27, 0
	s_waitcnt vmcnt(26)
	v_lshlrev_b32_e32 v0, 16, v38
	v_mul_f32_e32 v162, v0, v0
	v_and_b32_e32 v0, 0xffff0000, v38
	v_fmac_f32_e32 v162, v0, v0
	v_lshlrev_b32_e32 v0, 16, v39
	v_fmac_f32_e32 v162, v0, v0
	v_and_b32_e32 v0, 0xffff0000, v39
	v_fmac_f32_e32 v162, v0, v0
	v_lshlrev_b32_e32 v0, 16, v40
	v_fmac_f32_e32 v162, v0, v0
	v_and_b32_e32 v0, 0xffff0000, v40
	v_fmac_f32_e32 v162, v0, v0
	v_lshlrev_b32_e32 v0, 16, v41
	v_fmac_f32_e32 v162, v0, v0
	v_and_b32_e32 v0, 0xffff0000, v41
	v_fmac_f32_e32 v162, v0, v0
	v_mov_b32_e32 v38, v162
	v_mov_b32_e32 v39, 0
	s_waitcnt vmcnt(25)
; DI float bflo(unsigned u) { return __uint_as_float(u << 16); }
; DI float bfhi(unsigned u) { return __uint_as_float(u & 0xffff0000u); }
; DI int otid() { int t = threadIdx.x; asm volatile("" : "+v"(t)); return t; }
; DI void rowstats_item(const Params& p, int item) {
;   const int tid = otid(), lane = tid & 63, w = tid >> 6;
;   const bf16_t* pb = (const bf16_t*)(p.ws + O_PB);
;   float* st = (float*)(p.ws + O_STAT);
; #pragma unroll 1
;   for (int i = 0; i < 2; ++i) {
;     const int row = item * 16 + w * 2 + i;
;     const bf16_t* pr = pb + (size_t)row * PBW;
;     float sq = 0.f, sk = 0.f;
;     {
;       u32x4 u = *(const u32x4*)(pr + lane * 8);
; #pragma unroll
;       for (int j = 0; j < 4; ++j) { float a = bflo(u[j]), b2 = bfhi(u[j]); sq += a * a + b2 * b2; }
;     }
;     if (lane < 32) {
;       u32x4 u = *(const u32x4*)(pr + 512 + lane * 8);
; #pragma unroll
;       for (int j = 0; j < 4; ++j) { float a = bflo(u[j]), b2 = bfhi(u[j]); sq += a * a + b2 * b2; }
;       u32x4 u2 = *(const u32x4*)(pr + 768 + lane * 8);
; #pragma unroll
;       for (int j = 0; j < 4; ++j) { float a = bflo(u2[j]), b2 = bfhi(u2[j]); sk += a * a + b2 * b2; }
;     }
;     sq = wave_sum(sq); sk = wave_sum(sk);
;     if (lane == 0) { st[row * 2] = rsqrtf(sq * (1.f / 768.f) + EPS); st[row * 2 + 1] = rsqrtf(sk * (1.f / 256.f) + EPS); }
;   }
; }
	v_lshlrev_b32_e32 v0, 16, v50
	v_mul_f32_e32 v162, v0, v0
	v_and_b32_e32 v0, 0xffff0000, v50
	v_fmac_f32_e32 v162, v0, v0
	v_lshlrev_b32_e32 v0, 16, v51
	v_fmac_f32_e32 v162, v0, v0
	v_and_b32_e32 v0, 0xffff0000, v51
	v_fmac_f32_e32 v162, v0, v0
	v_lshlrev_b32_e32 v0, 16, v52
	v_fmac_f32_e32 v162, v0, v0
	v_and_b32_e32 v0, 0xffff0000, v52
	v_fmac_f32_e32 v162, v0, v0
	v_lshlrev_b32_e32 v0, 16, v53
	v_fmac_f32_e32 v162, v0, v0
	v_and_b32_e32 v0, 0xffff0000, v53
	v_fmac_f32_e32 v162, v0, v0
	v_mov_b32_e32 v50, v162
	v_mov_b32_e32 v51, 0
	s_waitcnt vmcnt(24)
	v_lshlrev_b32_e32 v0, 16, v62
	v_mul_f32_e32 v162, v0, v0
	v_and_b32_e32 v0, 0xffff0000, v62
	v_fmac_f32_e32 v162, v0, v0
	v_lshlrev_b32_e32 v0, 16, v63
	v_fmac_f32_e32 v162, v0, v0
	v_and_b32_e32 v0, 0xffff0000, v63
	v_fmac_f32_e32 v162, v0, v0
	v_lshlrev_b32_e32 v0, 16, v64
	v_fmac_f32_e32 v162, v0, v0
	v_and_b32_e32 v0, 0xffff0000, v64
	v_fmac_f32_e32 v162, v0, v0
	v_lshlrev_b32_e32 v0, 16, v65
	v_fmac_f32_e32 v162, v0, v0
	v_and_b32_e32 v0, 0xffff0000, v65
	v_fmac_f32_e32 v162, v0, v0
	v_mov_b32_e32 v62, v162
	v_mov_b32_e32 v63, 0
	s_waitcnt vmcnt(23)
	v_lshlrev_b32_e32 v0, 16, v74
	v_mul_f32_e32 v162, v0, v0
	v_and_b32_e32 v0, 0xffff0000, v74
	v_fmac_f32_e32 v162, v0, v0
	v_lshlrev_b32_e32 v0, 16, v75
	v_fmac_f32_e32 v162, v0, v0
	v_and_b32_e32 v0, 0xffff0000, v75
	v_fmac_f32_e32 v162, v0, v0
	v_lshlrev_b32_e32 v0, 16, v76
	v_fmac_f32_e32 v162, v0, v0
	v_and_b32_e32 v0, 0xffff0000, v76
	v_fmac_f32_e32 v162, v0, v0
	v_lshlrev_b32_e32 v0, 16, v77
	v_fmac_f32_e32 v162, v0, v0
	v_and_b32_e32 v0, 0xffff0000, v77
	v_fmac_f32_e32 v162, v0, v0
	v_mov_b32_e32 v74, v162
	v_mov_b32_e32 v75, 0
	s_waitcnt vmcnt(22)
	v_lshlrev_b32_e32 v0, 16, v86
	v_mul_f32_e32 v162, v0, v0
	v_and_b32_e32 v0, 0xffff0000, v86
	v_fmac_f32_e32 v162, v0, v0
	v_lshlrev_b32_e32 v0, 16, v87
	v_fmac_f32_e32 v162, v0, v0
	v_and_b32_e32 v0, 0xffff0000, v87
	v_fmac_f32_e32 v162, v0, v0
	v_lshlrev_b32_e32 v0, 16, v88
	v_fmac_f32_e32 v162, v0, v0
	v_and_b32_e32 v0, 0xffff0000, v88
	v_fmac_f32_e32 v162, v0, v0
	v_lshlrev_b32_e32 v0, 16, v89
	v_fmac_f32_e32 v162, v0, v0
	v_and_b32_e32 v0, 0xffff0000, v89
	v_fmac_f32_e32 v162, v0, v0
	v_mov_b32_e32 v86, v162
	v_mov_b32_e32 v87, 0
	s_waitcnt vmcnt(21)
	v_lshlrev_b32_e32 v0, 16, v98
	v_mul_f32_e32 v162, v0, v0
	v_and_b32_e32 v0, 0xffff0000, v98
	v_fmac_f32_e32 v162, v0, v0
	v_lshlrev_b32_e32 v0, 16, v99
	v_fmac_f32_e32 v162, v0, v0
	v_and_b32_e32 v0, 0xffff0000, v99
	v_fmac_f32_e32 v162, v0, v0
	v_lshlrev_b32_e32 v0, 16, v100
	v_fmac_f32_e32 v162, v0, v0
	v_and_b32_e32 v0, 0xffff0000, v100
	v_fmac_f32_e32 v162, v0, v0
	v_lshlrev_b32_e32 v0, 16, v101
	v_fmac_f32_e32 v162, v0, v0
	v_and_b32_e32 v0, 0xffff0000, v101
	v_fmac_f32_e32 v162, v0, v0
	v_mov_b32_e32 v98, v162
	v_mov_b32_e32 v99, 0
	s_waitcnt vmcnt(20)
	v_lshlrev_b32_e32 v0, 16, v110
	v_mul_f32_e32 v162, v0, v0
	v_and_b32_e32 v0, 0xffff0000, v110
	v_fmac_f32_e32 v162, v0, v0
	v_lshlrev_b32_e32 v0, 16, v111
	v_fmac_f32_e32 v162, v0, v0
	v_and_b32_e32 v0, 0xffff0000, v111
	v_fmac_f32_e32 v162, v0, v0
	v_lshlrev_b32_e32 v0, 16, v112
	v_fmac_f32_e32 v162, v0, v0
	v_and_b32_e32 v0, 0xffff0000, v112
	v_fmac_f32_e32 v162, v0, v0
	v_lshlrev_b32_e32 v0, 16, v113
	v_fmac_f32_e32 v162, v0, v0
	v_and_b32_e32 v0, 0xffff0000, v113
	v_fmac_f32_e32 v162, v0, v0
	v_mov_b32_e32 v110, v162
	v_mov_b32_e32 v111, 0
	s_mov_b64 exec, s[44:45]
	s_waitcnt vmcnt(18)
	v_lshlrev_b32_e32 v0, 16, v6
	v_fmac_f32_e32 v2, v0, v0
	v_and_b32_e32 v0, 0xffff0000, v6
	v_fmac_f32_e32 v2, v0, v0
	v_lshlrev_b32_e32 v0, 16, v7
	v_fmac_f32_e32 v2, v0, v0
	v_and_b32_e32 v0, 0xffff0000, v7
	v_fmac_f32_e32 v2, v0, v0
	v_lshlrev_b32_e32 v0, 16, v8
	v_fmac_f32_e32 v2, v0, v0
	v_and_b32_e32 v0, 0xffff0000, v8
	v_fmac_f32_e32 v2, v0, v0
	v_lshlrev_b32_e32 v0, 16, v9
	v_fmac_f32_e32 v2, v0, v0
	v_and_b32_e32 v0, 0xffff0000, v9
	v_fmac_f32_e32 v2, v0, v0
	v_lshlrev_b32_e32 v0, 16, v10
	v_fmac_f32_e32 v3, v0, v0
	v_and_b32_e32 v0, 0xffff0000, v10
	v_fmac_f32_e32 v3, v0, v0
	v_lshlrev_b32_e32 v0, 16, v11
	v_fmac_f32_e32 v3, v0, v0
	v_and_b32_e32 v0, 0xffff0000, v11
	v_fmac_f32_e32 v3, v0, v0
	v_lshlrev_b32_e32 v0, 16, v12
	v_fmac_f32_e32 v3, v0, v0
	v_and_b32_e32 v0, 0xffff0000, v12
	v_fmac_f32_e32 v3, v0, v0
	v_lshlrev_b32_e32 v0, 16, v13
	v_fmac_f32_e32 v3, v0, v0
	v_and_b32_e32 v0, 0xffff0000, v13
	v_fmac_f32_e32 v3, v0, v0
	s_waitcnt vmcnt(16)
	v_lshlrev_b32_e32 v0, 16, v18
	v_fmac_f32_e32 v14, v0, v0
	v_and_b32_e32 v0, 0xffff0000, v18
	v_fmac_f32_e32 v14, v0, v0
	v_lshlrev_b32_e32 v0, 16, v19
	v_fmac_f32_e32 v14, v0, v0
	v_and_b32_e32 v0, 0xffff0000, v19
	v_fmac_f32_e32 v14, v0, v0
	v_lshlrev_b32_e32 v0, 16, v20
	v_fmac_f32_e32 v14, v0, v0
	v_and_b32_e32 v0, 0xffff0000, v20
	v_fmac_f32_e32 v14, v0, v0
	v_lshlrev_b32_e32 v0, 16, v21
	v_fmac_f32_e32 v14, v0, v0
	v_and_b32_e32 v0, 0xffff0000, v21
	v_fmac_f32_e32 v14, v0, v0
	v_lshlrev_b32_e32 v0, 16, v22
	v_fmac_f32_e32 v15, v0, v0
	v_and_b32_e32 v0, 0xffff0000, v22
	v_fmac_f32_e32 v15, v0, v0
	v_lshlrev_b32_e32 v0, 16, v23
	v_fmac_f32_e32 v15, v0, v0
	v_and_b32_e32 v0, 0xffff0000, v23
	v_fmac_f32_e32 v15, v0, v0
	v_lshlrev_b32_e32 v0, 16, v24
	v_fmac_f32_e32 v15, v0, v0
	v_and_b32_e32 v0, 0xffff0000, v24
	v_fmac_f32_e32 v15, v0, v0
	v_lshlrev_b32_e32 v0, 16, v25
	v_fmac_f32_e32 v15, v0, v0
	v_and_b32_e32 v0, 0xffff0000, v25
	v_fmac_f32_e32 v15, v0, v0
	s_waitcnt vmcnt(14)
; DI float bflo(unsigned u) { return __uint_as_float(u << 16); }
; DI float bfhi(unsigned u) { return __uint_as_float(u & 0xffff0000u); }
; DI void rowstats_item(const Params& p, int item) {
;     ...
;       for (int j = 0; j < 4; ++j) { float a = bflo(u[j]), b2 = bfhi(u[j]); sq += a * a + b2 * b2; }
;     }
;     if (lane < 32) {
;       u32x4 u = *(const u32x4*)(pr + 512 + lane * 8);
; #pragma unroll
;       for (int j = 0; j < 4; ++j) { float a = bflo(u[j]), b2 = bfhi(u[j]); sq += a * a + b2 * b2; }
;       u32x4 u2 = *(const u32x4*)(pr + 768 + lane * 8);
; #pragma unroll
;       for (int j = 0; j < 4; ++j) { float a = bflo(u2[j]), b2 = bfhi(u2[j]); sk += a * a + b2 * b2; }
	v_lshlrev_b32_e32 v0, 16, v30
	v_fmac_f32_e32 v26, v0, v0
	v_and_b32_e32 v0, 0xffff0000, v30
	v_fmac_f32_e32 v26, v0, v0
	v_lshlrev_b32_e32 v0, 16, v31
	v_fmac_f32_e32 v26, v0, v0
	v_and_b32_e32 v0, 0xffff0000, v31
	v_fmac_f32_e32 v26, v0, v0
	v_lshlrev_b32_e32 v0, 16, v32
	v_fmac_f32_e32 v26, v0, v0
	v_and_b32_e32 v0, 0xffff0000, v32
	v_fmac_f32_e32 v26, v0, v0
	v_lshlrev_b32_e32 v0, 16, v33
	v_fmac_f32_e32 v26, v0, v0
	v_and_b32_e32 v0, 0xffff0000, v33
	v_fmac_f32_e32 v26, v0, v0
	v_lshlrev_b32_e32 v0, 16, v34
	v_fmac_f32_e32 v27, v0, v0
	v_and_b32_e32 v0, 0xffff0000, v34
	v_fmac_f32_e32 v27, v0, v0
	v_lshlrev_b32_e32 v0, 16, v35
	v_fmac_f32_e32 v27, v0, v0
	v_and_b32_e32 v0, 0xffff0000, v35
	v_fmac_f32_e32 v27, v0, v0
	v_lshlrev_b32_e32 v0, 16, v36
	v_fmac_f32_e32 v27, v0, v0
	v_and_b32_e32 v0, 0xffff0000, v36
	v_fmac_f32_e32 v27, v0, v0
	v_lshlrev_b32_e32 v0, 16, v37
	v_fmac_f32_e32 v27, v0, v0
	v_and_b32_e32 v0, 0xffff0000, v37
	v_fmac_f32_e32 v27, v0, v0
	s_waitcnt vmcnt(12)
	v_lshlrev_b32_e32 v0, 16, v42
	v_fmac_f32_e32 v38, v0, v0
	v_and_b32_e32 v0, 0xffff0000, v42
	v_fmac_f32_e32 v38, v0, v0
	v_lshlrev_b32_e32 v0, 16, v43
	v_fmac_f32_e32 v38, v0, v0
	v_and_b32_e32 v0, 0xffff0000, v43
	v_fmac_f32_e32 v38, v0, v0
	v_lshlrev_b32_e32 v0, 16, v44
	v_fmac_f32_e32 v38, v0, v0
	v_and_b32_e32 v0, 0xffff0000, v44
	v_fmac_f32_e32 v38, v0, v0
	v_lshlrev_b32_e32 v0, 16, v45
	v_fmac_f32_e32 v38, v0, v0
	v_and_b32_e32 v0, 0xffff0000, v45
	v_fmac_f32_e32 v38, v0, v0
	v_lshlrev_b32_e32 v0, 16, v46
	v_fmac_f32_e32 v39, v0, v0
	v_and_b32_e32 v0, 0xffff0000, v46
	v_fmac_f32_e32 v39, v0, v0
	v_lshlrev_b32_e32 v0, 16, v47
	v_fmac_f32_e32 v39, v0, v0
	v_and_b32_e32 v0, 0xffff0000, v47
	v_fmac_f32_e32 v39, v0, v0
	v_lshlrev_b32_e32 v0, 16, v48
	v_fmac_f32_e32 v39, v0, v0
	v_and_b32_e32 v0, 0xffff0000, v48
	v_fmac_f32_e32 v39, v0, v0
	v_lshlrev_b32_e32 v0, 16, v49
	v_fmac_f32_e32 v39, v0, v0
	v_and_b32_e32 v0, 0xffff0000, v49
	v_fmac_f32_e32 v39, v0, v0
	s_waitcnt vmcnt(10)
	v_lshlrev_b32_e32 v0, 16, v54
	v_fmac_f32_e32 v50, v0, v0
	v_and_b32_e32 v0, 0xffff0000, v54
	v_fmac_f32_e32 v50, v0, v0
	v_lshlrev_b32_e32 v0, 16, v55
	v_fmac_f32_e32 v50, v0, v0
	v_and_b32_e32 v0, 0xffff0000, v55
	v_fmac_f32_e32 v50, v0, v0
	v_lshlrev_b32_e32 v0, 16, v56
	v_fmac_f32_e32 v50, v0, v0
	v_and_b32_e32 v0, 0xffff0000, v56
	v_fmac_f32_e32 v50, v0, v0
	v_lshlrev_b32_e32 v0, 16, v57
	v_fmac_f32_e32 v50, v0, v0
	v_and_b32_e32 v0, 0xffff0000, v57
	v_fmac_f32_e32 v50, v0, v0
	v_lshlrev_b32_e32 v0, 16, v58
	v_fmac_f32_e32 v51, v0, v0
	v_and_b32_e32 v0, 0xffff0000, v58
	v_fmac_f32_e32 v51, v0, v0
	v_lshlrev_b32_e32 v0, 16, v59
	v_fmac_f32_e32 v51, v0, v0
	v_and_b32_e32 v0, 0xffff0000, v59
	v_fmac_f32_e32 v51, v0, v0
	v_lshlrev_b32_e32 v0, 16, v60
	v_fmac_f32_e32 v51, v0, v0
	v_and_b32_e32 v0, 0xffff0000, v60
	v_fmac_f32_e32 v51, v0, v0
	v_lshlrev_b32_e32 v0, 16, v61
	v_fmac_f32_e32 v51, v0, v0
	v_and_b32_e32 v0, 0xffff0000, v61
	v_fmac_f32_e32 v51, v0, v0
	s_waitcnt vmcnt(8)
	v_lshlrev_b32_e32 v0, 16, v66
	v_fmac_f32_e32 v62, v0, v0
	v_and_b32_e32 v0, 0xffff0000, v66
	v_fmac_f32_e32 v62, v0, v0
	v_lshlrev_b32_e32 v0, 16, v67
	v_fmac_f32_e32 v62, v0, v0
	v_and_b32_e32 v0, 0xffff0000, v67
	v_fmac_f32_e32 v62, v0, v0
	v_lshlrev_b32_e32 v0, 16, v68
	v_fmac_f32_e32 v62, v0, v0
	v_and_b32_e32 v0, 0xffff0000, v68
	v_fmac_f32_e32 v62, v0, v0
	v_lshlrev_b32_e32 v0, 16, v69
	v_fmac_f32_e32 v62, v0, v0
	v_and_b32_e32 v0, 0xffff0000, v69
	v_fmac_f32_e32 v62, v0, v0
	v_lshlrev_b32_e32 v0, 16, v70
	v_fmac_f32_e32 v63, v0, v0
	v_and_b32_e32 v0, 0xffff0000, v70
	v_fmac_f32_e32 v63, v0, v0
	v_lshlrev_b32_e32 v0, 16, v71
	v_fmac_f32_e32 v63, v0, v0
	v_and_b32_e32 v0, 0xffff0000, v71
	v_fmac_f32_e32 v63, v0, v0
	v_lshlrev_b32_e32 v0, 16, v72
	v_fmac_f32_e32 v63, v0, v0
	v_and_b32_e32 v0, 0xffff0000, v72
	v_fmac_f32_e32 v63, v0, v0
	v_lshlrev_b32_e32 v0, 16, v73
	v_fmac_f32_e32 v63, v0, v0
	v_and_b32_e32 v0, 0xffff0000, v73
	v_fmac_f32_e32 v63, v0, v0
	s_waitcnt vmcnt(6)
	v_lshlrev_b32_e32 v0, 16, v78
	v_fmac_f32_e32 v74, v0, v0
	v_and_b32_e32 v0, 0xffff0000, v78
	v_fmac_f32_e32 v74, v0, v0
	v_lshlrev_b32_e32 v0, 16, v79
	v_fmac_f32_e32 v74, v0, v0
	v_and_b32_e32 v0, 0xffff0000, v79
	v_fmac_f32_e32 v74, v0, v0
	v_lshlrev_b32_e32 v0, 16, v80
	v_fmac_f32_e32 v74, v0, v0
	v_and_b32_e32 v0, 0xffff0000, v80
	v_fmac_f32_e32 v74, v0, v0
	v_lshlrev_b32_e32 v0, 16, v81
	v_fmac_f32_e32 v74, v0, v0
	v_and_b32_e32 v0, 0xffff0000, v81
	v_fmac_f32_e32 v74, v0, v0
	v_lshlrev_b32_e32 v0, 16, v82
	v_fmac_f32_e32 v75, v0, v0
	v_and_b32_e32 v0, 0xffff0000, v82
	v_fmac_f32_e32 v75, v0, v0
	v_lshlrev_b32_e32 v0, 16, v83
	v_fmac_f32_e32 v75, v0, v0
	v_and_b32_e32 v0, 0xffff0000, v83
	v_fmac_f32_e32 v75, v0, v0
	v_lshlrev_b32_e32 v0, 16, v84
	v_fmac_f32_e32 v75, v0, v0
	v_and_b32_e32 v0, 0xffff0000, v84
	v_fmac_f32_e32 v75, v0, v0
	v_lshlrev_b32_e32 v0, 16, v85
	v_fmac_f32_e32 v75, v0, v0
	v_and_b32_e32 v0, 0xffff0000, v85
	v_fmac_f32_e32 v75, v0, v0
	s_waitcnt vmcnt(4)
	v_lshlrev_b32_e32 v0, 16, v90
	v_fmac_f32_e32 v86, v0, v0
	v_and_b32_e32 v0, 0xffff0000, v90
	v_fmac_f32_e32 v86, v0, v0
	v_lshlrev_b32_e32 v0, 16, v91
	v_fmac_f32_e32 v86, v0, v0
	v_and_b32_e32 v0, 0xffff0000, v91
	v_fmac_f32_e32 v86, v0, v0
	v_lshlrev_b32_e32 v0, 16, v92
	v_fmac_f32_e32 v86, v0, v0
	v_and_b32_e32 v0, 0xffff0000, v92
	v_fmac_f32_e32 v86, v0, v0
	v_lshlrev_b32_e32 v0, 16, v93
	v_fmac_f32_e32 v86, v0, v0
	v_and_b32_e32 v0, 0xffff0000, v93
	v_fmac_f32_e32 v86, v0, v0
	v_lshlrev_b32_e32 v0, 16, v94
	v_fmac_f32_e32 v87, v0, v0
	v_and_b32_e32 v0, 0xffff0000, v94
	v_fmac_f32_e32 v87, v0, v0
	v_lshlrev_b32_e32 v0, 16, v95
	v_fmac_f32_e32 v87, v0, v0
	v_and_b32_e32 v0, 0xffff0000, v95
	v_fmac_f32_e32 v87, v0, v0
	v_lshlrev_b32_e32 v0, 16, v96
	v_fmac_f32_e32 v87, v0, v0
	v_and_b32_e32 v0, 0xffff0000, v96
	v_fmac_f32_e32 v87, v0, v0
	v_lshlrev_b32_e32 v0, 16, v97
	v_fmac_f32_e32 v87, v0, v0
	v_and_b32_e32 v0, 0xffff0000, v97
	v_fmac_f32_e32 v87, v0, v0
	s_waitcnt vmcnt(2)
; DI float bflo(unsigned u) { return __uint_as_float(u << 16); }
; DI float bfhi(unsigned u) { return __uint_as_float(u & 0xffff0000u); }
; DI float wave_sum(float v) {
; #pragma unroll
;   for (int o = 32; o >= 1; o >>= 1) v += __shfl_xor(v, o);
;   return v;
; DI void rowstats_item(const Params& p, int item) {
;     ...
;       u32x4 u = *(const u32x4*)(pr + 512 + lane * 8);
; #pragma unroll
;       for (int j = 0; j < 4; ++j) { float a = bflo(u[j]), b2 = bfhi(u[j]); sq += a * a + b2 * b2; }
;       u32x4 u2 = *(const u32x4*)(pr + 768 + lane * 8);
; #pragma unroll
;       for (int j = 0; j < 4; ++j) { float a = bflo(u2[j]), b2 = bfhi(u2[j]); sk += a * a + b2 * b2; }
;     }
;     sq = wave_sum(sq); sk = wave_sum(sk);
	v_lshlrev_b32_e32 v0, 16, v102
	v_fmac_f32_e32 v98, v0, v0
	v_and_b32_e32 v0, 0xffff0000, v102
	v_fmac_f32_e32 v98, v0, v0
	v_lshlrev_b32_e32 v0, 16, v103
	v_fmac_f32_e32 v98, v0, v0
	v_and_b32_e32 v0, 0xffff0000, v103
	v_fmac_f32_e32 v98, v0, v0
	v_lshlrev_b32_e32 v0, 16, v104
	v_fmac_f32_e32 v98, v0, v0
	v_and_b32_e32 v0, 0xffff0000, v104
	v_fmac_f32_e32 v98, v0, v0
	v_lshlrev_b32_e32 v0, 16, v105
	v_fmac_f32_e32 v98, v0, v0
	v_and_b32_e32 v0, 0xffff0000, v105
	v_fmac_f32_e32 v98, v0, v0
	v_lshlrev_b32_e32 v0, 16, v106
	v_fmac_f32_e32 v99, v0, v0
	v_and_b32_e32 v0, 0xffff0000, v106
	v_fmac_f32_e32 v99, v0, v0
	v_lshlrev_b32_e32 v0, 16, v107
	v_fmac_f32_e32 v99, v0, v0
	v_and_b32_e32 v0, 0xffff0000, v107
	v_fmac_f32_e32 v99, v0, v0
	v_lshlrev_b32_e32 v0, 16, v108
	v_fmac_f32_e32 v99, v0, v0
	v_and_b32_e32 v0, 0xffff0000, v108
	v_fmac_f32_e32 v99, v0, v0
	v_lshlrev_b32_e32 v0, 16, v109
	v_fmac_f32_e32 v99, v0, v0
	v_and_b32_e32 v0, 0xffff0000, v109
	v_fmac_f32_e32 v99, v0, v0
	s_waitcnt vmcnt(0)
	v_lshlrev_b32_e32 v0, 16, v114
	v_fmac_f32_e32 v110, v0, v0
	v_and_b32_e32 v0, 0xffff0000, v114
	v_fmac_f32_e32 v110, v0, v0
	v_lshlrev_b32_e32 v0, 16, v115
	v_fmac_f32_e32 v110, v0, v0
	v_and_b32_e32 v0, 0xffff0000, v115
	v_fmac_f32_e32 v110, v0, v0
	v_lshlrev_b32_e32 v0, 16, v116
	v_fmac_f32_e32 v110, v0, v0
	v_and_b32_e32 v0, 0xffff0000, v116
	v_fmac_f32_e32 v110, v0, v0
	v_lshlrev_b32_e32 v0, 16, v117
	v_fmac_f32_e32 v110, v0, v0
	v_and_b32_e32 v0, 0xffff0000, v117
	v_fmac_f32_e32 v110, v0, v0
	v_lshlrev_b32_e32 v0, 16, v118
	v_fmac_f32_e32 v111, v0, v0
	v_and_b32_e32 v0, 0xffff0000, v118
	v_fmac_f32_e32 v111, v0, v0
	v_lshlrev_b32_e32 v0, 16, v119
	v_fmac_f32_e32 v111, v0, v0
	v_and_b32_e32 v0, 0xffff0000, v119
	v_fmac_f32_e32 v111, v0, v0
	v_lshlrev_b32_e32 v0, 16, v120
	v_fmac_f32_e32 v111, v0, v0
	v_and_b32_e32 v0, 0xffff0000, v120
	v_fmac_f32_e32 v111, v0, v0
	v_lshlrev_b32_e32 v0, 16, v121
	v_fmac_f32_e32 v111, v0, v0
	v_and_b32_e32 v0, 0xffff0000, v121
	v_fmac_f32_e32 v111, v0, v0
	s_mov_b64 exec, s[42:43]
	ds_bpermute_b32 v6, v126, v2
	ds_bpermute_b32 v7, v126, v3
	ds_bpermute_b32 v18, v126, v14
	ds_bpermute_b32 v19, v126, v15
	ds_bpermute_b32 v30, v126, v26
	ds_bpermute_b32 v31, v126, v27
	ds_bpermute_b32 v42, v126, v38
	ds_bpermute_b32 v43, v126, v39
	ds_bpermute_b32 v54, v126, v50
	ds_bpermute_b32 v55, v126, v51
	s_waitcnt lgkmcnt(0)
	v_add_f32_e32 v2, v2, v6
	v_add_f32_e32 v3, v3, v7
	v_add_f32_e32 v14, v14, v18
	v_add_f32_e32 v15, v15, v19
	v_add_f32_e32 v26, v26, v30
	v_add_f32_e32 v27, v27, v31
	v_add_f32_e32 v38, v38, v42
	v_add_f32_e32 v39, v39, v43
	v_add_f32_e32 v50, v50, v54
	v_add_f32_e32 v51, v51, v55
	ds_bpermute_b32 v66, v126, v62
	ds_bpermute_b32 v67, v126, v63
	ds_bpermute_b32 v78, v126, v74
	ds_bpermute_b32 v79, v126, v75
	ds_bpermute_b32 v90, v126, v86
	ds_bpermute_b32 v91, v126, v87
	ds_bpermute_b32 v102, v126, v98
	ds_bpermute_b32 v103, v126, v99
	ds_bpermute_b32 v114, v126, v110
	ds_bpermute_b32 v115, v126, v111
	s_waitcnt lgkmcnt(0)
	v_add_f32_e32 v62, v62, v66
	v_add_f32_e32 v63, v63, v67
	v_add_f32_e32 v74, v74, v78
	v_add_f32_e32 v75, v75, v79
	v_add_f32_e32 v86, v86, v90
	v_add_f32_e32 v87, v87, v91
	v_add_f32_e32 v98, v98, v102
	v_add_f32_e32 v99, v99, v103
	v_add_f32_e32 v110, v110, v114
	v_add_f32_e32 v111, v111, v115
	ds_bpermute_b32 v6, v127, v2
	ds_bpermute_b32 v7, v127, v3
	ds_bpermute_b32 v18, v127, v14
	ds_bpermute_b32 v19, v127, v15
	ds_bpermute_b32 v30, v127, v26
	ds_bpermute_b32 v31, v127, v27
	ds_bpermute_b32 v42, v127, v38
	ds_bpermute_b32 v43, v127, v39
	ds_bpermute_b32 v54, v127, v50
	ds_bpermute_b32 v55, v127, v51
	s_waitcnt lgkmcnt(0)
	v_add_f32_e32 v2, v2, v6
	v_add_f32_e32 v3, v3, v7
	v_add_f32_e32 v14, v14, v18
	v_add_f32_e32 v15, v15, v19
	v_add_f32_e32 v26, v26, v30
	v_add_f32_e32 v27, v27, v31
	v_add_f32_e32 v38, v38, v42
	v_add_f32_e32 v39, v39, v43
	v_add_f32_e32 v50, v50, v54
	v_add_f32_e32 v51, v51, v55
	ds_bpermute_b32 v66, v127, v62
	ds_bpermute_b32 v67, v127, v63
	ds_bpermute_b32 v78, v127, v74
	ds_bpermute_b32 v79, v127, v75
	ds_bpermute_b32 v90, v127, v86
	ds_bpermute_b32 v91, v127, v87
	ds_bpermute_b32 v102, v127, v98
	ds_bpermute_b32 v103, v127, v99
	ds_bpermute_b32 v114, v127, v110
	ds_bpermute_b32 v115, v127, v111
	s_waitcnt lgkmcnt(0)
	v_add_f32_e32 v62, v62, v66
	v_add_f32_e32 v63, v63, v67
	v_add_f32_e32 v74, v74, v78
	v_add_f32_e32 v75, v75, v79
	v_add_f32_e32 v86, v86, v90
	v_add_f32_e32 v87, v87, v91
	v_add_f32_e32 v98, v98, v102
	v_add_f32_e32 v99, v99, v103
	v_add_f32_e32 v110, v110, v114
	v_add_f32_e32 v111, v111, v115
	ds_bpermute_b32 v6, v128, v2
	ds_bpermute_b32 v7, v128, v3
	ds_bpermute_b32 v18, v128, v14
	ds_bpermute_b32 v19, v128, v15
	ds_bpermute_b32 v30, v128, v26
	ds_bpermute_b32 v31, v128, v27
	ds_bpermute_b32 v42, v128, v38
	ds_bpermute_b32 v43, v128, v39
	ds_bpermute_b32 v54, v128, v50
	ds_bpermute_b32 v55, v128, v51
	s_waitcnt lgkmcnt(0)
	v_add_f32_e32 v2, v2, v6
	v_add_f32_e32 v3, v3, v7
	v_add_f32_e32 v14, v14, v18
	v_add_f32_e32 v15, v15, v19
	v_add_f32_e32 v26, v26, v30
	v_add_f32_e32 v27, v27, v31
	v_add_f32_e32 v38, v38, v42
	v_add_f32_e32 v39, v39, v43
	v_add_f32_e32 v50, v50, v54
	v_add_f32_e32 v51, v51, v55
	ds_bpermute_b32 v66, v128, v62
	ds_bpermute_b32 v67, v128, v63
	ds_bpermute_b32 v78, v128, v74
	ds_bpermute_b32 v79, v128, v75
	ds_bpermute_b32 v90, v128, v86
	ds_bpermute_b32 v91, v128, v87
	ds_bpermute_b32 v102, v128, v98
	ds_bpermute_b32 v103, v128, v99
	ds_bpermute_b32 v114, v128, v110
	ds_bpermute_b32 v115, v128, v111
	s_waitcnt lgkmcnt(0)
; DI float wave_sum(float v) {
; #pragma unroll
;   for (int o = 32; o >= 1; o >>= 1) v += __shfl_xor(v, o);
;   return v;
; DI void rowstats_item(const Params& p, int item) {
;     ...
;     sq = wave_sum(sq); sk = wave_sum(sk);
;     if (lane == 0) { st[row * 2] = rsqrtf(sq * (1.f / 768.f) + EPS); st[row * 2 + 1] = rsqrtf(sk * (1.f / 256.f) + EPS); }
	v_add_f32_e32 v62, v62, v66
	v_add_f32_e32 v63, v63, v67
	v_add_f32_e32 v74, v74, v78
	v_add_f32_e32 v75, v75, v79
	v_add_f32_e32 v86, v86, v90
	v_add_f32_e32 v87, v87, v91
	v_add_f32_e32 v98, v98, v102
	v_add_f32_e32 v99, v99, v103
	v_add_f32_e32 v110, v110, v114
	v_add_f32_e32 v111, v111, v115
	ds_bpermute_b32 v6, v129, v2
	ds_bpermute_b32 v7, v129, v3
	ds_bpermute_b32 v18, v129, v14
	ds_bpermute_b32 v19, v129, v15
	ds_bpermute_b32 v30, v129, v26
	ds_bpermute_b32 v31, v129, v27
	ds_bpermute_b32 v42, v129, v38
	ds_bpermute_b32 v43, v129, v39
	ds_bpermute_b32 v54, v129, v50
	ds_bpermute_b32 v55, v129, v51
	s_waitcnt lgkmcnt(0)
	v_add_f32_e32 v2, v2, v6
	v_add_f32_e32 v3, v3, v7
	v_add_f32_e32 v14, v14, v18
	v_add_f32_e32 v15, v15, v19
	v_add_f32_e32 v26, v26, v30
	v_add_f32_e32 v27, v27, v31
	v_add_f32_e32 v38, v38, v42
	v_add_f32_e32 v39, v39, v43
	v_add_f32_e32 v50, v50, v54
	v_add_f32_e32 v51, v51, v55
	ds_bpermute_b32 v66, v129, v62
	ds_bpermute_b32 v67, v129, v63
	ds_bpermute_b32 v78, v129, v74
	ds_bpermute_b32 v79, v129, v75
	ds_bpermute_b32 v90, v129, v86
	ds_bpermute_b32 v91, v129, v87
	ds_bpermute_b32 v102, v129, v98
	ds_bpermute_b32 v103, v129, v99
	ds_bpermute_b32 v114, v129, v110
	ds_bpermute_b32 v115, v129, v111
	s_waitcnt lgkmcnt(0)
	v_add_f32_e32 v62, v62, v66
	v_add_f32_e32 v63, v63, v67
	v_add_f32_e32 v74, v74, v78
	v_add_f32_e32 v75, v75, v79
	v_add_f32_e32 v86, v86, v90
	v_add_f32_e32 v87, v87, v91
	v_add_f32_e32 v98, v98, v102
	v_add_f32_e32 v99, v99, v103
	v_add_f32_e32 v110, v110, v114
	v_add_f32_e32 v111, v111, v115
	ds_bpermute_b32 v6, v130, v2
	ds_bpermute_b32 v7, v130, v3
	ds_bpermute_b32 v18, v130, v14
	ds_bpermute_b32 v19, v130, v15
	ds_bpermute_b32 v30, v130, v26
	ds_bpermute_b32 v31, v130, v27
	ds_bpermute_b32 v42, v130, v38
	ds_bpermute_b32 v43, v130, v39
	ds_bpermute_b32 v54, v130, v50
	ds_bpermute_b32 v55, v130, v51
	s_waitcnt lgkmcnt(0)
	v_add_f32_e32 v2, v2, v6
	v_add_f32_e32 v3, v3, v7
	v_add_f32_e32 v14, v14, v18
	v_add_f32_e32 v15, v15, v19
	v_add_f32_e32 v26, v26, v30
	v_add_f32_e32 v27, v27, v31
	v_add_f32_e32 v38, v38, v42
	v_add_f32_e32 v39, v39, v43
	v_add_f32_e32 v50, v50, v54
	v_add_f32_e32 v51, v51, v55
	ds_bpermute_b32 v66, v130, v62
	ds_bpermute_b32 v67, v130, v63
	ds_bpermute_b32 v78, v130, v74
	ds_bpermute_b32 v79, v130, v75
	ds_bpermute_b32 v90, v130, v86
	ds_bpermute_b32 v91, v130, v87
	ds_bpermute_b32 v102, v130, v98
	ds_bpermute_b32 v103, v130, v99
	ds_bpermute_b32 v114, v130, v110
	ds_bpermute_b32 v115, v130, v111
	s_waitcnt lgkmcnt(0)
	v_add_f32_e32 v62, v62, v66
	v_add_f32_e32 v63, v63, v67
	v_add_f32_e32 v74, v74, v78
	v_add_f32_e32 v75, v75, v79
	v_add_f32_e32 v86, v86, v90
	v_add_f32_e32 v87, v87, v91
	v_add_f32_e32 v98, v98, v102
	v_add_f32_e32 v99, v99, v103
	v_add_f32_e32 v110, v110, v114
	v_add_f32_e32 v111, v111, v115
	ds_bpermute_b32 v6, v131, v2
	ds_bpermute_b32 v7, v131, v3
	ds_bpermute_b32 v18, v131, v14
	ds_bpermute_b32 v19, v131, v15
	ds_bpermute_b32 v30, v131, v26
	ds_bpermute_b32 v31, v131, v27
	ds_bpermute_b32 v42, v131, v38
	ds_bpermute_b32 v43, v131, v39
	ds_bpermute_b32 v54, v131, v50
	ds_bpermute_b32 v55, v131, v51
	s_waitcnt lgkmcnt(0)
	v_add_f32_e32 v2, v2, v6
	v_add_f32_e32 v3, v3, v7
	v_add_f32_e32 v14, v14, v18
	v_add_f32_e32 v15, v15, v19
	v_add_f32_e32 v26, v26, v30
	v_add_f32_e32 v27, v27, v31
	v_add_f32_e32 v38, v38, v42
	v_add_f32_e32 v39, v39, v43
	v_add_f32_e32 v50, v50, v54
	v_add_f32_e32 v51, v51, v55
	ds_bpermute_b32 v66, v131, v62
	ds_bpermute_b32 v67, v131, v63
	ds_bpermute_b32 v78, v131, v74
	ds_bpermute_b32 v79, v131, v75
	ds_bpermute_b32 v90, v131, v86
	ds_bpermute_b32 v91, v131, v87
	ds_bpermute_b32 v102, v131, v98
	ds_bpermute_b32 v103, v131, v99
	ds_bpermute_b32 v114, v131, v110
	ds_bpermute_b32 v115, v131, v111
	s_waitcnt lgkmcnt(0)
	v_add_f32_e32 v62, v62, v66
	v_add_f32_e32 v63, v63, v67
	v_add_f32_e32 v74, v74, v78
	v_add_f32_e32 v75, v75, v79
	v_add_f32_e32 v86, v86, v90
	v_add_f32_e32 v87, v87, v91
	v_add_f32_e32 v98, v98, v102
	v_add_f32_e32 v99, v99, v103
	v_add_f32_e32 v110, v110, v114
	v_add_f32_e32 v111, v111, v115
	v_fma_f32 v2, v2, s40, v148
	v_fma_f32 v3, v3, s41, v148
	v_fma_f32 v14, v14, s40, v148
	v_fma_f32 v15, v15, s41, v148
	v_fma_f32 v26, v26, s40, v148
	v_fma_f32 v27, v27, s41, v148
	v_fma_f32 v38, v38, s40, v148
	v_fma_f32 v39, v39, s41, v148
	v_fma_f32 v50, v50, s40, v148
	v_fma_f32 v51, v51, s41, v148
	v_fma_f32 v62, v62, s40, v148
	v_fma_f32 v63, v63, s41, v148
	v_fma_f32 v74, v74, s40, v148
	v_fma_f32 v75, v75, s41, v148
	v_fma_f32 v86, v86, s40, v148
	v_fma_f32 v87, v87, s41, v148
	v_fma_f32 v98, v98, s40, v148
	v_fma_f32 v99, v99, s41, v148
	v_fma_f32 v110, v110, s40, v148
	v_fma_f32 v111, v111, s41, v148
	v_rsq_f32_e32 v2, v2
	v_rsq_f32_e32 v3, v3
	v_lshlrev_b32_e32 v132, 3, v132
	v_rsq_f32_e32 v14, v14
	v_rsq_f32_e32 v15, v15
	v_lshlrev_b32_e32 v133, 3, v133
	v_rsq_f32_e32 v26, v26
	v_rsq_f32_e32 v27, v27
	v_lshlrev_b32_e32 v134, 3, v134
	v_rsq_f32_e32 v38, v38
	v_rsq_f32_e32 v39, v39
	v_lshlrev_b32_e32 v135, 3, v135
	v_rsq_f32_e32 v50, v50
	v_rsq_f32_e32 v51, v51
	v_lshlrev_b32_e32 v136, 3, v136
	v_rsq_f32_e32 v62, v62
	v_rsq_f32_e32 v63, v63
	v_lshlrev_b32_e32 v137, 3, v137
	v_rsq_f32_e32 v74, v74
	v_rsq_f32_e32 v75, v75
	v_lshlrev_b32_e32 v138, 3, v138
	v_rsq_f32_e32 v86, v86
	v_rsq_f32_e32 v87, v87
	v_lshlrev_b32_e32 v139, 3, v139
	v_rsq_f32_e32 v98, v98
	v_rsq_f32_e32 v99, v99
	v_lshlrev_b32_e32 v140, 3, v140
	v_rsq_f32_e32 v110, v110
	v_rsq_f32_e32 v111, v111
	v_lshlrev_b32_e32 v141, 3, v141
	s_mov_b64 exec, 1
	s_nop 3
	global_store_dwordx2 v132, v[2:3], s[26:27]
	global_store_dwordx2 v133, v[14:15], s[26:27]
	global_store_dwordx2 v134, v[26:27], s[26:27]
	global_store_dwordx2 v135, v[38:39], s[26:27]
	global_store_dwordx2 v136, v[50:51], s[26:27]
	global_store_dwordx2 v137, v[62:63], s[26:27]
	global_store_dwordx2 v138, v[74:75], s[26:27]
	global_store_dwordx2 v139, v[86:87], s[26:27]
	global_store_dwordx2 v140, v[98:99], s[26:27]
	global_store_dwordx2 v141, v[110:111], s[26:27]
	s_mov_b64 exec, s[42:43]
	s_branch .LBB0_399

; #define STG_A(P, ptr) do { const bf16_t* _g = (ptr); \
;     __builtin_amdgcn_global_load_lds((const unsigned*)(_g + oa0), (__attribute__((address_space(3))) unsigned*)((P) + tb0), 16, 0, 0); \
;     __builtin_amdgcn_global_load_lds((const unsigned*)(_g + (size_t)64 * lda + oa0), (__attribute__((address_space(3))) unsigned*)((P) + tb1), 16, 0, 0); } while (0)
; #define STG_B(P, ptr) do { const bf16_t* _g = (ptr); \
;     __builtin_amdgcn_global_load_lds((const unsigned*)(_g + ob0), (__attribute__((address_space(3))) unsigned*)((P) + tb0), 16, 0, 0); \
;     __builtin_amdgcn_global_load_lds((const unsigned*)(_g + (size_t)64 * ldb + ob0), (__attribute__((address_space(3))) unsigned*)((P) + tb1), 16, 0, 0); } while (0)
; #define LDA(dst, b, h) _Pragma("unroll") for (int m = 0; m < 4; ++m) _Pragma("unroll") for (int k = 0; k < 2; ++k) \
;     dst[m][k] = *reinterpret_cast<const bf16x8*>(SA(b, h) + lds_byte(wr * 64 + m * 16 + fr, k * 32 + fq * 8))
; #define LDB(dst, b, h) _Pragma("unroll") for (int n = 0; n < 2; ++n) _Pragma("unroll") for (int k = 0; k < 2; ++k) \
;     dst[n][k] = *reinterpret_cast<const bf16x8*>(SB(b, h) + lds_byte(wc * 32 + n * 16 + fr, k * 32 + fq * 8))
; #define MMA(ai, bj, At_, Bt_) do { __builtin_amdgcn_s_setprio(1); \
;     _Pragma("unroll") for (int m = 0; m < 4; ++m) _Pragma("unroll") for (int n = 0; n < 2; ++n) _Pragma("unroll") for (int k = 0; k < 2; ++k) \
;       acc[ai][bj][m][n] = __builtin_amdgcn_mfma_f32_16x16x32_bf16(Bt_[n][k], At_[m][k], acc[ai][bj][m][n], 0, 0, 0); \
;     __builtin_amdgcn_s_setprio(0); } while (0)
; #define WAIT_L(n) asm volatile("s_waitcnt lgkmcnt(" #n ")" ::: "memory")
; template <int lda, int ldb, int K, class Gen, class Epi>
; DI void gemm_stream(Gen gen, Epi epi) {
;     ...
;     for (int t = 0; t < nt; t += 2) {
;       const bool wrap = (t + 2 >= nt);
;       const bf16_t* a1 = A + (t + 1) * 64;
;       const bf16_t* a2 = wrap ? An : A + (t + 2) * 64;
;       const bf16_t* b2 = wrap ? Bn : Bt + (t + 2) * 64;
;       LDB(B0, 0, 0); SCHED; LDA(At, 0, 0); STG_A(SA(1, 1), a1 + (size_t)128 * lda);
;       WAIT_L(8); BAR; WAIT_L(0); MMA(0, 0, At, B0); BAR; SCHED;
;       LDB(B1, 0, 1); STG_B(SB(0, 0), b2);
;       BAR; WAIT_L(0); MMA(0, 1, At, B1); BAR;
;       LDA(At, 0, 1); STG_A(SA(0, 0), a2);
;       BAR; WAIT_L(0); MMA(1, 0, At, B0); BAR; SCHED;
;       STG_B(SB(0, 1), b2 + (size_t)128 * ldb);
.LBB0_1305:
	s_add_i32 s19, s19, 2
	ds_read_b128 v[158:161], v147
	ds_read_b128 v[162:165], v147 offset:1024
	ds_read_b128 v[166:169], v147 offset:2048
	ds_read_b128 v[170:173], v147 offset:3072
	s_cmp_gt_u32 s19, 13
	s_cselect_b64 s[0:1], -1, 0
	s_and_b64 vcc, s[0:1], exec
	s_cselect_b32 s30, 0, s26
	s_lshl_b64 s[0:1], s[30:31], 1
	s_add_u32 s40, s42, s0
	s_addc_u32 s41, s43, s1
	v_add_u32_e32 v203, 0xc000, v135
	ds_read_b128 v[174:177], v150
	ds_read_b128 v[178:181], v150 offset:1024
	ds_read_b128 v[182:185], v152
	ds_read_b128 v[186:189], v152 offset:1024
	ds_read_b128 v[204:207], v153
	ds_read_b128 v[208:211], v153 offset:1024
	ds_read_b128 v[212:215], v154
	ds_read_b128 v[216:219], v154 offset:1024
	v_readfirstlane_b32 s27, v203
	v_add_u32_e32 v203, 0xe000, v135
	s_mov_b32 m0, s27
	v_readfirstlane_b32 s27, v203
	global_load_lds_dwordx4 v[132:133], off
	v_lshl_add_u64 v[220:221], v[132:133], 0, s[24:25]
	s_mov_b32 m0, s27
	s_nop 0
	global_load_lds_dwordx4 v[220:221], off
	s_waitcnt lgkmcnt(8)
	s_barrier
	s_waitcnt lgkmcnt(0)
	s_setprio 1
	s_waitcnt lgkmcnt(0)
	v_mfma_f32_16x16x32_bf16 v[126:129], v[158:161], v[174:177], v[126:129]
	v_mfma_f32_16x16x32_bf16 v[122:125], v[166:169], v[174:177], v[122:125]
	v_mfma_f32_16x16x32_bf16 v[110:113], v[158:161], v[182:185], v[110:113]
	v_mfma_f32_16x16x32_bf16 v[106:109], v[166:169], v[182:185], v[106:109]
	v_mfma_f32_16x16x32_bf16 v[94:97], v[158:161], v[204:207], v[94:97]
	v_mfma_f32_16x16x32_bf16 v[90:93], v[166:169], v[204:207], v[90:93]
	v_mfma_f32_16x16x32_bf16 v[78:81], v[158:161], v[212:215], v[78:81]
	v_mfma_f32_16x16x32_bf16 v[74:77], v[166:169], v[212:215], v[74:77]
	v_mfma_f32_16x16x32_bf16 v[126:129], v[162:165], v[178:181], v[126:129]
	v_mfma_f32_16x16x32_bf16 v[122:125], v[170:173], v[178:181], v[122:125]
	v_mfma_f32_16x16x32_bf16 v[110:113], v[162:165], v[186:189], v[110:113]
	v_mfma_f32_16x16x32_bf16 v[106:109], v[170:173], v[186:189], v[106:109]
	v_mfma_f32_16x16x32_bf16 v[94:97], v[162:165], v[208:211], v[94:97]
	v_mfma_f32_16x16x32_bf16 v[90:93], v[170:173], v[208:211], v[90:93]
	v_mfma_f32_16x16x32_bf16 v[78:81], v[162:165], v[216:219], v[78:81]
	v_mfma_f32_16x16x32_bf16 v[74:77], v[170:173], v[216:219], v[74:77]
	s_setprio 0
	s_barrier
	s_add_u32 s0, s4, s0
	s_addc_u32 s1, s5, s1
	v_lshl_add_u64 v[240:241], v[0:1], 1, s[0:1]
	v_readfirstlane_b32 s0, v134
	v_add_u32_e32 v203, 0x2000, v134
	s_mov_b32 m0, s0
	v_readfirstlane_b32 s0, v203
	ds_read_b128 v[220:223], v155
	ds_read_b128 v[224:227], v155 offset:1024
	ds_read_b128 v[228:231], v155 offset:2048
	ds_read_b128 v[232:235], v155 offset:3072
	global_load_lds_dwordx4 v[240:241], off
	v_lshl_add_u64 v[242:243], v[240:241], 0, s[24:25]
	s_mov_b32 m0, s0
	s_nop 0
	global_load_lds_dwordx4 v[242:243], off
	s_barrier
	s_waitcnt lgkmcnt(0)
	s_setprio 1
	s_waitcnt lgkmcnt(0)
	v_mfma_f32_16x16x32_bf16 v[118:121], v[220:223], v[174:177], v[118:121]
	v_mfma_f32_16x16x32_bf16 v[114:117], v[228:231], v[174:177], v[114:117]
	v_mfma_f32_16x16x32_bf16 v[102:105], v[220:223], v[182:185], v[102:105]
	v_mfma_f32_16x16x32_bf16 v[98:101], v[228:231], v[182:185], v[98:101]
	v_mfma_f32_16x16x32_bf16 v[86:89], v[220:223], v[204:207], v[86:89]
	v_mfma_f32_16x16x32_bf16 v[82:85], v[228:231], v[204:207], v[82:85]
	v_mfma_f32_16x16x32_bf16 v[70:73], v[220:223], v[212:215], v[70:73]
	v_mfma_f32_16x16x32_bf16 v[66:69], v[228:231], v[212:215], v[66:69]
	v_mfma_f32_16x16x32_bf16 v[118:121], v[224:227], v[178:181], v[118:121]
	v_mfma_f32_16x16x32_bf16 v[114:117], v[232:235], v[178:181], v[114:117]
	v_mfma_f32_16x16x32_bf16 v[102:105], v[224:227], v[186:189], v[102:105]
	v_mfma_f32_16x16x32_bf16 v[98:101], v[232:235], v[186:189], v[98:101]
	v_mfma_f32_16x16x32_bf16 v[86:89], v[224:227], v[208:211], v[86:89]
	v_mfma_f32_16x16x32_bf16 v[82:85], v[232:235], v[208:211], v[82:85]
	v_mfma_f32_16x16x32_bf16 v[70:73], v[224:227], v[216:219], v[70:73]
	v_mfma_f32_16x16x32_bf16 v[66:69], v[232:235], v[216:219], v[66:69]
	s_setprio 0
	v_readfirstlane_b32 s0, v135
	v_lshl_add_u64 v[242:243], v[130:131], 1, s[40:41]
	s_mov_b32 m0, s0
	v_readfirstlane_b32 s0, v136
	s_barrier
	ds_read_b128 v[174:177], v150 offset:16384
	ds_read_b128 v[178:181], v150 offset:17408
	ds_read_b128 v[182:185], v152 offset:16384
	ds_read_b128 v[186:189], v152 offset:17408
	ds_read_b128 v[204:207], v153 offset:16384
	ds_read_b128 v[208:211], v153 offset:17408
	ds_read_b128 v[212:215], v154 offset:16384
	ds_read_b128 v[216:219], v154 offset:17408
	global_load_lds_dwordx4 v[242:243], off
	v_lshl_add_u64 v[244:245], v[242:243], 0, s[24:25]
	s_mov_b32 m0, s0
	s_nop 0
	global_load_lds_dwordx4 v[244:245], off
	s_barrier
	s_waitcnt lgkmcnt(0)
	s_setprio 1
	s_waitcnt lgkmcnt(0)
	v_mfma_f32_16x16x32_bf16 v[62:65], v[158:161], v[174:177], v[62:65]
	v_mfma_f32_16x16x32_bf16 v[58:61], v[166:169], v[174:177], v[58:61]
	v_mfma_f32_16x16x32_bf16 v[46:49], v[158:161], v[182:185], v[46:49]
	v_mfma_f32_16x16x32_bf16 v[42:45], v[166:169], v[182:185], v[42:45]
	v_mfma_f32_16x16x32_bf16 v[30:33], v[158:161], v[204:207], v[30:33]
	v_mfma_f32_16x16x32_bf16 v[26:29], v[166:169], v[204:207], v[26:29]
	v_mfma_f32_16x16x32_bf16 v[14:17], v[158:161], v[212:215], v[14:17]
	v_mfma_f32_16x16x32_bf16 v[10:13], v[166:169], v[212:215], v[10:13]
	v_mfma_f32_16x16x32_bf16 v[62:65], v[162:165], v[178:181], v[62:65]
	v_mfma_f32_16x16x32_bf16 v[58:61], v[170:173], v[178:181], v[58:61]
	v_mfma_f32_16x16x32_bf16 v[46:49], v[162:165], v[186:189], v[46:49]
	v_mfma_f32_16x16x32_bf16 v[42:45], v[170:173], v[186:189], v[42:45]
	v_mfma_f32_16x16x32_bf16 v[30:33], v[162:165], v[208:211], v[30:33]
	v_mfma_f32_16x16x32_bf16 v[26:29], v[170:173], v[208:211], v[26:29]
	v_mfma_f32_16x16x32_bf16 v[14:17], v[162:165], v[216:219], v[14:17]
	v_mfma_f32_16x16x32_bf16 v[10:13], v[170:173], v[216:219], v[10:13]
	s_setprio 0
	s_barrier
; #define STG_A(P, ptr) do { const bf16_t* _g = (ptr); \
;     __builtin_amdgcn_global_load_lds((const unsigned*)(_g + oa0), (__attribute__((address_space(3))) unsigned*)((P) + tb0), 16, 0, 0); \
;     __builtin_amdgcn_global_load_lds((const unsigned*)(_g + (size_t)64 * lda + oa0), (__attribute__((address_space(3))) unsigned*)((P) + tb1), 16, 0, 0); } while (0)
; #define STG_B(P, ptr) do { const bf16_t* _g = (ptr); \
;     __builtin_amdgcn_global_load_lds((const unsigned*)(_g + ob0), (__attribute__((address_space(3))) unsigned*)((P) + tb0), 16, 0, 0); \
;     __builtin_amdgcn_global_load_lds((const unsigned*)(_g + (size_t)64 * ldb + ob0), (__attribute__((address_space(3))) unsigned*)((P) + tb1), 16, 0, 0); } while (0)
; #define LDA(dst, b, h) _Pragma("unroll") for (int m = 0; m < 4; ++m) _Pragma("unroll") for (int k = 0; k < 2; ++k) \
;     dst[m][k] = *reinterpret_cast<const bf16x8*>(SA(b, h) + lds_byte(wr * 64 + m * 16 + fr, k * 32 + fq * 8))
; #define LDB(dst, b, h) _Pragma("unroll") for (int n = 0; n < 2; ++n) _Pragma("unroll") for (int k = 0; k < 2; ++k) \
;     dst[n][k] = *reinterpret_cast<const bf16x8*>(SB(b, h) + lds_byte(wc * 32 + n * 16 + fr, k * 32 + fq * 8))
; #define MMA(ai, bj, At_, Bt_) do { __builtin_amdgcn_s_setprio(1); \
;     _Pragma("unroll") for (int m = 0; m < 4; ++m) _Pragma("unroll") for (int n = 0; n < 2; ++n) _Pragma("unroll") for (int k = 0; k < 2; ++k) \
;       acc[ai][bj][m][n] = __builtin_amdgcn_mfma_f32_16x16x32_bf16(Bt_[n][k], At_[m][k], acc[ai][bj][m][n], 0, 0, 0); \
;     __builtin_amdgcn_s_setprio(0); } while (0)
; #define WAIT_V(n) asm volatile("s_waitcnt vmcnt(" #n ")" ::: "memory")
; #define WAIT_L(n) asm volatile("s_waitcnt lgkmcnt(" #n ")" ::: "memory")
; #define BAR __builtin_amdgcn_s_barrier()
; #define SCHED __builtin_amdgcn_sched_barrier(0)
; template <int lda, int ldb, int K, class Gen, class Epi>
; DI void gemm_stream(Gen gen, Epi epi) {
;     ...
;       STG_B(SB(0, 1), b2 + (size_t)128 * ldb);
;       WAIT_V(6); BAR; MMA(1, 1, At, B1); BAR;
;       LDB(B0, 1, 0); SCHED; LDA(At, 1, 0); STG_A(SA(0, 1), a2 + (size_t)128 * lda);
;       WAIT_L(8); BAR; WAIT_L(0); MMA(0, 0, At, B0); BAR; SCHED;
;       LDB(B1, 1, 1); STG_B(SB(1, 0), b2 + 64);
;       BAR; WAIT_L(0); MMA(0, 1, At, B1); BAR;
;       LDA(At, 1, 1); STG_A(SA(1, 0), a2 + 64);
	v_readfirstlane_b32 s0, v137
	v_add_u32_e32 v160, 0x2000, v137
	v_lshl_add_u64 v[158:159], v[240:241], 0, s[38:39]
	s_mov_b32 m0, s0
	v_readfirstlane_b32 s0, v160
	global_load_lds_dwordx4 v[158:159], off
	v_lshl_add_u64 v[158:159], v[240:241], 0, s[12:13]
	s_mov_b32 m0, s0
	s_nop 0
	global_load_lds_dwordx4 v[158:159], off
	s_waitcnt vmcnt(6)
	s_barrier
	s_setprio 1
	v_mfma_f32_16x16x32_bf16 v[54:57], v[220:223], v[174:177], v[54:57]
	v_mfma_f32_16x16x32_bf16 v[50:53], v[228:231], v[174:177], v[50:53]
	v_mfma_f32_16x16x32_bf16 v[38:41], v[220:223], v[182:185], v[38:41]
	v_mfma_f32_16x16x32_bf16 v[34:37], v[228:231], v[182:185], v[34:37]
	v_mfma_f32_16x16x32_bf16 v[22:25], v[220:223], v[204:207], v[22:25]
	v_mfma_f32_16x16x32_bf16 v[18:21], v[228:231], v[204:207], v[18:21]
	v_mfma_f32_16x16x32_bf16 v[6:9], v[220:223], v[212:215], v[6:9]
	v_mfma_f32_16x16x32_bf16 v[2:5], v[228:231], v[212:215], v[2:5]
	v_mfma_f32_16x16x32_bf16 v[54:57], v[224:227], v[178:181], v[54:57]
	v_mfma_f32_16x16x32_bf16 v[50:53], v[232:235], v[178:181], v[50:53]
	v_mfma_f32_16x16x32_bf16 v[38:41], v[224:227], v[186:189], v[38:41]
	v_mfma_f32_16x16x32_bf16 v[34:37], v[232:235], v[186:189], v[34:37]
	v_mfma_f32_16x16x32_bf16 v[22:25], v[224:227], v[208:211], v[22:25]
	v_mfma_f32_16x16x32_bf16 v[18:21], v[232:235], v[208:211], v[18:21]
	v_mfma_f32_16x16x32_bf16 v[6:9], v[224:227], v[216:219], v[6:9]
	v_mfma_f32_16x16x32_bf16 v[2:5], v[232:235], v[216:219], v[2:5]
	s_setprio 0
	s_barrier
	ds_read_b128 v[158:161], v156
	ds_read_b128 v[162:165], v156 offset:1024
	ds_read_b128 v[166:169], v156 offset:2048
	ds_read_b128 v[170:173], v156 offset:3072
	v_readfirstlane_b32 s0, v139
	v_lshl_add_u64 v[220:221], v[242:243], 0, s[38:39]
	s_mov_b32 m0, s0
	v_readfirstlane_b32 s0, v140
	ds_read_b128 v[174:177], v150 offset:32768
	ds_read_b128 v[178:181], v150 offset:33792
	ds_read_b128 v[182:185], v152 offset:32768
	ds_read_b128 v[186:189], v152 offset:33792
	ds_read_b128 v[204:207], v153 offset:32768
	ds_read_b128 v[208:211], v153 offset:33792
	ds_read_b128 v[212:215], v154 offset:32768
	ds_read_b128 v[216:219], v154 offset:33792
	global_load_lds_dwordx4 v[220:221], off
	v_lshl_add_u64 v[220:221], v[242:243], 0, s[12:13]
	s_mov_b32 m0, s0
	s_nop 0
	global_load_lds_dwordx4 v[220:221], off
	s_waitcnt lgkmcnt(8)
	s_barrier
	s_waitcnt lgkmcnt(0)
	s_setprio 1
	s_waitcnt lgkmcnt(0)
	v_mfma_f32_16x16x32_bf16 v[126:129], v[158:161], v[174:177], v[126:129]
	v_mfma_f32_16x16x32_bf16 v[122:125], v[166:169], v[174:177], v[122:125]
	v_mfma_f32_16x16x32_bf16 v[110:113], v[158:161], v[182:185], v[110:113]
	v_mfma_f32_16x16x32_bf16 v[106:109], v[166:169], v[182:185], v[106:109]
	v_mfma_f32_16x16x32_bf16 v[94:97], v[158:161], v[204:207], v[94:97]
	v_mfma_f32_16x16x32_bf16 v[90:93], v[166:169], v[204:207], v[90:93]
	v_mfma_f32_16x16x32_bf16 v[78:81], v[158:161], v[212:215], v[78:81]
	v_mfma_f32_16x16x32_bf16 v[74:77], v[166:169], v[212:215], v[74:77]
	v_mfma_f32_16x16x32_bf16 v[126:129], v[162:165], v[178:181], v[126:129]
	v_mfma_f32_16x16x32_bf16 v[122:125], v[170:173], v[178:181], v[122:125]
	v_mfma_f32_16x16x32_bf16 v[110:113], v[162:165], v[186:189], v[110:113]
	v_mfma_f32_16x16x32_bf16 v[106:109], v[170:173], v[186:189], v[106:109]
	v_mfma_f32_16x16x32_bf16 v[94:97], v[162:165], v[208:211], v[94:97]
	v_mfma_f32_16x16x32_bf16 v[90:93], v[170:173], v[208:211], v[90:93]
	v_mfma_f32_16x16x32_bf16 v[78:81], v[162:165], v[216:219], v[78:81]
	v_mfma_f32_16x16x32_bf16 v[74:77], v[170:173], v[216:219], v[74:77]
	s_setprio 0
	s_barrier
	v_readfirstlane_b32 s0, v141
	v_lshl_add_u64 v[244:245], v[240:241], 0, s[34:35]
	s_mov_b32 m0, s0
	v_readfirstlane_b32 s0, v142
	ds_read_b128 v[220:223], v157
	ds_read_b128 v[224:227], v157 offset:1024
	ds_read_b128 v[228:231], v157 offset:2048
	ds_read_b128 v[232:235], v157 offset:3072
	global_load_lds_dwordx4 v[244:245], off
	v_lshl_add_u64 v[244:245], v[240:241], 0, s[10:11]
	s_mov_b32 m0, s0
	s_nop 0
	global_load_lds_dwordx4 v[244:245], off
	s_barrier
	s_waitcnt lgkmcnt(0)
	s_setprio 1
	s_waitcnt lgkmcnt(0)
	v_mfma_f32_16x16x32_bf16 v[118:121], v[220:223], v[174:177], v[118:121]
	v_mfma_f32_16x16x32_bf16 v[114:117], v[228:231], v[174:177], v[114:117]
	v_mfma_f32_16x16x32_bf16 v[102:105], v[220:223], v[182:185], v[102:105]
	v_mfma_f32_16x16x32_bf16 v[98:101], v[228:231], v[182:185], v[98:101]
	v_mfma_f32_16x16x32_bf16 v[86:89], v[220:223], v[204:207], v[86:89]
	v_mfma_f32_16x16x32_bf16 v[82:85], v[228:231], v[204:207], v[82:85]
	v_mfma_f32_16x16x32_bf16 v[70:73], v[220:223], v[212:215], v[70:73]
	v_mfma_f32_16x16x32_bf16 v[66:69], v[228:231], v[212:215], v[66:69]
	v_mfma_f32_16x16x32_bf16 v[118:121], v[224:227], v[178:181], v[118:121]
	v_mfma_f32_16x16x32_bf16 v[114:117], v[232:235], v[178:181], v[114:117]
	v_mfma_f32_16x16x32_bf16 v[102:105], v[224:227], v[186:189], v[102:105]
	v_mfma_f32_16x16x32_bf16 v[98:101], v[232:235], v[186:189], v[98:101]
	v_mfma_f32_16x16x32_bf16 v[86:89], v[224:227], v[208:211], v[86:89]
	v_mfma_f32_16x16x32_bf16 v[82:85], v[232:235], v[208:211], v[82:85]
	v_mfma_f32_16x16x32_bf16 v[70:73], v[224:227], v[216:219], v[70:73]
	v_mfma_f32_16x16x32_bf16 v[66:69], v[232:235], v[216:219], v[66:69]
	s_setprio 0
	v_readfirstlane_b32 s0, v143
	v_lshl_add_u64 v[244:245], v[242:243], 0, s[34:35]
	s_mov_b32 m0, s0
	v_readfirstlane_b32 s0, v144
	s_barrier
	ds_read_b128 v[174:177], v150 offset:49152
	ds_read_b128 v[178:181], v150 offset:50176
	ds_read_b128 v[182:185], v152 offset:49152
	ds_read_b128 v[186:189], v152 offset:50176
	ds_read_b128 v[204:207], v153 offset:49152
	ds_read_b128 v[208:211], v153 offset:50176
	ds_read_b128 v[212:215], v154 offset:49152
	ds_read_b128 v[216:219], v154 offset:50176
	global_load_lds_dwordx4 v[244:245], off
	v_lshl_add_u64 v[242:243], v[242:243], 0, s[10:11]
	s_mov_b32 m0, s0
	s_nop 0
	global_load_lds_dwordx4 v[242:243], off
	s_barrier
; #define STG_A(P, ptr) do { const bf16_t* _g = (ptr); \
;     __builtin_amdgcn_global_load_lds((const unsigned*)(_g + oa0), (__attribute__((address_space(3))) unsigned*)((P) + tb0), 16, 0, 0); \
;     __builtin_amdgcn_global_load_lds((const unsigned*)(_g + (size_t)64 * lda + oa0), (__attribute__((address_space(3))) unsigned*)((P) + tb1), 16, 0, 0); } while (0)
; #define STG_B(P, ptr) do { const bf16_t* _g = (ptr); \
;     __builtin_amdgcn_global_load_lds((const unsigned*)(_g + ob0), (__attribute__((address_space(3))) unsigned*)((P) + tb0), 16, 0, 0); \
;     __builtin_amdgcn_global_load_lds((const unsigned*)(_g + (size_t)64 * ldb + ob0), (__attribute__((address_space(3))) unsigned*)((P) + tb1), 16, 0, 0); } while (0)
; #define LDA(dst, b, h) _Pragma("unroll") for (int m = 0; m < 4; ++m) _Pragma("unroll") for (int k = 0; k < 2; ++k) \
;     dst[m][k] = *reinterpret_cast<const bf16x8*>(SA(b, h) + lds_byte(wr * 64 + m * 16 + fr, k * 32 + fq * 8))
; #define MMA(ai, bj, At_, Bt_) do { __builtin_amdgcn_s_setprio(1); \
;     _Pragma("unroll") for (int m = 0; m < 4; ++m) _Pragma("unroll") for (int n = 0; n < 2; ++n) _Pragma("unroll") for (int k = 0; k < 2; ++k) \
;       acc[ai][bj][m][n] = __builtin_amdgcn_mfma_f32_16x16x32_bf16(Bt_[n][k], At_[m][k], acc[ai][bj][m][n], 0, 0, 0); \
;     __builtin_amdgcn_s_setprio(0); } while (0)
; #define WAIT_V(n) asm volatile("s_waitcnt vmcnt(" #n ")" ::: "memory")
; #define WAIT_L(n) asm volatile("s_waitcnt lgkmcnt(" #n ")" ::: "memory")
; #define BAR __builtin_amdgcn_s_barrier()
; template <int lda, int ldb, int K, class Gen, class Epi>
; DI void gemm_stream(Gen gen, Epi epi) {
;     ...
;       LDA(At, 1, 1); STG_A(SA(1, 0), a2 + 64);
;       BAR; WAIT_L(0); MMA(1, 0, At, B0); BAR; SCHED;
;       STG_B(SB(1, 1), b2 + (size_t)128 * ldb + 64);
;       WAIT_V(6); BAR; MMA(1, 1, At, B1); BAR;
; DI void residual_tile(acc_t& acc, float* X, const float* gate, const float* Xin = nullptr) {
;   const float* xs = Xin ? Xin : X;
;   epi_foreach(acc, [&](int r, int c, f32x4& v0, f32x4& v1) {
;     const f32x4 g0 = *(const f32x4*)(gate + c), g1 = *(const f32x4*)(gate + c + 4);
;     f32x4 x0 = *(const f32x4*)(xs + (size_t)r * DM + c), x1 = *(const f32x4*)(xs + (size_t)r * DM + c + 4);
;     x0 = x0 + g0 * v0; x1 = x1 + g1 * v1;
;     *(f32x4*)(X + (size_t)r * DM + c) = x0; *(f32x4*)(X + (size_t)r * DM + c + 4) = x1;
	s_waitcnt lgkmcnt(0)
	s_setprio 1
	s_waitcnt lgkmcnt(0)
	v_mfma_f32_16x16x32_bf16 v[62:65], v[158:161], v[174:177], v[62:65]
	v_mfma_f32_16x16x32_bf16 v[58:61], v[166:169], v[174:177], v[58:61]
	v_mfma_f32_16x16x32_bf16 v[46:49], v[158:161], v[182:185], v[46:49]
	v_mfma_f32_16x16x32_bf16 v[42:45], v[166:169], v[182:185], v[42:45]
	v_mfma_f32_16x16x32_bf16 v[30:33], v[158:161], v[204:207], v[30:33]
	v_mfma_f32_16x16x32_bf16 v[26:29], v[166:169], v[204:207], v[26:29]
	v_mfma_f32_16x16x32_bf16 v[14:17], v[158:161], v[212:215], v[14:17]
	v_mfma_f32_16x16x32_bf16 v[10:13], v[166:169], v[212:215], v[10:13]
	v_mfma_f32_16x16x32_bf16 v[62:65], v[162:165], v[178:181], v[62:65]
	v_mfma_f32_16x16x32_bf16 v[58:61], v[170:173], v[178:181], v[58:61]
	v_mfma_f32_16x16x32_bf16 v[46:49], v[162:165], v[186:189], v[46:49]
	v_mfma_f32_16x16x32_bf16 v[42:45], v[170:173], v[186:189], v[42:45]
	v_mfma_f32_16x16x32_bf16 v[30:33], v[162:165], v[208:211], v[30:33]
	v_mfma_f32_16x16x32_bf16 v[26:29], v[170:173], v[208:211], v[26:29]
	v_mfma_f32_16x16x32_bf16 v[14:17], v[162:165], v[216:219], v[14:17]
	v_mfma_f32_16x16x32_bf16 v[10:13], v[170:173], v[216:219], v[10:13]
	s_setprio 0
	s_barrier
	v_readfirstlane_b32 s0, v145
	v_lshl_add_u64 v[158:159], v[240:241], 0, s[36:37]
	s_mov_b32 m0, s0
	v_readfirstlane_b32 s0, v146
	global_load_lds_dwordx4 v[158:159], off
	v_lshl_add_u64 v[158:159], v[240:241], 0, s[8:9]
	s_mov_b32 m0, s0
	s_nop 0
	global_load_lds_dwordx4 v[158:159], off
	s_waitcnt vmcnt(6)
	s_barrier
	s_setprio 1
	v_mfma_f32_16x16x32_bf16 v[54:57], v[220:223], v[174:177], v[54:57]
	v_mfma_f32_16x16x32_bf16 v[50:53], v[228:231], v[174:177], v[50:53]
	v_mfma_f32_16x16x32_bf16 v[38:41], v[220:223], v[182:185], v[38:41]
	v_mfma_f32_16x16x32_bf16 v[34:37], v[228:231], v[182:185], v[34:37]
	v_mfma_f32_16x16x32_bf16 v[22:25], v[220:223], v[204:207], v[22:25]
	v_mfma_f32_16x16x32_bf16 v[18:21], v[228:231], v[204:207], v[18:21]
	v_mfma_f32_16x16x32_bf16 v[6:9], v[220:223], v[212:215], v[6:9]
	v_mfma_f32_16x16x32_bf16 v[2:5], v[228:231], v[212:215], v[2:5]
	v_mfma_f32_16x16x32_bf16 v[54:57], v[224:227], v[178:181], v[54:57]
	v_mfma_f32_16x16x32_bf16 v[50:53], v[232:235], v[178:181], v[50:53]
	v_mfma_f32_16x16x32_bf16 v[38:41], v[224:227], v[186:189], v[38:41]
	v_mfma_f32_16x16x32_bf16 v[34:37], v[232:235], v[186:189], v[34:37]
	v_mfma_f32_16x16x32_bf16 v[22:25], v[224:227], v[208:211], v[22:25]
	v_mfma_f32_16x16x32_bf16 v[18:21], v[232:235], v[208:211], v[18:21]
	v_mfma_f32_16x16x32_bf16 v[6:9], v[224:227], v[216:219], v[6:9]
	v_mfma_f32_16x16x32_bf16 v[2:5], v[232:235], v[216:219], v[2:5]
	s_setprio 0
	v_lshl_add_u64 v[132:133], v[132:133], 0, s[44:45]
	s_addk_i32 s26, 0x80
	s_barrier
	s_cbranch_vccz .LBB0_1305
	v_readlane_b32 s0, v248, 6
	s_add_u32 s0, s20, s0
	v_readlane_b32 s4, v251, 54
	s_addc_u32 s1, s21, 0
	s_lshl_b32 s4, s4, 2
	s_add_u32 s0, s0, s4
	v_readlane_b32 s4, v248, 2
	v_mov_b32_e32 v0, v149
	s_addc_u32 s1, s1, 0
	v_readlane_b32 s5, v248, 3
	s_and_b64 s[4:5], s[4:5], exec
	v_and_b32_e32 v130, 15, v0
	v_ashrrev_i32_e32 v131, 2, v0
	v_lshlrev_b32_e32 v0, 1, v0
	v_readlane_b32 s4, v252, 9
	v_and_b32_e32 v0, 0x1e0, v0
	s_cselect_b32 s5, s4, 0
	v_readlane_b32 s4, v252, 8
	s_movk_i32 s19, 0xffc0
	v_lshl_add_u64 v[132:133], s[0:1], 0, v[0:1]
	s_mov_b64 s[0:1], 0x1f52000
	s_cselect_b32 s4, s4, 0
	v_readlane_b32 s26, v252, 6
	v_and_or_b32 v136, v131, s19, v130
	v_lshl_add_u64 v[130:131], v[132:133], 0, s[0:1]
	s_mov_b32 s0, 0x1f52000
	s_cmp_eq_u64 s[4:5], 0
	v_readlane_b32 s27, v252, 7
	v_ashrrev_i32_e32 v137, 31, v136
	v_add_co_u32_e32 v134, vcc, s0, v132
	s_cselect_b32 s5, s27, s5
	s_cselect_b32 s4, s26, s4
	v_addc_co_u32_e32 v135, vcc, 0, v133, vcc
	v_lshlrev_b64 v[132:133], 12, v[136:137]
	v_lshl_add_u64 v[152:153], s[4:5], 0, v[132:133]
	v_lshl_add_u64 v[160:161], v[152:153], 0, v[0:1]
	v_mov_b32_e32 v188, v130
	v_mov_b32_e32 v189, v131
	v_mov_b32_e32 v136, v160
	v_mov_b32_e32 v137, v161
	v_lshl_add_u64 v[134:135], s[26:27], 0, v[132:133]
	v_lshl_add_u64 v[134:135], v[134:135], 0, v[0:1]
	s_nop 0
	global_load_dwordx4 v[152:155], v[188:189], off
	global_load_dwordx4 v[156:159], v[188:189], off offset:16
	global_load_dwordx4 v[160:163], v[188:189], off offset:512
	global_load_dwordx4 v[164:167], v[188:189], off offset:528
	v_mov_b32_e32 v144, v136
	v_mov_b32_e32 v145, v137
	global_load_dwordx4 v[168:171], v[144:145], off
	global_load_dwordx4 v[172:175], v[144:145], off offset:16
	global_load_dwordx4 v[176:179], v[144:145], off offset:512
	global_load_dwordx4 v[180:183], v[144:145], off offset:528
	v_add_co_u32_e32 v146, vcc, 0x10000, v136
	s_nop 1
	v_addc_co_u32_e32 v147, vcc, 0, v137, vcc
	global_load_dwordx4 v[184:187], v[146:147], off
	global_load_dwordx4 v[204:207], v[146:147], off offset:16
	global_load_dwordx4 v[208:211], v[146:147], off offset:512
	global_load_dwordx4 v[212:215], v[146:147], off offset:528
	v_add_co_u32_e32 v144, vcc, 0x20000, v136
	s_nop 1
	v_addc_co_u32_e32 v145, vcc, 0, v137, vcc
	global_load_dwordx4 v[216:219], v[144:145], off
	global_load_dwordx4 v[220:223], v[144:145], off offset:16
	global_load_dwordx4 v[224:227], v[144:145], off offset:512
	global_load_dwordx4 v[228:231], v[144:145], off offset:528
	v_add_co_u32_e32 v146, vcc, 0x30000, v136
	s_nop 1
	v_addc_co_u32_e32 v147, vcc, 0, v137, vcc
	global_load_dwordx4 v[232:235], v[146:147], off
	global_load_dwordx4 v[140:143], v[146:147], off offset:16
	s_waitcnt vmcnt(12)
; DI int otid() { int t = threadIdx.x; asm volatile("" : "+v"(t)); return t; }
; template <class F>
; DI void epi_foreach(acc_t& acc, F f) {
;   const int tid = otid(), wid = tid >> 6, lane = tid & 63, wr = wid >> 2, wc = wid & 3, fr = lane & 15, fq = lane >> 4;
; #pragma unroll
;   for (int ai = 0; ai < 2; ++ai)
; #pragma unroll
;     for (int m = 0; m < 4; ++m) {
; #pragma unroll
;       for (int bj = 0; bj < 2; ++bj) f(ai * 128 + wr * 64 + m * 16 + fr, bj * 128 + wc * 32 + 8 * fq, acc[ai][bj][m][0], acc[ai][bj][m][1]);
;       if (m == 3 && ai == 0) __builtin_amdgcn_sched_barrier(0);
;     }
; DI void residual_tile(acc_t& acc, float* X, const float* gate, const float* Xin = nullptr) {
;     ...
;   epi_foreach(acc, [&](int r, int c, f32x4& v0, f32x4& v1) {
;     const f32x4 g0 = *(const f32x4*)(gate + c), g1 = *(const f32x4*)(gate + c + 4);
;     f32x4 x0 = *(const f32x4*)(xs + (size_t)r * DM + c), x1 = *(const f32x4*)(xs + (size_t)r * DM + c + 4);
;     x0 = x0 + g0 * v0; x1 = x1 + g1 * v1;
;     *(f32x4*)(X + (size_t)r * DM + c) = x0; *(f32x4*)(X + (size_t)r * DM + c + 4) = x1;
;   });
	v_pk_fma_f32 v[126:127], v[126:127], v[152:153], v[168:169]
	v_pk_fma_f32 v[128:129], v[128:129], v[154:155], v[170:171]
	v_pk_fma_f32 v[122:123], v[122:123], v[156:157], v[172:173]
	v_pk_fma_f32 v[124:125], v[124:125], v[158:159], v[174:175]
	v_mov_b32_e32 v130, v134
	v_mov_b32_e32 v131, v135
	global_store_dwordx4 v[130:131], v[126:129], off
	global_store_dwordx4 v[130:131], v[122:125], off offset:16
	v_add_co_u32_e32 v146, vcc, 0x30000, v136
	s_nop 1
	v_addc_co_u32_e32 v147, vcc, 0, v137, vcc
	global_load_dwordx4 v[126:129], v[146:147], off offset:512
	global_load_dwordx4 v[122:125], v[146:147], off offset:528
	s_waitcnt vmcnt(12)
	v_pk_fma_f32 v[118:119], v[118:119], v[160:161], v[176:177]
	v_pk_fma_f32 v[120:121], v[120:121], v[162:163], v[178:179]
	v_pk_fma_f32 v[114:115], v[114:115], v[164:165], v[180:181]
	v_pk_fma_f32 v[116:117], v[116:117], v[166:167], v[182:183]
	global_store_dwordx4 v[130:131], v[118:121], off offset:512
	global_store_dwordx4 v[130:131], v[114:117], off offset:528
	v_add_co_u32_e32 v144, vcc, 0x80000, v136
	s_nop 1
	v_addc_co_u32_e32 v145, vcc, 0, v137, vcc
	global_load_dwordx4 v[118:121], v[144:145], off
	global_load_dwordx4 v[114:117], v[144:145], off offset:16
	s_waitcnt vmcnt(12)
	v_pk_fma_f32 v[110:111], v[110:111], v[152:153], v[184:185]
	v_pk_fma_f32 v[112:113], v[112:113], v[154:155], v[186:187]
	v_pk_fma_f32 v[106:107], v[106:107], v[156:157], v[204:205]
	v_pk_fma_f32 v[108:109], v[108:109], v[158:159], v[206:207]
	v_add_co_u32_e32 v132, vcc, 0x10000, v134
	s_nop 1
	v_addc_co_u32_e32 v133, vcc, 0, v135, vcc
	global_store_dwordx4 v[132:133], v[110:113], off
	global_store_dwordx4 v[132:133], v[106:109], off offset:16
	global_load_dwordx4 v[110:113], v[144:145], off offset:512
	global_load_dwordx4 v[106:109], v[144:145], off offset:528
	s_waitcnt vmcnt(12)
	v_pk_fma_f32 v[102:103], v[102:103], v[160:161], v[208:209]
	v_pk_fma_f32 v[104:105], v[104:105], v[162:163], v[210:211]
	v_pk_fma_f32 v[98:99], v[98:99], v[164:165], v[212:213]
	v_pk_fma_f32 v[100:101], v[100:101], v[166:167], v[214:215]
	global_store_dwordx4 v[132:133], v[102:105], off offset:512
	global_store_dwordx4 v[132:133], v[98:101], off offset:528
	v_add_co_u32_e32 v146, vcc, 0x90000, v136
	s_nop 1
	v_addc_co_u32_e32 v147, vcc, 0, v137, vcc
	global_load_dwordx4 v[102:105], v[146:147], off
	global_load_dwordx4 v[98:101], v[146:147], off offset:16
	s_waitcnt vmcnt(12)
	v_pk_fma_f32 v[94:95], v[94:95], v[152:153], v[216:217]
	v_pk_fma_f32 v[96:97], v[96:97], v[154:155], v[218:219]
	v_pk_fma_f32 v[90:91], v[90:91], v[156:157], v[220:221]
	v_pk_fma_f32 v[92:93], v[92:93], v[158:159], v[222:223]
	v_add_co_u32_e32 v130, vcc, 0x20000, v134
	s_nop 1
	v_addc_co_u32_e32 v131, vcc, 0, v135, vcc
	global_store_dwordx4 v[130:131], v[94:97], off
	global_store_dwordx4 v[130:131], v[90:93], off offset:16
	global_load_dwordx4 v[94:97], v[146:147], off offset:512
	global_load_dwordx4 v[90:93], v[146:147], off offset:528
	s_waitcnt vmcnt(12)
	v_pk_fma_f32 v[86:87], v[86:87], v[160:161], v[224:225]
	v_pk_fma_f32 v[88:89], v[88:89], v[162:163], v[226:227]
	v_pk_fma_f32 v[82:83], v[82:83], v[164:165], v[228:229]
	v_pk_fma_f32 v[84:85], v[84:85], v[166:167], v[230:231]
	global_store_dwordx4 v[130:131], v[86:89], off offset:512
	global_store_dwordx4 v[130:131], v[82:85], off offset:528
	v_add_co_u32_e32 v144, vcc, 0xa0000, v136
	s_nop 1
	v_addc_co_u32_e32 v145, vcc, 0, v137, vcc
	global_load_dwordx4 v[86:89], v[144:145], off
	global_load_dwordx4 v[82:85], v[144:145], off offset:16
	s_waitcnt vmcnt(12)
	v_pk_fma_f32 v[78:79], v[78:79], v[152:153], v[232:233]
	v_pk_fma_f32 v[80:81], v[80:81], v[154:155], v[234:235]
	v_pk_fma_f32 v[74:75], v[74:75], v[156:157], v[140:141]
	v_pk_fma_f32 v[76:77], v[76:77], v[158:159], v[142:143]
	v_add_co_u32_e32 v132, vcc, 0x30000, v134
	s_nop 1
	v_addc_co_u32_e32 v133, vcc, 0, v135, vcc
	global_store_dwordx4 v[132:133], v[78:81], off
	global_store_dwordx4 v[132:133], v[74:77], off offset:16
	global_load_dwordx4 v[78:81], v[144:145], off offset:512
	global_load_dwordx4 v[74:77], v[144:145], off offset:528
	s_waitcnt vmcnt(12)
; #define WAIT_V(n) asm volatile("s_waitcnt vmcnt(" #n ")" ::: "memory")
; #define BAR __builtin_amdgcn_s_barrier()
; template <int lda, int ldb, int K, class Gen, class Epi>
; DI void gemm_stream(Gen gen, Epi epi) {
;     ...
;   WAIT_V(0);
;   if (wr == 0) BAR;
;   BAR;
; DI void residual_tile(acc_t& acc, float* X, const float* gate, const float* Xin = nullptr) {
;     ...
;   epi_foreach(acc, [&](int r, int c, f32x4& v0, f32x4& v1) {
;     const f32x4 g0 = *(const f32x4*)(gate + c), g1 = *(const f32x4*)(gate + c + 4);
;     f32x4 x0 = *(const f32x4*)(xs + (size_t)r * DM + c), x1 = *(const f32x4*)(xs + (size_t)r * DM + c + 4);
;     x0 = x0 + g0 * v0; x1 = x1 + g1 * v1;
;     *(f32x4*)(X + (size_t)r * DM + c) = x0; *(f32x4*)(X + (size_t)r * DM + c + 4) = x1;
;   });
	v_pk_fma_f32 v[70:71], v[70:71], v[160:161], v[126:127]
	v_pk_fma_f32 v[72:73], v[72:73], v[162:163], v[128:129]
	v_pk_fma_f32 v[66:67], v[66:67], v[164:165], v[122:123]
	v_pk_fma_f32 v[68:69], v[68:69], v[166:167], v[124:125]
	global_store_dwordx4 v[132:133], v[70:73], off offset:512
	global_store_dwordx4 v[132:133], v[66:69], off offset:528
	v_add_co_u32_e32 v146, vcc, 0xb0000, v136
	s_nop 1
	v_addc_co_u32_e32 v147, vcc, 0, v137, vcc
	global_load_dwordx4 v[70:73], v[146:147], off
	global_load_dwordx4 v[66:69], v[146:147], off offset:16
	s_waitcnt vmcnt(12)
	v_pk_fma_f32 v[62:63], v[62:63], v[152:153], v[118:119]
	v_pk_fma_f32 v[64:65], v[64:65], v[154:155], v[120:121]
	v_pk_fma_f32 v[58:59], v[58:59], v[156:157], v[114:115]
	v_pk_fma_f32 v[60:61], v[60:61], v[158:159], v[116:117]
	v_add_co_u32_e32 v130, vcc, 0x80000, v134
	s_nop 1
	v_addc_co_u32_e32 v131, vcc, 0, v135, vcc
	global_store_dwordx4 v[130:131], v[62:65], off
	global_store_dwordx4 v[130:131], v[58:61], off offset:16
	global_load_dwordx4 v[62:65], v[146:147], off offset:512
	global_load_dwordx4 v[58:61], v[146:147], off offset:528
	s_waitcnt vmcnt(12)
	v_pk_fma_f32 v[54:55], v[54:55], v[160:161], v[110:111]
	v_pk_fma_f32 v[56:57], v[56:57], v[162:163], v[112:113]
	v_pk_fma_f32 v[50:51], v[50:51], v[164:165], v[106:107]
	v_pk_fma_f32 v[52:53], v[52:53], v[166:167], v[108:109]
	global_store_dwordx4 v[130:131], v[54:57], off offset:512
	global_store_dwordx4 v[130:131], v[50:53], off offset:528
	s_waitcnt vmcnt(10)
	v_pk_fma_f32 v[46:47], v[46:47], v[152:153], v[102:103]
	v_pk_fma_f32 v[48:49], v[48:49], v[154:155], v[104:105]
	v_pk_fma_f32 v[42:43], v[42:43], v[156:157], v[98:99]
	v_pk_fma_f32 v[44:45], v[44:45], v[158:159], v[100:101]
	v_add_co_u32_e32 v132, vcc, 0x90000, v134
	s_nop 1
	v_addc_co_u32_e32 v133, vcc, 0, v135, vcc
	global_store_dwordx4 v[132:133], v[46:49], off
	global_store_dwordx4 v[132:133], v[42:45], off offset:16
	s_waitcnt vmcnt(8)
	v_pk_fma_f32 v[38:39], v[38:39], v[160:161], v[94:95]
	v_pk_fma_f32 v[40:41], v[40:41], v[162:163], v[96:97]
	v_pk_fma_f32 v[34:35], v[34:35], v[164:165], v[90:91]
	v_pk_fma_f32 v[36:37], v[36:37], v[166:167], v[92:93]
	global_store_dwordx4 v[132:133], v[38:41], off offset:512
	global_store_dwordx4 v[132:133], v[34:37], off offset:528
	s_waitcnt vmcnt(6)
	v_pk_fma_f32 v[30:31], v[30:31], v[152:153], v[86:87]
	v_pk_fma_f32 v[32:33], v[32:33], v[154:155], v[88:89]
	v_pk_fma_f32 v[26:27], v[26:27], v[156:157], v[82:83]
	v_pk_fma_f32 v[28:29], v[28:29], v[158:159], v[84:85]
	v_add_co_u32_e32 v130, vcc, 0xa0000, v134
	s_nop 1
	v_addc_co_u32_e32 v131, vcc, 0, v135, vcc
	global_store_dwordx4 v[130:131], v[30:33], off
	global_store_dwordx4 v[130:131], v[26:29], off offset:16
	s_waitcnt vmcnt(4)
	v_pk_fma_f32 v[22:23], v[22:23], v[160:161], v[78:79]
	v_pk_fma_f32 v[24:25], v[24:25], v[162:163], v[80:81]
	v_pk_fma_f32 v[18:19], v[18:19], v[164:165], v[74:75]
	v_pk_fma_f32 v[20:21], v[20:21], v[166:167], v[76:77]
	global_store_dwordx4 v[130:131], v[22:25], off offset:512
	global_store_dwordx4 v[130:131], v[18:21], off offset:528
	s_waitcnt vmcnt(2)
	v_pk_fma_f32 v[14:15], v[14:15], v[152:153], v[70:71]
	v_pk_fma_f32 v[16:17], v[16:17], v[154:155], v[72:73]
	v_pk_fma_f32 v[10:11], v[10:11], v[156:157], v[66:67]
	v_pk_fma_f32 v[12:13], v[12:13], v[158:159], v[68:69]
	v_add_co_u32_e32 v132, vcc, 0xb0000, v134
	s_nop 1
	v_addc_co_u32_e32 v133, vcc, 0, v135, vcc
	global_store_dwordx4 v[132:133], v[14:17], off
	global_store_dwordx4 v[132:133], v[10:13], off offset:16
	s_waitcnt vmcnt(0)
	v_pk_fma_f32 v[6:7], v[6:7], v[160:161], v[62:63]
	v_pk_fma_f32 v[8:9], v[8:9], v[162:163], v[64:65]
	v_pk_fma_f32 v[2:3], v[2:3], v[164:165], v[58:59]
	v_pk_fma_f32 v[4:5], v[4:5], v[166:167], v[60:61]
	global_store_dwordx4 v[132:133], v[6:9], off offset:512
	global_store_dwordx4 v[132:133], v[2:5], off offset:528
	s_movk_i32 s0, 0x100
	v_cmp_gt_u32_e32 vcc, s0, v138
	s_waitcnt vmcnt(0)
	s_and_saveexec_b64 s[4:5], vcc
	s_cbranch_execz .LBB0_1308
	s_barrier

; #define STG_A(P, ptr) do { const bf16_t* _g = (ptr); \
;     __builtin_amdgcn_global_load_lds((const unsigned*)(_g + oa0), (__attribute__((address_space(3))) unsigned*)((P) + tb0), 16, 0, 0); \
;     __builtin_amdgcn_global_load_lds((const unsigned*)(_g + (size_t)64 * lda + oa0), (__attribute__((address_space(3))) unsigned*)((P) + tb1), 16, 0, 0); } while (0)
; #define STG_B(P, ptr) do { const bf16_t* _g = (ptr); \
;     __builtin_amdgcn_global_load_lds((const unsigned*)(_g + ob0), (__attribute__((address_space(3))) unsigned*)((P) + tb0), 16, 0, 0); \
;     __builtin_amdgcn_global_load_lds((const unsigned*)(_g + (size_t)64 * ldb + ob0), (__attribute__((address_space(3))) unsigned*)((P) + tb1), 16, 0, 0); } while (0)
; #define LDA(dst, b, h) _Pragma("unroll") for (int m = 0; m < 4; ++m) _Pragma("unroll") for (int k = 0; k < 2; ++k) \
;     dst[m][k] = *reinterpret_cast<const bf16x8*>(SA(b, h) + lds_byte(wr * 64 + m * 16 + fr, k * 32 + fq * 8))
; #define LDB(dst, b, h) _Pragma("unroll") for (int n = 0; n < 2; ++n) _Pragma("unroll") for (int k = 0; k < 2; ++k) \
;     dst[n][k] = *reinterpret_cast<const bf16x8*>(SB(b, h) + lds_byte(wc * 32 + n * 16 + fr, k * 32 + fq * 8))
; #define MMA(ai, bj, At_, Bt_) do { __builtin_amdgcn_s_setprio(1); \
;     _Pragma("unroll") for (int m = 0; m < 4; ++m) _Pragma("unroll") for (int n = 0; n < 2; ++n) _Pragma("unroll") for (int k = 0; k < 2; ++k) \
;       acc[ai][bj][m][n] = __builtin_amdgcn_mfma_f32_16x16x32_bf16(Bt_[n][k], At_[m][k], acc[ai][bj][m][n], 0, 0, 0); \
;     __builtin_amdgcn_s_setprio(0); } while (0)
; #define WAIT_L(n) asm volatile("s_waitcnt lgkmcnt(" #n ")" ::: "memory")
; template <int lda, int ldb, int K, class Gen, class Epi>
; DI void gemm_stream(Gen gen, Epi epi) {
;     ...
;     for (int t = 0; t < nt; t += 2) {
;       const bool wrap = (t + 2 >= nt);
;       const bf16_t* a1 = A + (t + 1) * 64;
;       const bf16_t* a2 = wrap ? An : A + (t + 2) * 64;
;       const bf16_t* b2 = wrap ? Bn : Bt + (t + 2) * 64;
;       LDB(B0, 0, 0); SCHED; LDA(At, 0, 0); STG_A(SA(1, 1), a1 + (size_t)128 * lda);
;       WAIT_L(8); BAR; WAIT_L(0); MMA(0, 0, At, B0); BAR; SCHED;
;       LDB(B1, 0, 1); STG_B(SB(0, 0), b2);
;       BAR; WAIT_L(0); MMA(0, 1, At, B1); BAR;
;       LDA(At, 0, 1); STG_A(SA(0, 0), a2);
;       BAR; WAIT_L(0); MMA(1, 0, At, B0); BAR; SCHED;
;       STG_B(SB(0, 1), b2 + (size_t)128 * ldb);
.LBB0_1336:
	s_add_i32 s27, s27, 2
	ds_read_b128 v[158:161], v147
	ds_read_b128 v[162:165], v147 offset:1024
	ds_read_b128 v[166:169], v147 offset:2048
	ds_read_b128 v[170:173], v147 offset:3072
	s_cmp_gt_u32 s27, 13
	s_cselect_b64 s[0:1], -1, 0
	s_and_b64 vcc, s[0:1], exec
	s_cselect_b32 s30, 0, s48
	s_lshl_b64 s[0:1], s[30:31], 1
	s_add_u32 s50, s44, s0
	s_addc_u32 s51, s45, s1
	v_add_u32_e32 v203, 0xc000, v135
	ds_read_b128 v[174:177], v150
	ds_read_b128 v[178:181], v150 offset:1024
	ds_read_b128 v[182:185], v152
	ds_read_b128 v[186:189], v152 offset:1024
	ds_read_b128 v[204:207], v153
	ds_read_b128 v[208:211], v153 offset:1024
	ds_read_b128 v[212:215], v154
	ds_read_b128 v[216:219], v154 offset:1024
	v_readfirstlane_b32 s30, v203
	v_add_u32_e32 v203, 0xe000, v135
	s_mov_b32 m0, s30
	v_readfirstlane_b32 s30, v203
	global_load_lds_dwordx4 v[132:133], off
	v_lshl_add_u64 v[220:221], v[132:133], 0, s[24:25]
	s_mov_b32 m0, s30
	s_nop 0
	global_load_lds_dwordx4 v[220:221], off
	s_waitcnt lgkmcnt(8)
	s_barrier
	s_waitcnt lgkmcnt(0)
	s_setprio 1
	s_waitcnt lgkmcnt(0)
	v_mfma_f32_16x16x32_bf16 v[126:129], v[158:161], v[174:177], v[126:129]
	v_mfma_f32_16x16x32_bf16 v[122:125], v[166:169], v[174:177], v[122:125]
	v_mfma_f32_16x16x32_bf16 v[110:113], v[158:161], v[182:185], v[110:113]
	v_mfma_f32_16x16x32_bf16 v[106:109], v[166:169], v[182:185], v[106:109]
	v_mfma_f32_16x16x32_bf16 v[94:97], v[158:161], v[204:207], v[94:97]
	v_mfma_f32_16x16x32_bf16 v[90:93], v[166:169], v[204:207], v[90:93]
	v_mfma_f32_16x16x32_bf16 v[78:81], v[158:161], v[212:215], v[78:81]
	v_mfma_f32_16x16x32_bf16 v[74:77], v[166:169], v[212:215], v[74:77]
	v_mfma_f32_16x16x32_bf16 v[126:129], v[162:165], v[178:181], v[126:129]
	v_mfma_f32_16x16x32_bf16 v[122:125], v[170:173], v[178:181], v[122:125]
	v_mfma_f32_16x16x32_bf16 v[110:113], v[162:165], v[186:189], v[110:113]
	v_mfma_f32_16x16x32_bf16 v[106:109], v[170:173], v[186:189], v[106:109]
	v_mfma_f32_16x16x32_bf16 v[94:97], v[162:165], v[208:211], v[94:97]
	v_mfma_f32_16x16x32_bf16 v[90:93], v[170:173], v[208:211], v[90:93]
	v_mfma_f32_16x16x32_bf16 v[78:81], v[162:165], v[216:219], v[78:81]
	v_mfma_f32_16x16x32_bf16 v[74:77], v[170:173], v[216:219], v[74:77]
	s_setprio 0
	s_barrier
	s_add_u32 s0, s46, s0
	s_addc_u32 s1, s47, s1
	v_lshl_add_u64 v[240:241], v[0:1], 1, s[0:1]
	v_readfirstlane_b32 s0, v134
	v_add_u32_e32 v203, 0x2000, v134
	s_mov_b32 m0, s0
	v_readfirstlane_b32 s0, v203
	ds_read_b128 v[220:223], v155
	ds_read_b128 v[224:227], v155 offset:1024
	ds_read_b128 v[228:231], v155 offset:2048
	ds_read_b128 v[232:235], v155 offset:3072
	global_load_lds_dwordx4 v[240:241], off
	v_lshl_add_u64 v[242:243], v[240:241], 0, s[24:25]
	s_mov_b32 m0, s0
	s_nop 0
	global_load_lds_dwordx4 v[242:243], off
	s_barrier
	s_waitcnt lgkmcnt(0)
	s_setprio 1
	s_waitcnt lgkmcnt(0)
	v_mfma_f32_16x16x32_bf16 v[118:121], v[220:223], v[174:177], v[118:121]
	v_mfma_f32_16x16x32_bf16 v[114:117], v[228:231], v[174:177], v[114:117]
	v_mfma_f32_16x16x32_bf16 v[102:105], v[220:223], v[182:185], v[102:105]
	v_mfma_f32_16x16x32_bf16 v[98:101], v[228:231], v[182:185], v[98:101]
	v_mfma_f32_16x16x32_bf16 v[86:89], v[220:223], v[204:207], v[86:89]
	v_mfma_f32_16x16x32_bf16 v[82:85], v[228:231], v[204:207], v[82:85]
	v_mfma_f32_16x16x32_bf16 v[70:73], v[220:223], v[212:215], v[70:73]
	v_mfma_f32_16x16x32_bf16 v[66:69], v[228:231], v[212:215], v[66:69]
	v_mfma_f32_16x16x32_bf16 v[118:121], v[224:227], v[178:181], v[118:121]
	v_mfma_f32_16x16x32_bf16 v[114:117], v[232:235], v[178:181], v[114:117]
	v_mfma_f32_16x16x32_bf16 v[102:105], v[224:227], v[186:189], v[102:105]
	v_mfma_f32_16x16x32_bf16 v[98:101], v[232:235], v[186:189], v[98:101]
	v_mfma_f32_16x16x32_bf16 v[86:89], v[224:227], v[208:211], v[86:89]
	v_mfma_f32_16x16x32_bf16 v[82:85], v[232:235], v[208:211], v[82:85]
	v_mfma_f32_16x16x32_bf16 v[70:73], v[224:227], v[216:219], v[70:73]
	v_mfma_f32_16x16x32_bf16 v[66:69], v[232:235], v[216:219], v[66:69]
	s_setprio 0
	v_readfirstlane_b32 s0, v135
	v_lshl_add_u64 v[242:243], v[130:131], 1, s[50:51]
	s_mov_b32 m0, s0
	v_readfirstlane_b32 s0, v136
	s_barrier
	ds_read_b128 v[174:177], v150 offset:16384
	ds_read_b128 v[178:181], v150 offset:17408
	ds_read_b128 v[182:185], v152 offset:16384
	ds_read_b128 v[186:189], v152 offset:17408
	ds_read_b128 v[204:207], v153 offset:16384
	ds_read_b128 v[208:211], v153 offset:17408
	ds_read_b128 v[212:215], v154 offset:16384
	ds_read_b128 v[216:219], v154 offset:17408
	global_load_lds_dwordx4 v[242:243], off
	v_lshl_add_u64 v[244:245], v[242:243], 0, s[24:25]
	s_mov_b32 m0, s0
	s_nop 0
	global_load_lds_dwordx4 v[244:245], off
	s_barrier
	s_waitcnt lgkmcnt(0)
	s_setprio 1
	s_waitcnt lgkmcnt(0)
	v_mfma_f32_16x16x32_bf16 v[62:65], v[158:161], v[174:177], v[62:65]
	v_mfma_f32_16x16x32_bf16 v[58:61], v[166:169], v[174:177], v[58:61]
	v_mfma_f32_16x16x32_bf16 v[50:53], v[158:161], v[182:185], v[50:53]
	v_mfma_f32_16x16x32_bf16 v[42:45], v[166:169], v[182:185], v[42:45]
	v_mfma_f32_16x16x32_bf16 v[34:37], v[158:161], v[204:207], v[34:37]
	v_mfma_f32_16x16x32_bf16 v[26:29], v[166:169], v[204:207], v[26:29]
	v_mfma_f32_16x16x32_bf16 v[18:21], v[158:161], v[212:215], v[18:21]
	v_mfma_f32_16x16x32_bf16 v[10:13], v[166:169], v[212:215], v[10:13]
	v_mfma_f32_16x16x32_bf16 v[62:65], v[162:165], v[178:181], v[62:65]
	v_mfma_f32_16x16x32_bf16 v[58:61], v[170:173], v[178:181], v[58:61]
	v_mfma_f32_16x16x32_bf16 v[50:53], v[162:165], v[186:189], v[50:53]
	v_mfma_f32_16x16x32_bf16 v[42:45], v[170:173], v[186:189], v[42:45]
	v_mfma_f32_16x16x32_bf16 v[34:37], v[162:165], v[208:211], v[34:37]
	v_mfma_f32_16x16x32_bf16 v[26:29], v[170:173], v[208:211], v[26:29]
	v_mfma_f32_16x16x32_bf16 v[18:21], v[162:165], v[216:219], v[18:21]
	v_mfma_f32_16x16x32_bf16 v[10:13], v[170:173], v[216:219], v[10:13]
	s_setprio 0
	s_barrier
; #define STG_A(P, ptr) do { const bf16_t* _g = (ptr); \
;     __builtin_amdgcn_global_load_lds((const unsigned*)(_g + oa0), (__attribute__((address_space(3))) unsigned*)((P) + tb0), 16, 0, 0); \
;     __builtin_amdgcn_global_load_lds((const unsigned*)(_g + (size_t)64 * lda + oa0), (__attribute__((address_space(3))) unsigned*)((P) + tb1), 16, 0, 0); } while (0)
; #define STG_B(P, ptr) do { const bf16_t* _g = (ptr); \
;     __builtin_amdgcn_global_load_lds((const unsigned*)(_g + ob0), (__attribute__((address_space(3))) unsigned*)((P) + tb0), 16, 0, 0); \
;     __builtin_amdgcn_global_load_lds((const unsigned*)(_g + (size_t)64 * ldb + ob0), (__attribute__((address_space(3))) unsigned*)((P) + tb1), 16, 0, 0); } while (0)
; #define LDA(dst, b, h) _Pragma("unroll") for (int m = 0; m < 4; ++m) _Pragma("unroll") for (int k = 0; k < 2; ++k) \
;     dst[m][k] = *reinterpret_cast<const bf16x8*>(SA(b, h) + lds_byte(wr * 64 + m * 16 + fr, k * 32 + fq * 8))
; #define LDB(dst, b, h) _Pragma("unroll") for (int n = 0; n < 2; ++n) _Pragma("unroll") for (int k = 0; k < 2; ++k) \
;     dst[n][k] = *reinterpret_cast<const bf16x8*>(SB(b, h) + lds_byte(wc * 32 + n * 16 + fr, k * 32 + fq * 8))
; #define MMA(ai, bj, At_, Bt_) do { __builtin_amdgcn_s_setprio(1); \
;     _Pragma("unroll") for (int m = 0; m < 4; ++m) _Pragma("unroll") for (int n = 0; n < 2; ++n) _Pragma("unroll") for (int k = 0; k < 2; ++k) \
;       acc[ai][bj][m][n] = __builtin_amdgcn_mfma_f32_16x16x32_bf16(Bt_[n][k], At_[m][k], acc[ai][bj][m][n], 0, 0, 0); \
;     __builtin_amdgcn_s_setprio(0); } while (0)
; #define WAIT_V(n) asm volatile("s_waitcnt vmcnt(" #n ")" ::: "memory")
; #define WAIT_L(n) asm volatile("s_waitcnt lgkmcnt(" #n ")" ::: "memory")
; #define BAR __builtin_amdgcn_s_barrier()
; #define SCHED __builtin_amdgcn_sched_barrier(0)
; template <int lda, int ldb, int K, class Gen, class Epi>
; DI void gemm_stream(Gen gen, Epi epi) {
;     ...
;       STG_B(SB(0, 1), b2 + (size_t)128 * ldb);
;       WAIT_V(6); BAR; MMA(1, 1, At, B1); BAR;
;       LDB(B0, 1, 0); SCHED; LDA(At, 1, 0); STG_A(SA(0, 1), a2 + (size_t)128 * lda);
;       WAIT_L(8); BAR; WAIT_L(0); MMA(0, 0, At, B0); BAR; SCHED;
;       LDB(B1, 1, 1); STG_B(SB(1, 0), b2 + 64);
;       BAR; WAIT_L(0); MMA(0, 1, At, B1); BAR;
;       LDA(At, 1, 1); STG_A(SA(1, 0), a2 + 64);
	v_readfirstlane_b32 s0, v137
	v_add_u32_e32 v160, 0x2000, v137
	v_lshl_add_u64 v[158:159], v[240:241], 0, s[38:39]
	s_mov_b32 m0, s0
	v_readfirstlane_b32 s0, v160
	global_load_lds_dwordx4 v[158:159], off
	v_lshl_add_u64 v[158:159], v[240:241], 0, s[12:13]
	s_mov_b32 m0, s0
	s_nop 0
	global_load_lds_dwordx4 v[158:159], off
	s_waitcnt vmcnt(6)
	s_barrier
	s_setprio 1
	v_mfma_f32_16x16x32_bf16 v[54:57], v[220:223], v[174:177], v[54:57]
	v_mfma_f32_16x16x32_bf16 v[46:49], v[228:231], v[174:177], v[46:49]
	v_mfma_f32_16x16x32_bf16 v[38:41], v[220:223], v[182:185], v[38:41]
	v_mfma_f32_16x16x32_bf16 v[30:33], v[228:231], v[182:185], v[30:33]
	v_mfma_f32_16x16x32_bf16 v[22:25], v[220:223], v[204:207], v[22:25]
	v_mfma_f32_16x16x32_bf16 v[14:17], v[228:231], v[204:207], v[14:17]
	v_mfma_f32_16x16x32_bf16 v[6:9], v[220:223], v[212:215], v[6:9]
	v_mfma_f32_16x16x32_bf16 v[2:5], v[228:231], v[212:215], v[2:5]
	v_mfma_f32_16x16x32_bf16 v[54:57], v[224:227], v[178:181], v[54:57]
	v_mfma_f32_16x16x32_bf16 v[46:49], v[232:235], v[178:181], v[46:49]
	v_mfma_f32_16x16x32_bf16 v[38:41], v[224:227], v[186:189], v[38:41]
	v_mfma_f32_16x16x32_bf16 v[30:33], v[232:235], v[186:189], v[30:33]
	v_mfma_f32_16x16x32_bf16 v[22:25], v[224:227], v[208:211], v[22:25]
	v_mfma_f32_16x16x32_bf16 v[14:17], v[232:235], v[208:211], v[14:17]
	v_mfma_f32_16x16x32_bf16 v[6:9], v[224:227], v[216:219], v[6:9]
	v_mfma_f32_16x16x32_bf16 v[2:5], v[232:235], v[216:219], v[2:5]
	s_setprio 0
	s_barrier
	ds_read_b128 v[158:161], v156
	ds_read_b128 v[162:165], v156 offset:1024
	ds_read_b128 v[166:169], v156 offset:2048
	ds_read_b128 v[170:173], v156 offset:3072
	v_readfirstlane_b32 s0, v139
	v_lshl_add_u64 v[220:221], v[242:243], 0, s[38:39]
	s_mov_b32 m0, s0
	v_readfirstlane_b32 s0, v140
	ds_read_b128 v[174:177], v150 offset:32768
	ds_read_b128 v[178:181], v150 offset:33792
	ds_read_b128 v[182:185], v152 offset:32768
	ds_read_b128 v[186:189], v152 offset:33792
	ds_read_b128 v[204:207], v153 offset:32768
	ds_read_b128 v[208:211], v153 offset:33792
	ds_read_b128 v[212:215], v154 offset:32768
	ds_read_b128 v[216:219], v154 offset:33792
	global_load_lds_dwordx4 v[220:221], off
	v_lshl_add_u64 v[220:221], v[242:243], 0, s[12:13]
	s_mov_b32 m0, s0
	s_nop 0
	global_load_lds_dwordx4 v[220:221], off
	s_waitcnt lgkmcnt(8)
	s_barrier
	s_waitcnt lgkmcnt(0)
	s_setprio 1
	s_waitcnt lgkmcnt(0)
	v_mfma_f32_16x16x32_bf16 v[126:129], v[158:161], v[174:177], v[126:129]
	v_mfma_f32_16x16x32_bf16 v[122:125], v[166:169], v[174:177], v[122:125]
	v_mfma_f32_16x16x32_bf16 v[110:113], v[158:161], v[182:185], v[110:113]
	v_mfma_f32_16x16x32_bf16 v[106:109], v[166:169], v[182:185], v[106:109]
	v_mfma_f32_16x16x32_bf16 v[94:97], v[158:161], v[204:207], v[94:97]
	v_mfma_f32_16x16x32_bf16 v[90:93], v[166:169], v[204:207], v[90:93]
	v_mfma_f32_16x16x32_bf16 v[78:81], v[158:161], v[212:215], v[78:81]
	v_mfma_f32_16x16x32_bf16 v[74:77], v[166:169], v[212:215], v[74:77]
	v_mfma_f32_16x16x32_bf16 v[126:129], v[162:165], v[178:181], v[126:129]
	v_mfma_f32_16x16x32_bf16 v[122:125], v[170:173], v[178:181], v[122:125]
	v_mfma_f32_16x16x32_bf16 v[110:113], v[162:165], v[186:189], v[110:113]
	v_mfma_f32_16x16x32_bf16 v[106:109], v[170:173], v[186:189], v[106:109]
	v_mfma_f32_16x16x32_bf16 v[94:97], v[162:165], v[208:211], v[94:97]
	v_mfma_f32_16x16x32_bf16 v[90:93], v[170:173], v[208:211], v[90:93]
	v_mfma_f32_16x16x32_bf16 v[78:81], v[162:165], v[216:219], v[78:81]
	v_mfma_f32_16x16x32_bf16 v[74:77], v[170:173], v[216:219], v[74:77]
	s_setprio 0
	s_barrier
	v_readfirstlane_b32 s0, v141
	v_lshl_add_u64 v[244:245], v[240:241], 0, s[34:35]
	s_mov_b32 m0, s0
	v_readfirstlane_b32 s0, v142
	ds_read_b128 v[220:223], v157
	ds_read_b128 v[224:227], v157 offset:1024
	ds_read_b128 v[228:231], v157 offset:2048
	ds_read_b128 v[232:235], v157 offset:3072
	global_load_lds_dwordx4 v[244:245], off
	v_lshl_add_u64 v[244:245], v[240:241], 0, s[10:11]
	s_mov_b32 m0, s0
	s_nop 0
	global_load_lds_dwordx4 v[244:245], off
	s_barrier
	s_waitcnt lgkmcnt(0)
	s_setprio 1
	s_waitcnt lgkmcnt(0)
	v_mfma_f32_16x16x32_bf16 v[118:121], v[220:223], v[174:177], v[118:121]
	v_mfma_f32_16x16x32_bf16 v[114:117], v[228:231], v[174:177], v[114:117]
	v_mfma_f32_16x16x32_bf16 v[102:105], v[220:223], v[182:185], v[102:105]
	v_mfma_f32_16x16x32_bf16 v[98:101], v[228:231], v[182:185], v[98:101]
	v_mfma_f32_16x16x32_bf16 v[86:89], v[220:223], v[204:207], v[86:89]
	v_mfma_f32_16x16x32_bf16 v[82:85], v[228:231], v[204:207], v[82:85]
	v_mfma_f32_16x16x32_bf16 v[70:73], v[220:223], v[212:215], v[70:73]
	v_mfma_f32_16x16x32_bf16 v[66:69], v[228:231], v[212:215], v[66:69]
	v_mfma_f32_16x16x32_bf16 v[118:121], v[224:227], v[178:181], v[118:121]
	v_mfma_f32_16x16x32_bf16 v[114:117], v[232:235], v[178:181], v[114:117]
	v_mfma_f32_16x16x32_bf16 v[102:105], v[224:227], v[186:189], v[102:105]
	v_mfma_f32_16x16x32_bf16 v[98:101], v[232:235], v[186:189], v[98:101]
	v_mfma_f32_16x16x32_bf16 v[86:89], v[224:227], v[208:211], v[86:89]
	v_mfma_f32_16x16x32_bf16 v[82:85], v[232:235], v[208:211], v[82:85]
	v_mfma_f32_16x16x32_bf16 v[70:73], v[224:227], v[216:219], v[70:73]
	v_mfma_f32_16x16x32_bf16 v[66:69], v[232:235], v[216:219], v[66:69]
	s_setprio 0
	v_readfirstlane_b32 s0, v143
	v_lshl_add_u64 v[244:245], v[242:243], 0, s[34:35]
	s_mov_b32 m0, s0
	v_readfirstlane_b32 s0, v144
	s_barrier
	ds_read_b128 v[174:177], v150 offset:49152
	ds_read_b128 v[178:181], v150 offset:50176
	ds_read_b128 v[182:185], v152 offset:49152
	ds_read_b128 v[186:189], v152 offset:50176
	ds_read_b128 v[204:207], v153 offset:49152
	ds_read_b128 v[208:211], v153 offset:50176
	ds_read_b128 v[212:215], v154 offset:49152
	ds_read_b128 v[216:219], v154 offset:50176
	global_load_lds_dwordx4 v[244:245], off
	v_lshl_add_u64 v[242:243], v[242:243], 0, s[10:11]
	s_mov_b32 m0, s0
	s_nop 0
	global_load_lds_dwordx4 v[242:243], off
	s_barrier
; #define STG_A(P, ptr) do { const bf16_t* _g = (ptr); \
;     __builtin_amdgcn_global_load_lds((const unsigned*)(_g + oa0), (__attribute__((address_space(3))) unsigned*)((P) + tb0), 16, 0, 0); \
;     __builtin_amdgcn_global_load_lds((const unsigned*)(_g + (size_t)64 * lda + oa0), (__attribute__((address_space(3))) unsigned*)((P) + tb1), 16, 0, 0); } while (0)
; #define STG_B(P, ptr) do { const bf16_t* _g = (ptr); \
;     __builtin_amdgcn_global_load_lds((const unsigned*)(_g + ob0), (__attribute__((address_space(3))) unsigned*)((P) + tb0), 16, 0, 0); \
;     __builtin_amdgcn_global_load_lds((const unsigned*)(_g + (size_t)64 * ldb + ob0), (__attribute__((address_space(3))) unsigned*)((P) + tb1), 16, 0, 0); } while (0)
; #define LDA(dst, b, h) _Pragma("unroll") for (int m = 0; m < 4; ++m) _Pragma("unroll") for (int k = 0; k < 2; ++k) \
;     dst[m][k] = *reinterpret_cast<const bf16x8*>(SA(b, h) + lds_byte(wr * 64 + m * 16 + fr, k * 32 + fq * 8))
; #define MMA(ai, bj, At_, Bt_) do { __builtin_amdgcn_s_setprio(1); \
;     _Pragma("unroll") for (int m = 0; m < 4; ++m) _Pragma("unroll") for (int n = 0; n < 2; ++n) _Pragma("unroll") for (int k = 0; k < 2; ++k) \
;       acc[ai][bj][m][n] = __builtin_amdgcn_mfma_f32_16x16x32_bf16(Bt_[n][k], At_[m][k], acc[ai][bj][m][n], 0, 0, 0); \
;     __builtin_amdgcn_s_setprio(0); } while (0)
; #define WAIT_V(n) asm volatile("s_waitcnt vmcnt(" #n ")" ::: "memory")
; #define WAIT_L(n) asm volatile("s_waitcnt lgkmcnt(" #n ")" ::: "memory")
; #define BAR __builtin_amdgcn_s_barrier()
; template <int lda, int ldb, int K, class Gen, class Epi>
; DI void gemm_stream(Gen gen, Epi epi) {
;     ...
;       LDA(At, 1, 1); STG_A(SA(1, 0), a2 + 64);
;       BAR; WAIT_L(0); MMA(1, 0, At, B0); BAR; SCHED;
;       STG_B(SB(1, 1), b2 + (size_t)128 * ldb + 64);
;       WAIT_V(6); BAR; MMA(1, 1, At, B1); BAR;
; DI void residual_tile(acc_t& acc, float* X, const float* gate, const float* Xin = nullptr) {
;   const float* xs = Xin ? Xin : X;
;   epi_foreach(acc, [&](int r, int c, f32x4& v0, f32x4& v1) {
;     const f32x4 g0 = *(const f32x4*)(gate + c), g1 = *(const f32x4*)(gate + c + 4);
;     f32x4 x0 = *(const f32x4*)(xs + (size_t)r * DM + c), x1 = *(const f32x4*)(xs + (size_t)r * DM + c + 4);
;     x0 = x0 + g0 * v0; x1 = x1 + g1 * v1;
;     *(f32x4*)(X + (size_t)r * DM + c) = x0; *(f32x4*)(X + (size_t)r * DM + c + 4) = x1;
	s_waitcnt lgkmcnt(0)
	s_setprio 1
	s_waitcnt lgkmcnt(0)
	v_mfma_f32_16x16x32_bf16 v[62:65], v[158:161], v[174:177], v[62:65]
	v_mfma_f32_16x16x32_bf16 v[58:61], v[166:169], v[174:177], v[58:61]
	v_mfma_f32_16x16x32_bf16 v[50:53], v[158:161], v[182:185], v[50:53]
	v_mfma_f32_16x16x32_bf16 v[42:45], v[166:169], v[182:185], v[42:45]
	v_mfma_f32_16x16x32_bf16 v[34:37], v[158:161], v[204:207], v[34:37]
	v_mfma_f32_16x16x32_bf16 v[26:29], v[166:169], v[204:207], v[26:29]
	v_mfma_f32_16x16x32_bf16 v[18:21], v[158:161], v[212:215], v[18:21]
	v_mfma_f32_16x16x32_bf16 v[10:13], v[166:169], v[212:215], v[10:13]
	v_mfma_f32_16x16x32_bf16 v[62:65], v[162:165], v[178:181], v[62:65]
	v_mfma_f32_16x16x32_bf16 v[58:61], v[170:173], v[178:181], v[58:61]
	v_mfma_f32_16x16x32_bf16 v[50:53], v[162:165], v[186:189], v[50:53]
	v_mfma_f32_16x16x32_bf16 v[42:45], v[170:173], v[186:189], v[42:45]
	v_mfma_f32_16x16x32_bf16 v[34:37], v[162:165], v[208:211], v[34:37]
	v_mfma_f32_16x16x32_bf16 v[26:29], v[170:173], v[208:211], v[26:29]
	v_mfma_f32_16x16x32_bf16 v[18:21], v[162:165], v[216:219], v[18:21]
	v_mfma_f32_16x16x32_bf16 v[10:13], v[170:173], v[216:219], v[10:13]
	s_setprio 0
	s_barrier
	v_readfirstlane_b32 s0, v145
	v_lshl_add_u64 v[158:159], v[240:241], 0, s[36:37]
	s_mov_b32 m0, s0
	v_readfirstlane_b32 s0, v146
	global_load_lds_dwordx4 v[158:159], off
	v_lshl_add_u64 v[158:159], v[240:241], 0, s[8:9]
	s_mov_b32 m0, s0
	s_nop 0
	global_load_lds_dwordx4 v[158:159], off
	s_waitcnt vmcnt(6)
	s_barrier
	s_setprio 1
	v_mfma_f32_16x16x32_bf16 v[54:57], v[220:223], v[174:177], v[54:57]
	v_mfma_f32_16x16x32_bf16 v[46:49], v[228:231], v[174:177], v[46:49]
	v_mfma_f32_16x16x32_bf16 v[38:41], v[220:223], v[182:185], v[38:41]
	v_mfma_f32_16x16x32_bf16 v[30:33], v[228:231], v[182:185], v[30:33]
	v_mfma_f32_16x16x32_bf16 v[22:25], v[220:223], v[204:207], v[22:25]
	v_mfma_f32_16x16x32_bf16 v[14:17], v[228:231], v[204:207], v[14:17]
	v_mfma_f32_16x16x32_bf16 v[6:9], v[220:223], v[212:215], v[6:9]
	v_mfma_f32_16x16x32_bf16 v[2:5], v[228:231], v[212:215], v[2:5]
	v_mfma_f32_16x16x32_bf16 v[54:57], v[224:227], v[178:181], v[54:57]
	v_mfma_f32_16x16x32_bf16 v[46:49], v[232:235], v[178:181], v[46:49]
	v_mfma_f32_16x16x32_bf16 v[38:41], v[224:227], v[186:189], v[38:41]
	v_mfma_f32_16x16x32_bf16 v[30:33], v[232:235], v[186:189], v[30:33]
	v_mfma_f32_16x16x32_bf16 v[22:25], v[224:227], v[208:211], v[22:25]
	v_mfma_f32_16x16x32_bf16 v[14:17], v[232:235], v[208:211], v[14:17]
	v_mfma_f32_16x16x32_bf16 v[6:9], v[224:227], v[216:219], v[6:9]
	v_mfma_f32_16x16x32_bf16 v[2:5], v[232:235], v[216:219], v[2:5]
	s_setprio 0
	v_lshl_add_u64 v[132:133], v[132:133], 0, s[52:53]
	s_addk_i32 s48, 0x80
	s_barrier
	s_cbranch_vccz .LBB0_1336
	s_ashr_i32 s27, s26, 31
	s_lshl_b64 s[0:1], s[26:27], 12
	s_add_u32 s0, s40, s0
	s_addc_u32 s1, s41, s1
	s_lshl_b32 s30, s19, 2
	s_add_u32 s26, s0, s30
	s_addc_u32 s27, s1, 0
	v_readlane_b32 s0, v248, 6
	s_add_u32 s19, s20, s0
	s_addc_u32 s96, s21, 0
	s_add_u32 s0, s19, s4
	v_mov_b32_e32 v0, v149
	s_addc_u32 s1, s96, s5
	s_add_u32 s0, s0, s30
	v_and_b32_e32 v130, 15, v0
	v_ashrrev_i32_e32 v131, 2, v0
	s_movk_i32 s30, 0xffc0
	v_lshlrev_b32_e32 v0, 1, v0
	s_addc_u32 s1, s1, 0
	v_and_or_b32 v136, v131, s30, v130
	v_and_b32_e32 v0, 0x1e0, v0
	s_cmp_eq_u64 s[42:43], 0
	v_ashrrev_i32_e32 v137, 31, v136
	v_lshl_add_u64 v[132:133], s[0:1], 0, v[0:1]
	s_mov_b64 s[0:1], 0x1f22000
	s_cselect_b32 s5, s27, s43
	s_cselect_b32 s4, s26, s42
	v_lshl_add_u64 v[130:131], v[132:133], 0, s[0:1]
	s_mov_b32 s0, 0x1f22000
	v_lshlrev_b64 v[134:135], 12, v[136:137]
	v_add_co_u32_e32 v132, vcc, s0, v132
	v_lshl_add_u64 v[152:153], s[4:5], 0, v[134:135]
	s_nop 0
	v_addc_co_u32_e32 v133, vcc, 0, v133, vcc
	v_lshl_add_u64 v[160:161], v[152:153], 0, v[0:1]
	v_mov_b32_e32 v188, v130
	v_mov_b32_e32 v189, v131
	v_mov_b32_e32 v136, v160
	v_mov_b32_e32 v137, v161
	v_lshl_add_u64 v[134:135], s[26:27], 0, v[134:135]
	v_lshl_add_u64 v[134:135], v[134:135], 0, v[0:1]
	s_nop 0
	global_load_dwordx4 v[152:155], v[188:189], off
	global_load_dwordx4 v[156:159], v[188:189], off offset:16
	global_load_dwordx4 v[160:163], v[188:189], off offset:512
	global_load_dwordx4 v[164:167], v[188:189], off offset:528
	v_mov_b32_e32 v144, v136
	v_mov_b32_e32 v145, v137
	global_load_dwordx4 v[168:171], v[144:145], off
	global_load_dwordx4 v[172:175], v[144:145], off offset:16
	global_load_dwordx4 v[176:179], v[144:145], off offset:512
	global_load_dwordx4 v[180:183], v[144:145], off offset:528
	v_add_co_u32_e32 v146, vcc, 0x10000, v136
	s_nop 1
	v_addc_co_u32_e32 v147, vcc, 0, v137, vcc
	global_load_dwordx4 v[184:187], v[146:147], off
	global_load_dwordx4 v[204:207], v[146:147], off offset:16
	global_load_dwordx4 v[208:211], v[146:147], off offset:512
	global_load_dwordx4 v[212:215], v[146:147], off offset:528
	v_add_co_u32_e32 v144, vcc, 0x20000, v136
	s_nop 1
	v_addc_co_u32_e32 v145, vcc, 0, v137, vcc
	global_load_dwordx4 v[216:219], v[144:145], off
	global_load_dwordx4 v[220:223], v[144:145], off offset:16
	global_load_dwordx4 v[224:227], v[144:145], off offset:512
	global_load_dwordx4 v[228:231], v[144:145], off offset:528
	v_add_co_u32_e32 v146, vcc, 0x30000, v136
	s_nop 1
	v_addc_co_u32_e32 v147, vcc, 0, v137, vcc
	global_load_dwordx4 v[232:235], v[146:147], off
	global_load_dwordx4 v[140:143], v[146:147], off offset:16
	s_waitcnt vmcnt(12)
; DI int otid() { int t = threadIdx.x; asm volatile("" : "+v"(t)); return t; }
; template <class F>
; DI void epi_foreach(acc_t& acc, F f) {
;   const int tid = otid(), wid = tid >> 6, lane = tid & 63, wr = wid >> 2, wc = wid & 3, fr = lane & 15, fq = lane >> 4;
; #pragma unroll
;   for (int ai = 0; ai < 2; ++ai)
; #pragma unroll
;     for (int m = 0; m < 4; ++m) {
; #pragma unroll
;       for (int bj = 0; bj < 2; ++bj) f(ai * 128 + wr * 64 + m * 16 + fr, bj * 128 + wc * 32 + 8 * fq, acc[ai][bj][m][0], acc[ai][bj][m][1]);
;       if (m == 3 && ai == 0) __builtin_amdgcn_sched_barrier(0);
;     }
; DI void residual_tile(acc_t& acc, float* X, const float* gate, const float* Xin = nullptr) {
;     ...
;   epi_foreach(acc, [&](int r, int c, f32x4& v0, f32x4& v1) {
;     const f32x4 g0 = *(const f32x4*)(gate + c), g1 = *(const f32x4*)(gate + c + 4);
;     f32x4 x0 = *(const f32x4*)(xs + (size_t)r * DM + c), x1 = *(const f32x4*)(xs + (size_t)r * DM + c + 4);
;     x0 = x0 + g0 * v0; x1 = x1 + g1 * v1;
;     *(f32x4*)(X + (size_t)r * DM + c) = x0; *(f32x4*)(X + (size_t)r * DM + c + 4) = x1;
;   });
	v_pk_fma_f32 v[126:127], v[126:127], v[152:153], v[168:169]
	v_pk_fma_f32 v[128:129], v[128:129], v[154:155], v[170:171]
	v_pk_fma_f32 v[122:123], v[122:123], v[156:157], v[172:173]
	v_pk_fma_f32 v[124:125], v[124:125], v[158:159], v[174:175]
	v_mov_b32_e32 v130, v134
	v_mov_b32_e32 v131, v135
	global_store_dwordx4 v[130:131], v[126:129], off
	global_store_dwordx4 v[130:131], v[122:125], off offset:16
	v_add_co_u32_e32 v146, vcc, 0x30000, v136
	s_nop 1
	v_addc_co_u32_e32 v147, vcc, 0, v137, vcc
	global_load_dwordx4 v[126:129], v[146:147], off offset:512
	global_load_dwordx4 v[122:125], v[146:147], off offset:528
	s_waitcnt vmcnt(12)
	v_pk_fma_f32 v[118:119], v[118:119], v[160:161], v[176:177]
	v_pk_fma_f32 v[120:121], v[120:121], v[162:163], v[178:179]
	v_pk_fma_f32 v[114:115], v[114:115], v[164:165], v[180:181]
	v_pk_fma_f32 v[116:117], v[116:117], v[166:167], v[182:183]
	global_store_dwordx4 v[130:131], v[118:121], off offset:512
	global_store_dwordx4 v[130:131], v[114:117], off offset:528
	v_add_co_u32_e32 v144, vcc, 0x80000, v136
	s_nop 1
	v_addc_co_u32_e32 v145, vcc, 0, v137, vcc
	global_load_dwordx4 v[118:121], v[144:145], off
	global_load_dwordx4 v[114:117], v[144:145], off offset:16
	s_waitcnt vmcnt(12)
	v_pk_fma_f32 v[110:111], v[110:111], v[152:153], v[184:185]
	v_pk_fma_f32 v[112:113], v[112:113], v[154:155], v[186:187]
	v_pk_fma_f32 v[106:107], v[106:107], v[156:157], v[204:205]
	v_pk_fma_f32 v[108:109], v[108:109], v[158:159], v[206:207]
	v_add_co_u32_e32 v132, vcc, 0x10000, v134
	s_nop 1
	v_addc_co_u32_e32 v133, vcc, 0, v135, vcc
	global_store_dwordx4 v[132:133], v[110:113], off
	global_store_dwordx4 v[132:133], v[106:109], off offset:16
	global_load_dwordx4 v[110:113], v[144:145], off offset:512
	global_load_dwordx4 v[106:109], v[144:145], off offset:528
	s_waitcnt vmcnt(12)
	v_pk_fma_f32 v[102:103], v[102:103], v[160:161], v[208:209]
	v_pk_fma_f32 v[104:105], v[104:105], v[162:163], v[210:211]
	v_pk_fma_f32 v[98:99], v[98:99], v[164:165], v[212:213]
	v_pk_fma_f32 v[100:101], v[100:101], v[166:167], v[214:215]
	global_store_dwordx4 v[132:133], v[102:105], off offset:512
	global_store_dwordx4 v[132:133], v[98:101], off offset:528
	v_add_co_u32_e32 v146, vcc, 0x90000, v136
	s_nop 1
	v_addc_co_u32_e32 v147, vcc, 0, v137, vcc
	global_load_dwordx4 v[102:105], v[146:147], off
	global_load_dwordx4 v[98:101], v[146:147], off offset:16
	s_waitcnt vmcnt(12)
	v_pk_fma_f32 v[94:95], v[94:95], v[152:153], v[216:217]
	v_pk_fma_f32 v[96:97], v[96:97], v[154:155], v[218:219]
	v_pk_fma_f32 v[90:91], v[90:91], v[156:157], v[220:221]
	v_pk_fma_f32 v[92:93], v[92:93], v[158:159], v[222:223]
	v_add_co_u32_e32 v130, vcc, 0x20000, v134
	s_nop 1
	v_addc_co_u32_e32 v131, vcc, 0, v135, vcc
	global_store_dwordx4 v[130:131], v[94:97], off
	global_store_dwordx4 v[130:131], v[90:93], off offset:16
	global_load_dwordx4 v[94:97], v[146:147], off offset:512
	global_load_dwordx4 v[90:93], v[146:147], off offset:528
	s_waitcnt vmcnt(12)
	v_pk_fma_f32 v[86:87], v[86:87], v[160:161], v[224:225]
	v_pk_fma_f32 v[88:89], v[88:89], v[162:163], v[226:227]
	v_pk_fma_f32 v[82:83], v[82:83], v[164:165], v[228:229]
	v_pk_fma_f32 v[84:85], v[84:85], v[166:167], v[230:231]
	global_store_dwordx4 v[130:131], v[86:89], off offset:512
	global_store_dwordx4 v[130:131], v[82:85], off offset:528
	v_add_co_u32_e32 v144, vcc, 0xa0000, v136
	s_nop 1
	v_addc_co_u32_e32 v145, vcc, 0, v137, vcc
	global_load_dwordx4 v[86:89], v[144:145], off
	global_load_dwordx4 v[82:85], v[144:145], off offset:16
	s_waitcnt vmcnt(12)
	v_pk_fma_f32 v[78:79], v[78:79], v[152:153], v[232:233]
	v_pk_fma_f32 v[80:81], v[80:81], v[154:155], v[234:235]
	v_pk_fma_f32 v[74:75], v[74:75], v[156:157], v[140:141]
	v_pk_fma_f32 v[76:77], v[76:77], v[158:159], v[142:143]
	v_add_co_u32_e32 v132, vcc, 0x30000, v134
	s_nop 1
	v_addc_co_u32_e32 v133, vcc, 0, v135, vcc
	global_store_dwordx4 v[132:133], v[78:81], off
	global_store_dwordx4 v[132:133], v[74:77], off offset:16
	global_load_dwordx4 v[78:81], v[144:145], off offset:512
	global_load_dwordx4 v[74:77], v[144:145], off offset:528
	s_waitcnt vmcnt(12)
; #define WAIT_V(n) asm volatile("s_waitcnt vmcnt(" #n ")" ::: "memory")
; #define BAR __builtin_amdgcn_s_barrier()
; template <int lda, int ldb, int K, class Gen, class Epi>
; DI void gemm_stream(Gen gen, Epi epi) {
;     ...
;   WAIT_V(0);
;   if (wr == 0) BAR;
;   BAR;
; DI void residual_tile(acc_t& acc, float* X, const float* gate, const float* Xin = nullptr) {
;     ...
;   epi_foreach(acc, [&](int r, int c, f32x4& v0, f32x4& v1) {
;     const f32x4 g0 = *(const f32x4*)(gate + c), g1 = *(const f32x4*)(gate + c + 4);
;     f32x4 x0 = *(const f32x4*)(xs + (size_t)r * DM + c), x1 = *(const f32x4*)(xs + (size_t)r * DM + c + 4);
;     x0 = x0 + g0 * v0; x1 = x1 + g1 * v1;
;     *(f32x4*)(X + (size_t)r * DM + c) = x0; *(f32x4*)(X + (size_t)r * DM + c + 4) = x1;
;   });
	v_pk_fma_f32 v[70:71], v[70:71], v[160:161], v[126:127]
	v_pk_fma_f32 v[72:73], v[72:73], v[162:163], v[128:129]
	v_pk_fma_f32 v[66:67], v[66:67], v[164:165], v[122:123]
	v_pk_fma_f32 v[68:69], v[68:69], v[166:167], v[124:125]
	global_store_dwordx4 v[132:133], v[70:73], off offset:512
	global_store_dwordx4 v[132:133], v[66:69], off offset:528
	v_add_co_u32_e32 v146, vcc, 0xb0000, v136
	s_nop 1
	v_addc_co_u32_e32 v147, vcc, 0, v137, vcc
	global_load_dwordx4 v[70:73], v[146:147], off
	global_load_dwordx4 v[66:69], v[146:147], off offset:16
	s_waitcnt vmcnt(12)
	v_pk_fma_f32 v[62:63], v[62:63], v[152:153], v[118:119]
	v_pk_fma_f32 v[64:65], v[64:65], v[154:155], v[120:121]
	v_pk_fma_f32 v[58:59], v[58:59], v[156:157], v[114:115]
	v_pk_fma_f32 v[60:61], v[60:61], v[158:159], v[116:117]
	v_add_co_u32_e32 v130, vcc, 0x80000, v134
	s_nop 1
	v_addc_co_u32_e32 v131, vcc, 0, v135, vcc
	global_store_dwordx4 v[130:131], v[62:65], off
	global_store_dwordx4 v[130:131], v[58:61], off offset:16
	global_load_dwordx4 v[62:65], v[146:147], off offset:512
	global_load_dwordx4 v[58:61], v[146:147], off offset:528
	s_waitcnt vmcnt(12)
	v_pk_fma_f32 v[54:55], v[54:55], v[160:161], v[110:111]
	v_pk_fma_f32 v[56:57], v[56:57], v[162:163], v[112:113]
	v_pk_fma_f32 v[46:47], v[46:47], v[164:165], v[106:107]
	v_pk_fma_f32 v[48:49], v[48:49], v[166:167], v[108:109]
	global_store_dwordx4 v[130:131], v[54:57], off offset:512
	global_store_dwordx4 v[130:131], v[46:49], off offset:528
	s_waitcnt vmcnt(10)
	v_pk_fma_f32 v[50:51], v[50:51], v[152:153], v[102:103]
	v_pk_fma_f32 v[52:53], v[52:53], v[154:155], v[104:105]
	v_pk_fma_f32 v[42:43], v[42:43], v[156:157], v[98:99]
	v_pk_fma_f32 v[44:45], v[44:45], v[158:159], v[100:101]
	v_add_co_u32_e32 v132, vcc, 0x90000, v134
	s_nop 1
	v_addc_co_u32_e32 v133, vcc, 0, v135, vcc
	global_store_dwordx4 v[132:133], v[50:53], off
	global_store_dwordx4 v[132:133], v[42:45], off offset:16
	s_waitcnt vmcnt(8)
	v_pk_fma_f32 v[38:39], v[38:39], v[160:161], v[94:95]
	v_pk_fma_f32 v[40:41], v[40:41], v[162:163], v[96:97]
	v_pk_fma_f32 v[30:31], v[30:31], v[164:165], v[90:91]
	v_pk_fma_f32 v[32:33], v[32:33], v[166:167], v[92:93]
	global_store_dwordx4 v[132:133], v[38:41], off offset:512
	global_store_dwordx4 v[132:133], v[30:33], off offset:528
	s_waitcnt vmcnt(6)
	v_pk_fma_f32 v[34:35], v[34:35], v[152:153], v[86:87]
	v_pk_fma_f32 v[36:37], v[36:37], v[154:155], v[88:89]
	v_pk_fma_f32 v[26:27], v[26:27], v[156:157], v[82:83]
	v_pk_fma_f32 v[28:29], v[28:29], v[158:159], v[84:85]
	v_add_co_u32_e32 v130, vcc, 0xa0000, v134
	s_nop 1
	v_addc_co_u32_e32 v131, vcc, 0, v135, vcc
	global_store_dwordx4 v[130:131], v[34:37], off
	global_store_dwordx4 v[130:131], v[26:29], off offset:16
	s_waitcnt vmcnt(4)
	v_pk_fma_f32 v[22:23], v[22:23], v[160:161], v[78:79]
	v_pk_fma_f32 v[24:25], v[24:25], v[162:163], v[80:81]
	v_pk_fma_f32 v[14:15], v[14:15], v[164:165], v[74:75]
	v_pk_fma_f32 v[16:17], v[16:17], v[166:167], v[76:77]
	global_store_dwordx4 v[130:131], v[22:25], off offset:512
	global_store_dwordx4 v[130:131], v[14:17], off offset:528
	s_waitcnt vmcnt(2)
	v_pk_fma_f32 v[18:19], v[18:19], v[152:153], v[70:71]
	v_pk_fma_f32 v[20:21], v[20:21], v[154:155], v[72:73]
	v_pk_fma_f32 v[10:11], v[10:11], v[156:157], v[66:67]
	v_pk_fma_f32 v[12:13], v[12:13], v[158:159], v[68:69]
	v_add_co_u32_e32 v132, vcc, 0xb0000, v134
	s_nop 1
	v_addc_co_u32_e32 v133, vcc, 0, v135, vcc
	global_store_dwordx4 v[132:133], v[18:21], off
	global_store_dwordx4 v[132:133], v[10:13], off offset:16
	s_waitcnt vmcnt(0)
	v_pk_fma_f32 v[6:7], v[6:7], v[160:161], v[62:63]
	v_pk_fma_f32 v[8:9], v[8:9], v[162:163], v[64:65]
	v_pk_fma_f32 v[2:3], v[2:3], v[164:165], v[58:59]
	v_pk_fma_f32 v[4:5], v[4:5], v[166:167], v[60:61]
	global_store_dwordx4 v[132:133], v[6:9], off offset:512
	global_store_dwordx4 v[132:133], v[2:5], off offset:528
	s_movk_i32 s0, 0x100
	v_cmp_gt_u32_e32 vcc, s0, v138
	s_waitcnt vmcnt(0)
	s_and_saveexec_b64 s[4:5], vcc
	s_cbranch_execz .LBB0_1339
	s_barrier

; #define STG_A(P, ptr) do { const bf16_t* _g = (ptr); \
;     __builtin_amdgcn_global_load_lds((const unsigned*)(_g + oa0), (__attribute__((address_space(3))) unsigned*)((P) + tb0), 16, 0, 0); \
;     __builtin_amdgcn_global_load_lds((const unsigned*)(_g + (size_t)64 * lda + oa0), (__attribute__((address_space(3))) unsigned*)((P) + tb1), 16, 0, 0); } while (0)
; #define STG_B(P, ptr) do { const bf16_t* _g = (ptr); \
;     __builtin_amdgcn_global_load_lds((const unsigned*)(_g + ob0), (__attribute__((address_space(3))) unsigned*)((P) + tb0), 16, 0, 0); \
;     __builtin_amdgcn_global_load_lds((const unsigned*)(_g + (size_t)64 * ldb + ob0), (__attribute__((address_space(3))) unsigned*)((P) + tb1), 16, 0, 0); } while (0)
; #define LDA(dst, b, h) _Pragma("unroll") for (int m = 0; m < 4; ++m) _Pragma("unroll") for (int k = 0; k < 2; ++k) \
;     dst[m][k] = *reinterpret_cast<const bf16x8*>(SA(b, h) + lds_byte(wr * 64 + m * 16 + fr, k * 32 + fq * 8))
; #define LDB(dst, b, h) _Pragma("unroll") for (int n = 0; n < 2; ++n) _Pragma("unroll") for (int k = 0; k < 2; ++k) \
;     dst[n][k] = *reinterpret_cast<const bf16x8*>(SB(b, h) + lds_byte(wc * 32 + n * 16 + fr, k * 32 + fq * 8))
; #define MMA(ai, bj, At_, Bt_) do { __builtin_amdgcn_s_setprio(1); \
;     _Pragma("unroll") for (int m = 0; m < 4; ++m) _Pragma("unroll") for (int n = 0; n < 2; ++n) _Pragma("unroll") for (int k = 0; k < 2; ++k) \
;       acc[ai][bj][m][n] = __builtin_amdgcn_mfma_f32_16x16x32_bf16(Bt_[n][k], At_[m][k], acc[ai][bj][m][n], 0, 0, 0); \
;     __builtin_amdgcn_s_setprio(0); } while (0)
; #define WAIT_L(n) asm volatile("s_waitcnt lgkmcnt(" #n ")" ::: "memory")
; template <int lda, int ldb, int K, class Gen, class Epi>
; DI void gemm_stream(Gen gen, Epi epi) {
;     ...
;     for (int t = 0; t < nt; t += 2) {
;       const bool wrap = (t + 2 >= nt);
;       const bf16_t* a1 = A + (t + 1) * 64;
;       const bf16_t* a2 = wrap ? An : A + (t + 2) * 64;
;       const bf16_t* b2 = wrap ? Bn : Bt + (t + 2) * 64;
;       LDB(B0, 0, 0); SCHED; LDA(At, 0, 0); STG_A(SA(1, 1), a1 + (size_t)128 * lda);
;       WAIT_L(8); BAR; WAIT_L(0); MMA(0, 0, At, B0); BAR; SCHED;
;       LDB(B1, 0, 1); STG_B(SB(0, 0), b2);
;       BAR; WAIT_L(0); MMA(0, 1, At, B1); BAR;
;       LDA(At, 0, 1); STG_A(SA(0, 0), a2);
;       BAR; WAIT_L(0); MMA(1, 0, At, B0); BAR; SCHED;
;       STG_B(SB(0, 1), b2 + (size_t)128 * ldb);
.LBB0_1412:
	s_add_i32 s4, s4, 2
	ds_read_b128 v[158:161], v147
	ds_read_b128 v[162:165], v147 offset:1024
	ds_read_b128 v[166:169], v147 offset:2048
	ds_read_b128 v[170:173], v147 offset:3072
	s_cmp_gt_u32 s4, 13
	s_cselect_b64 s[26:27], -1, 0
	s_and_b64 vcc, s[26:27], exec
	s_cselect_b32 s30, 0, s5
	s_lshl_b64 s[26:27], s[30:31], 1
	s_add_u32 s40, s42, s26
	s_addc_u32 s41, s43, s27
	v_add_u32_e32 v203, 0xc000, v135
	ds_read_b128 v[174:177], v150
	ds_read_b128 v[178:181], v150 offset:1024
	ds_read_b128 v[182:185], v152
	ds_read_b128 v[186:189], v152 offset:1024
	ds_read_b128 v[204:207], v153
	ds_read_b128 v[208:211], v153 offset:1024
	ds_read_b128 v[212:215], v154
	ds_read_b128 v[216:219], v154 offset:1024
	v_readfirstlane_b32 s18, v203
	v_add_u32_e32 v203, 0xe000, v135
	s_mov_b32 m0, s18
	v_readfirstlane_b32 s18, v203
	global_load_lds_dwordx4 v[132:133], off
	v_lshl_add_u64 v[220:221], v[132:133], 0, s[24:25]
	s_mov_b32 m0, s18
	s_nop 0
	global_load_lds_dwordx4 v[220:221], off
	s_waitcnt lgkmcnt(8)
	s_barrier
	s_waitcnt lgkmcnt(0)
	s_setprio 1
	s_waitcnt lgkmcnt(0)
	v_mfma_f32_16x16x32_bf16 v[126:129], v[158:161], v[174:177], v[126:129]
	v_mfma_f32_16x16x32_bf16 v[122:125], v[166:169], v[174:177], v[122:125]
	v_mfma_f32_16x16x32_bf16 v[110:113], v[158:161], v[182:185], v[110:113]
	v_mfma_f32_16x16x32_bf16 v[106:109], v[166:169], v[182:185], v[106:109]
	v_mfma_f32_16x16x32_bf16 v[94:97], v[158:161], v[204:207], v[94:97]
	v_mfma_f32_16x16x32_bf16 v[90:93], v[166:169], v[204:207], v[90:93]
	v_mfma_f32_16x16x32_bf16 v[78:81], v[158:161], v[212:215], v[78:81]
	v_mfma_f32_16x16x32_bf16 v[74:77], v[166:169], v[212:215], v[74:77]
	v_mfma_f32_16x16x32_bf16 v[126:129], v[162:165], v[178:181], v[126:129]
	v_mfma_f32_16x16x32_bf16 v[122:125], v[170:173], v[178:181], v[122:125]
	v_mfma_f32_16x16x32_bf16 v[110:113], v[162:165], v[186:189], v[110:113]
	v_mfma_f32_16x16x32_bf16 v[106:109], v[170:173], v[186:189], v[106:109]
	v_mfma_f32_16x16x32_bf16 v[94:97], v[162:165], v[208:211], v[94:97]
	v_mfma_f32_16x16x32_bf16 v[90:93], v[170:173], v[208:211], v[90:93]
	v_mfma_f32_16x16x32_bf16 v[78:81], v[162:165], v[216:219], v[78:81]
	v_mfma_f32_16x16x32_bf16 v[74:77], v[170:173], v[216:219], v[74:77]
	s_setprio 0
	s_barrier
	s_add_u32 s26, s0, s26
	s_addc_u32 s27, s1, s27
	v_readfirstlane_b32 s18, v134
	v_add_u32_e32 v203, 0x2000, v134
	v_lshl_add_u64 v[240:241], v[0:1], 1, s[26:27]
	s_mov_b32 m0, s18
	v_readfirstlane_b32 s18, v203
	ds_read_b128 v[220:223], v155
	ds_read_b128 v[224:227], v155 offset:1024
	ds_read_b128 v[228:231], v155 offset:2048
	ds_read_b128 v[232:235], v155 offset:3072
	global_load_lds_dwordx4 v[240:241], off
	v_lshl_add_u64 v[242:243], v[240:241], 0, s[24:25]
	s_mov_b32 m0, s18
	s_nop 0
	global_load_lds_dwordx4 v[242:243], off
	s_barrier
	s_waitcnt lgkmcnt(0)
	s_setprio 1
	s_waitcnt lgkmcnt(0)
	v_mfma_f32_16x16x32_bf16 v[118:121], v[220:223], v[174:177], v[118:121]
	v_mfma_f32_16x16x32_bf16 v[114:117], v[228:231], v[174:177], v[114:117]
	v_mfma_f32_16x16x32_bf16 v[102:105], v[220:223], v[182:185], v[102:105]
	v_mfma_f32_16x16x32_bf16 v[98:101], v[228:231], v[182:185], v[98:101]
	v_mfma_f32_16x16x32_bf16 v[86:89], v[220:223], v[204:207], v[86:89]
	v_mfma_f32_16x16x32_bf16 v[82:85], v[228:231], v[204:207], v[82:85]
	v_mfma_f32_16x16x32_bf16 v[70:73], v[220:223], v[212:215], v[70:73]
	v_mfma_f32_16x16x32_bf16 v[66:69], v[228:231], v[212:215], v[66:69]
	v_mfma_f32_16x16x32_bf16 v[118:121], v[224:227], v[178:181], v[118:121]
	v_mfma_f32_16x16x32_bf16 v[114:117], v[232:235], v[178:181], v[114:117]
	v_mfma_f32_16x16x32_bf16 v[102:105], v[224:227], v[186:189], v[102:105]
	v_mfma_f32_16x16x32_bf16 v[98:101], v[232:235], v[186:189], v[98:101]
	v_mfma_f32_16x16x32_bf16 v[86:89], v[224:227], v[208:211], v[86:89]
	v_mfma_f32_16x16x32_bf16 v[82:85], v[232:235], v[208:211], v[82:85]
	v_mfma_f32_16x16x32_bf16 v[70:73], v[224:227], v[216:219], v[70:73]
	v_mfma_f32_16x16x32_bf16 v[66:69], v[232:235], v[216:219], v[66:69]
	s_setprio 0
	v_readfirstlane_b32 s18, v135
	v_lshl_add_u64 v[242:243], v[130:131], 1, s[40:41]
	s_mov_b32 m0, s18
	v_readfirstlane_b32 s18, v136
	s_barrier
	ds_read_b128 v[174:177], v150 offset:16384
	ds_read_b128 v[178:181], v150 offset:17408
	ds_read_b128 v[182:185], v152 offset:16384
	ds_read_b128 v[186:189], v152 offset:17408
	ds_read_b128 v[204:207], v153 offset:16384
	ds_read_b128 v[208:211], v153 offset:17408
	ds_read_b128 v[212:215], v154 offset:16384
	ds_read_b128 v[216:219], v154 offset:17408
	global_load_lds_dwordx4 v[242:243], off
	v_lshl_add_u64 v[244:245], v[242:243], 0, s[24:25]
	s_mov_b32 m0, s18
	s_nop 0
	global_load_lds_dwordx4 v[244:245], off
	s_barrier
	s_waitcnt lgkmcnt(0)
	s_setprio 1
	s_waitcnt lgkmcnt(0)
	v_mfma_f32_16x16x32_bf16 v[62:65], v[158:161], v[174:177], v[62:65]
	v_mfma_f32_16x16x32_bf16 v[58:61], v[166:169], v[174:177], v[58:61]
	v_mfma_f32_16x16x32_bf16 v[50:53], v[158:161], v[182:185], v[50:53]
	v_mfma_f32_16x16x32_bf16 v[42:45], v[166:169], v[182:185], v[42:45]
	v_mfma_f32_16x16x32_bf16 v[34:37], v[158:161], v[204:207], v[34:37]
	v_mfma_f32_16x16x32_bf16 v[26:29], v[166:169], v[204:207], v[26:29]
	v_mfma_f32_16x16x32_bf16 v[18:21], v[158:161], v[212:215], v[18:21]
	v_mfma_f32_16x16x32_bf16 v[10:13], v[166:169], v[212:215], v[10:13]
	v_mfma_f32_16x16x32_bf16 v[62:65], v[162:165], v[178:181], v[62:65]
	v_mfma_f32_16x16x32_bf16 v[58:61], v[170:173], v[178:181], v[58:61]
	v_mfma_f32_16x16x32_bf16 v[50:53], v[162:165], v[186:189], v[50:53]
	v_mfma_f32_16x16x32_bf16 v[42:45], v[170:173], v[186:189], v[42:45]
	v_mfma_f32_16x16x32_bf16 v[34:37], v[162:165], v[208:211], v[34:37]
	v_mfma_f32_16x16x32_bf16 v[26:29], v[170:173], v[208:211], v[26:29]
	v_mfma_f32_16x16x32_bf16 v[18:21], v[162:165], v[216:219], v[18:21]
	v_mfma_f32_16x16x32_bf16 v[10:13], v[170:173], v[216:219], v[10:13]
	s_setprio 0
	s_barrier
; #define STG_A(P, ptr) do { const bf16_t* _g = (ptr); \
;     __builtin_amdgcn_global_load_lds((const unsigned*)(_g + oa0), (__attribute__((address_space(3))) unsigned*)((P) + tb0), 16, 0, 0); \
;     __builtin_amdgcn_global_load_lds((const unsigned*)(_g + (size_t)64 * lda + oa0), (__attribute__((address_space(3))) unsigned*)((P) + tb1), 16, 0, 0); } while (0)
; #define STG_B(P, ptr) do { const bf16_t* _g = (ptr); \
;     __builtin_amdgcn_global_load_lds((const unsigned*)(_g + ob0), (__attribute__((address_space(3))) unsigned*)((P) + tb0), 16, 0, 0); \
;     __builtin_amdgcn_global_load_lds((const unsigned*)(_g + (size_t)64 * ldb + ob0), (__attribute__((address_space(3))) unsigned*)((P) + tb1), 16, 0, 0); } while (0)
; #define LDA(dst, b, h) _Pragma("unroll") for (int m = 0; m < 4; ++m) _Pragma("unroll") for (int k = 0; k < 2; ++k) \
;     dst[m][k] = *reinterpret_cast<const bf16x8*>(SA(b, h) + lds_byte(wr * 64 + m * 16 + fr, k * 32 + fq * 8))
; #define LDB(dst, b, h) _Pragma("unroll") for (int n = 0; n < 2; ++n) _Pragma("unroll") for (int k = 0; k < 2; ++k) \
;     dst[n][k] = *reinterpret_cast<const bf16x8*>(SB(b, h) + lds_byte(wc * 32 + n * 16 + fr, k * 32 + fq * 8))
; #define MMA(ai, bj, At_, Bt_) do { __builtin_amdgcn_s_setprio(1); \
;     _Pragma("unroll") for (int m = 0; m < 4; ++m) _Pragma("unroll") for (int n = 0; n < 2; ++n) _Pragma("unroll") for (int k = 0; k < 2; ++k) \
;       acc[ai][bj][m][n] = __builtin_amdgcn_mfma_f32_16x16x32_bf16(Bt_[n][k], At_[m][k], acc[ai][bj][m][n], 0, 0, 0); \
;     __builtin_amdgcn_s_setprio(0); } while (0)
; #define WAIT_V(n) asm volatile("s_waitcnt vmcnt(" #n ")" ::: "memory")
; #define WAIT_L(n) asm volatile("s_waitcnt lgkmcnt(" #n ")" ::: "memory")
; #define BAR __builtin_amdgcn_s_barrier()
; #define SCHED __builtin_amdgcn_sched_barrier(0)
; template <int lda, int ldb, int K, class Gen, class Epi>
; DI void gemm_stream(Gen gen, Epi epi) {
;     ...
;       STG_B(SB(0, 1), b2 + (size_t)128 * ldb);
;       WAIT_V(6); BAR; MMA(1, 1, At, B1); BAR;
;       LDB(B0, 1, 0); SCHED; LDA(At, 1, 0); STG_A(SA(0, 1), a2 + (size_t)128 * lda);
;       WAIT_L(8); BAR; WAIT_L(0); MMA(0, 0, At, B0); BAR; SCHED;
;       LDB(B1, 1, 1); STG_B(SB(1, 0), b2 + 64);
;       BAR; WAIT_L(0); MMA(0, 1, At, B1); BAR;
;       LDA(At, 1, 1); STG_A(SA(1, 0), a2 + 64);
	v_readfirstlane_b32 s18, v137
	v_add_u32_e32 v160, 0x2000, v137
	v_lshl_add_u64 v[158:159], v[240:241], 0, s[38:39]
	s_mov_b32 m0, s18
	v_readfirstlane_b32 s18, v160
	global_load_lds_dwordx4 v[158:159], off
	v_lshl_add_u64 v[158:159], v[240:241], 0, s[12:13]
	s_mov_b32 m0, s18
	s_nop 0
	global_load_lds_dwordx4 v[158:159], off
	s_waitcnt vmcnt(6)
	s_barrier
	s_setprio 1
	v_mfma_f32_16x16x32_bf16 v[54:57], v[220:223], v[174:177], v[54:57]
	v_mfma_f32_16x16x32_bf16 v[46:49], v[228:231], v[174:177], v[46:49]
	v_mfma_f32_16x16x32_bf16 v[38:41], v[220:223], v[182:185], v[38:41]
	v_mfma_f32_16x16x32_bf16 v[30:33], v[228:231], v[182:185], v[30:33]
	v_mfma_f32_16x16x32_bf16 v[22:25], v[220:223], v[204:207], v[22:25]
	v_mfma_f32_16x16x32_bf16 v[14:17], v[228:231], v[204:207], v[14:17]
	v_mfma_f32_16x16x32_bf16 v[6:9], v[220:223], v[212:215], v[6:9]
	v_mfma_f32_16x16x32_bf16 v[2:5], v[228:231], v[212:215], v[2:5]
	v_mfma_f32_16x16x32_bf16 v[54:57], v[224:227], v[178:181], v[54:57]
	v_mfma_f32_16x16x32_bf16 v[46:49], v[232:235], v[178:181], v[46:49]
	v_mfma_f32_16x16x32_bf16 v[38:41], v[224:227], v[186:189], v[38:41]
	v_mfma_f32_16x16x32_bf16 v[30:33], v[232:235], v[186:189], v[30:33]
	v_mfma_f32_16x16x32_bf16 v[22:25], v[224:227], v[208:211], v[22:25]
	v_mfma_f32_16x16x32_bf16 v[14:17], v[232:235], v[208:211], v[14:17]
	v_mfma_f32_16x16x32_bf16 v[6:9], v[224:227], v[216:219], v[6:9]
	v_mfma_f32_16x16x32_bf16 v[2:5], v[232:235], v[216:219], v[2:5]
	s_setprio 0
	s_barrier
	ds_read_b128 v[158:161], v156
	ds_read_b128 v[162:165], v156 offset:1024
	ds_read_b128 v[166:169], v156 offset:2048
	ds_read_b128 v[170:173], v156 offset:3072
	v_readfirstlane_b32 s18, v139
	v_lshl_add_u64 v[220:221], v[242:243], 0, s[38:39]
	s_mov_b32 m0, s18
	v_readfirstlane_b32 s18, v140
	ds_read_b128 v[174:177], v150 offset:32768
	ds_read_b128 v[178:181], v150 offset:33792
	ds_read_b128 v[182:185], v152 offset:32768
	ds_read_b128 v[186:189], v152 offset:33792
	ds_read_b128 v[204:207], v153 offset:32768
	ds_read_b128 v[208:211], v153 offset:33792
	ds_read_b128 v[212:215], v154 offset:32768
	ds_read_b128 v[216:219], v154 offset:33792
	global_load_lds_dwordx4 v[220:221], off
	v_lshl_add_u64 v[220:221], v[242:243], 0, s[12:13]
	s_mov_b32 m0, s18
	s_nop 0
	global_load_lds_dwordx4 v[220:221], off
	s_waitcnt lgkmcnt(8)
	s_barrier
	s_waitcnt lgkmcnt(0)
	s_setprio 1
	s_waitcnt lgkmcnt(0)
	v_mfma_f32_16x16x32_bf16 v[126:129], v[158:161], v[174:177], v[126:129]
	v_mfma_f32_16x16x32_bf16 v[122:125], v[166:169], v[174:177], v[122:125]
	v_mfma_f32_16x16x32_bf16 v[110:113], v[158:161], v[182:185], v[110:113]
	v_mfma_f32_16x16x32_bf16 v[106:109], v[166:169], v[182:185], v[106:109]
	v_mfma_f32_16x16x32_bf16 v[94:97], v[158:161], v[204:207], v[94:97]
	v_mfma_f32_16x16x32_bf16 v[90:93], v[166:169], v[204:207], v[90:93]
	v_mfma_f32_16x16x32_bf16 v[78:81], v[158:161], v[212:215], v[78:81]
	v_mfma_f32_16x16x32_bf16 v[74:77], v[166:169], v[212:215], v[74:77]
	v_mfma_f32_16x16x32_bf16 v[126:129], v[162:165], v[178:181], v[126:129]
	v_mfma_f32_16x16x32_bf16 v[122:125], v[170:173], v[178:181], v[122:125]
	v_mfma_f32_16x16x32_bf16 v[110:113], v[162:165], v[186:189], v[110:113]
	v_mfma_f32_16x16x32_bf16 v[106:109], v[170:173], v[186:189], v[106:109]
	v_mfma_f32_16x16x32_bf16 v[94:97], v[162:165], v[208:211], v[94:97]
	v_mfma_f32_16x16x32_bf16 v[90:93], v[170:173], v[208:211], v[90:93]
	v_mfma_f32_16x16x32_bf16 v[78:81], v[162:165], v[216:219], v[78:81]
	v_mfma_f32_16x16x32_bf16 v[74:77], v[170:173], v[216:219], v[74:77]
	s_setprio 0
	s_barrier
	v_readfirstlane_b32 s18, v141
	v_lshl_add_u64 v[244:245], v[240:241], 0, s[34:35]
	s_mov_b32 m0, s18
	v_readfirstlane_b32 s18, v142
	ds_read_b128 v[220:223], v157
	ds_read_b128 v[224:227], v157 offset:1024
	ds_read_b128 v[228:231], v157 offset:2048
	ds_read_b128 v[232:235], v157 offset:3072
	global_load_lds_dwordx4 v[244:245], off
	v_lshl_add_u64 v[244:245], v[240:241], 0, s[10:11]
	s_mov_b32 m0, s18
	s_nop 0
	global_load_lds_dwordx4 v[244:245], off
	s_barrier
	s_waitcnt lgkmcnt(0)
	s_setprio 1
	s_waitcnt lgkmcnt(0)
	v_mfma_f32_16x16x32_bf16 v[118:121], v[220:223], v[174:177], v[118:121]
	v_mfma_f32_16x16x32_bf16 v[114:117], v[228:231], v[174:177], v[114:117]
	v_mfma_f32_16x16x32_bf16 v[102:105], v[220:223], v[182:185], v[102:105]
	v_mfma_f32_16x16x32_bf16 v[98:101], v[228:231], v[182:185], v[98:101]
	v_mfma_f32_16x16x32_bf16 v[86:89], v[220:223], v[204:207], v[86:89]
	v_mfma_f32_16x16x32_bf16 v[82:85], v[228:231], v[204:207], v[82:85]
	v_mfma_f32_16x16x32_bf16 v[70:73], v[220:223], v[212:215], v[70:73]
	v_mfma_f32_16x16x32_bf16 v[66:69], v[228:231], v[212:215], v[66:69]
	v_mfma_f32_16x16x32_bf16 v[118:121], v[224:227], v[178:181], v[118:121]
	v_mfma_f32_16x16x32_bf16 v[114:117], v[232:235], v[178:181], v[114:117]
	v_mfma_f32_16x16x32_bf16 v[102:105], v[224:227], v[186:189], v[102:105]
	v_mfma_f32_16x16x32_bf16 v[98:101], v[232:235], v[186:189], v[98:101]
	v_mfma_f32_16x16x32_bf16 v[86:89], v[224:227], v[208:211], v[86:89]
	v_mfma_f32_16x16x32_bf16 v[82:85], v[232:235], v[208:211], v[82:85]
	v_mfma_f32_16x16x32_bf16 v[70:73], v[224:227], v[216:219], v[70:73]
	v_mfma_f32_16x16x32_bf16 v[66:69], v[232:235], v[216:219], v[66:69]
	s_setprio 0
	v_readfirstlane_b32 s18, v143
	v_lshl_add_u64 v[244:245], v[242:243], 0, s[34:35]
	s_mov_b32 m0, s18
	v_readfirstlane_b32 s18, v144
	s_barrier
	ds_read_b128 v[174:177], v150 offset:49152
	ds_read_b128 v[178:181], v150 offset:50176
	ds_read_b128 v[182:185], v152 offset:49152
	ds_read_b128 v[186:189], v152 offset:50176
	ds_read_b128 v[204:207], v153 offset:49152
	ds_read_b128 v[208:211], v153 offset:50176
	ds_read_b128 v[212:215], v154 offset:49152
	ds_read_b128 v[216:219], v154 offset:50176
	global_load_lds_dwordx4 v[244:245], off
	v_lshl_add_u64 v[242:243], v[242:243], 0, s[10:11]
	s_mov_b32 m0, s18
	s_nop 0
	global_load_lds_dwordx4 v[242:243], off
	s_barrier
; #define STG_A(P, ptr) do { const bf16_t* _g = (ptr); \
;     __builtin_amdgcn_global_load_lds((const unsigned*)(_g + oa0), (__attribute__((address_space(3))) unsigned*)((P) + tb0), 16, 0, 0); \
;     __builtin_amdgcn_global_load_lds((const unsigned*)(_g + (size_t)64 * lda + oa0), (__attribute__((address_space(3))) unsigned*)((P) + tb1), 16, 0, 0); } while (0)
; #define STG_B(P, ptr) do { const bf16_t* _g = (ptr); \
;     __builtin_amdgcn_global_load_lds((const unsigned*)(_g + ob0), (__attribute__((address_space(3))) unsigned*)((P) + tb0), 16, 0, 0); \
;     __builtin_amdgcn_global_load_lds((const unsigned*)(_g + (size_t)64 * ldb + ob0), (__attribute__((address_space(3))) unsigned*)((P) + tb1), 16, 0, 0); } while (0)
; #define LDA(dst, b, h) _Pragma("unroll") for (int m = 0; m < 4; ++m) _Pragma("unroll") for (int k = 0; k < 2; ++k) \
;     dst[m][k] = *reinterpret_cast<const bf16x8*>(SA(b, h) + lds_byte(wr * 64 + m * 16 + fr, k * 32 + fq * 8))
; #define MMA(ai, bj, At_, Bt_) do { __builtin_amdgcn_s_setprio(1); \
;     _Pragma("unroll") for (int m = 0; m < 4; ++m) _Pragma("unroll") for (int n = 0; n < 2; ++n) _Pragma("unroll") for (int k = 0; k < 2; ++k) \
;       acc[ai][bj][m][n] = __builtin_amdgcn_mfma_f32_16x16x32_bf16(Bt_[n][k], At_[m][k], acc[ai][bj][m][n], 0, 0, 0); \
;     __builtin_amdgcn_s_setprio(0); } while (0)
; #define WAIT_V(n) asm volatile("s_waitcnt vmcnt(" #n ")" ::: "memory")
; #define WAIT_L(n) asm volatile("s_waitcnt lgkmcnt(" #n ")" ::: "memory")
; #define BAR __builtin_amdgcn_s_barrier()
; template <int lda, int ldb, int K, class Gen, class Epi>
; DI void gemm_stream(Gen gen, Epi epi) {
;     ...
;       LDA(At, 1, 1); STG_A(SA(1, 0), a2 + 64);
;       BAR; WAIT_L(0); MMA(1, 0, At, B0); BAR; SCHED;
;       STG_B(SB(1, 1), b2 + (size_t)128 * ldb + 64);
;       WAIT_V(6); BAR; MMA(1, 1, At, B1); BAR;
; DI void residual_tile(acc_t& acc, float* X, const float* gate, const float* Xin = nullptr) {
;   const float* xs = Xin ? Xin : X;
;   epi_foreach(acc, [&](int r, int c, f32x4& v0, f32x4& v1) {
;     const f32x4 g0 = *(const f32x4*)(gate + c), g1 = *(const f32x4*)(gate + c + 4);
;     f32x4 x0 = *(const f32x4*)(xs + (size_t)r * DM + c), x1 = *(const f32x4*)(xs + (size_t)r * DM + c + 4);
;     x0 = x0 + g0 * v0; x1 = x1 + g1 * v1;
;     *(f32x4*)(X + (size_t)r * DM + c) = x0; *(f32x4*)(X + (size_t)r * DM + c + 4) = x1;
	s_waitcnt lgkmcnt(0)
	s_setprio 1
	s_waitcnt lgkmcnt(0)
	v_mfma_f32_16x16x32_bf16 v[62:65], v[158:161], v[174:177], v[62:65]
	v_mfma_f32_16x16x32_bf16 v[58:61], v[166:169], v[174:177], v[58:61]
	v_mfma_f32_16x16x32_bf16 v[50:53], v[158:161], v[182:185], v[50:53]
	v_mfma_f32_16x16x32_bf16 v[42:45], v[166:169], v[182:185], v[42:45]
	v_mfma_f32_16x16x32_bf16 v[34:37], v[158:161], v[204:207], v[34:37]
	v_mfma_f32_16x16x32_bf16 v[26:29], v[166:169], v[204:207], v[26:29]
	v_mfma_f32_16x16x32_bf16 v[18:21], v[158:161], v[212:215], v[18:21]
	v_mfma_f32_16x16x32_bf16 v[10:13], v[166:169], v[212:215], v[10:13]
	v_mfma_f32_16x16x32_bf16 v[62:65], v[162:165], v[178:181], v[62:65]
	v_mfma_f32_16x16x32_bf16 v[58:61], v[170:173], v[178:181], v[58:61]
	v_mfma_f32_16x16x32_bf16 v[50:53], v[162:165], v[186:189], v[50:53]
	v_mfma_f32_16x16x32_bf16 v[42:45], v[170:173], v[186:189], v[42:45]
	v_mfma_f32_16x16x32_bf16 v[34:37], v[162:165], v[208:211], v[34:37]
	v_mfma_f32_16x16x32_bf16 v[26:29], v[170:173], v[208:211], v[26:29]
	v_mfma_f32_16x16x32_bf16 v[18:21], v[162:165], v[216:219], v[18:21]
	v_mfma_f32_16x16x32_bf16 v[10:13], v[170:173], v[216:219], v[10:13]
	s_setprio 0
	s_barrier
	v_readfirstlane_b32 s18, v145
	v_lshl_add_u64 v[158:159], v[240:241], 0, s[36:37]
	s_mov_b32 m0, s18
	v_readfirstlane_b32 s18, v146
	global_load_lds_dwordx4 v[158:159], off
	v_lshl_add_u64 v[158:159], v[240:241], 0, s[8:9]
	s_mov_b32 m0, s18
	s_nop 0
	global_load_lds_dwordx4 v[158:159], off
	s_waitcnt vmcnt(6)
	s_barrier
	s_setprio 1
	v_mfma_f32_16x16x32_bf16 v[54:57], v[220:223], v[174:177], v[54:57]
	v_mfma_f32_16x16x32_bf16 v[46:49], v[228:231], v[174:177], v[46:49]
	v_mfma_f32_16x16x32_bf16 v[38:41], v[220:223], v[182:185], v[38:41]
	v_mfma_f32_16x16x32_bf16 v[30:33], v[228:231], v[182:185], v[30:33]
	v_mfma_f32_16x16x32_bf16 v[22:25], v[220:223], v[204:207], v[22:25]
	v_mfma_f32_16x16x32_bf16 v[14:17], v[228:231], v[204:207], v[14:17]
	v_mfma_f32_16x16x32_bf16 v[6:9], v[220:223], v[212:215], v[6:9]
	v_mfma_f32_16x16x32_bf16 v[2:5], v[228:231], v[212:215], v[2:5]
	v_mfma_f32_16x16x32_bf16 v[54:57], v[224:227], v[178:181], v[54:57]
	v_mfma_f32_16x16x32_bf16 v[46:49], v[232:235], v[178:181], v[46:49]
	v_mfma_f32_16x16x32_bf16 v[38:41], v[224:227], v[186:189], v[38:41]
	v_mfma_f32_16x16x32_bf16 v[30:33], v[232:235], v[186:189], v[30:33]
	v_mfma_f32_16x16x32_bf16 v[22:25], v[224:227], v[208:211], v[22:25]
	v_mfma_f32_16x16x32_bf16 v[14:17], v[232:235], v[208:211], v[14:17]
	v_mfma_f32_16x16x32_bf16 v[6:9], v[224:227], v[216:219], v[6:9]
	v_mfma_f32_16x16x32_bf16 v[2:5], v[232:235], v[216:219], v[2:5]
	s_setprio 0
	v_lshl_add_u64 v[132:133], v[132:133], 0, s[44:45]
	s_addk_i32 s5, 0x80
	s_barrier
	s_cbranch_vccz .LBB0_1412
	v_readlane_b32 s0, v253, 38
	s_add_u32 s0, s19, s0
	v_readlane_b32 s1, v253, 37
	v_readlane_b32 s4, v251, 54
	s_addc_u32 s1, s96, s1
	s_lshl_b32 s4, s4, 2
	s_add_u32 s4, s0, s4
	s_addc_u32 s5, s1, 0
	v_readlane_b32 s0, v248, 2
	v_readlane_b32 s1, v248, 3
	s_and_b64 s[0:1], s[0:1], exec
	v_mov_b32_e32 v0, v149
	v_readlane_b32 s0, v253, 45
	s_cselect_b32 s1, s0, 0
	v_readlane_b32 s0, v253, 44
	v_and_b32_e32 v130, 15, v0
	v_ashrrev_i32_e32 v131, 2, v0
	s_movk_i32 s26, 0xffc0
	v_lshlrev_b32_e32 v0, 1, v0
	s_cselect_b32 s0, s0, 0
	v_readlane_b32 s18, v253, 39
	v_and_or_b32 v136, v131, s26, v130
	v_and_b32_e32 v0, 0x1e0, v0
	s_cmp_eq_u64 s[0:1], 0
	v_readlane_b32 s19, v253, 40
	v_ashrrev_i32_e32 v137, 31, v136
	v_lshl_add_u64 v[132:133], s[4:5], 0, v[0:1]
	s_mov_b64 s[4:5], 0x1f22000
	s_cselect_b32 s1, s19, s1
	s_cselect_b32 s0, s18, s0
	v_lshl_add_u64 v[130:131], v[132:133], 0, s[4:5]
	s_mov_b32 s4, 0x1f22000
	v_lshlrev_b64 v[134:135], 12, v[136:137]
	v_add_co_u32_e32 v132, vcc, s4, v132
	v_lshl_add_u64 v[152:153], s[0:1], 0, v[134:135]
	s_nop 0
	v_addc_co_u32_e32 v133, vcc, 0, v133, vcc
	v_lshl_add_u64 v[160:161], v[152:153], 0, v[0:1]
	v_mov_b32_e32 v188, v130
	v_mov_b32_e32 v189, v131
	v_mov_b32_e32 v136, v160
	v_mov_b32_e32 v137, v161
	v_lshl_add_u64 v[134:135], s[18:19], 0, v[134:135]
	v_lshl_add_u64 v[134:135], v[134:135], 0, v[0:1]
	s_nop 0
	global_load_dwordx4 v[152:155], v[188:189], off
	global_load_dwordx4 v[156:159], v[188:189], off offset:16
	global_load_dwordx4 v[160:163], v[188:189], off offset:512
	global_load_dwordx4 v[164:167], v[188:189], off offset:528
	v_mov_b32_e32 v144, v136
	v_mov_b32_e32 v145, v137
	global_load_dwordx4 v[168:171], v[144:145], off
	global_load_dwordx4 v[172:175], v[144:145], off offset:16
	global_load_dwordx4 v[176:179], v[144:145], off offset:512
	global_load_dwordx4 v[180:183], v[144:145], off offset:528
	v_add_co_u32_e32 v146, vcc, 0x10000, v136
	s_nop 1
	v_addc_co_u32_e32 v147, vcc, 0, v137, vcc
	global_load_dwordx4 v[184:187], v[146:147], off
	global_load_dwordx4 v[204:207], v[146:147], off offset:16
	global_load_dwordx4 v[208:211], v[146:147], off offset:512
	global_load_dwordx4 v[212:215], v[146:147], off offset:528
	v_add_co_u32_e32 v144, vcc, 0x20000, v136
	s_nop 1
	v_addc_co_u32_e32 v145, vcc, 0, v137, vcc
	global_load_dwordx4 v[216:219], v[144:145], off
	global_load_dwordx4 v[220:223], v[144:145], off offset:16
	global_load_dwordx4 v[224:227], v[144:145], off offset:512
	global_load_dwordx4 v[228:231], v[144:145], off offset:528
	v_add_co_u32_e32 v146, vcc, 0x30000, v136
	s_nop 1
	v_addc_co_u32_e32 v147, vcc, 0, v137, vcc
	global_load_dwordx4 v[232:235], v[146:147], off
	global_load_dwordx4 v[140:143], v[146:147], off offset:16
	s_waitcnt vmcnt(12)
; DI int otid() { int t = threadIdx.x; asm volatile("" : "+v"(t)); return t; }
; template <class F>
; DI void epi_foreach(acc_t& acc, F f) {
;   const int tid = otid(), wid = tid >> 6, lane = tid & 63, wr = wid >> 2, wc = wid & 3, fr = lane & 15, fq = lane >> 4;
; #pragma unroll
;   for (int ai = 0; ai < 2; ++ai)
; #pragma unroll
;     for (int m = 0; m < 4; ++m) {
; #pragma unroll
;       for (int bj = 0; bj < 2; ++bj) f(ai * 128 + wr * 64 + m * 16 + fr, bj * 128 + wc * 32 + 8 * fq, acc[ai][bj][m][0], acc[ai][bj][m][1]);
;       if (m == 3 && ai == 0) __builtin_amdgcn_sched_barrier(0);
;     }
; DI void residual_tile(acc_t& acc, float* X, const float* gate, const float* Xin = nullptr) {
;     ...
;   epi_foreach(acc, [&](int r, int c, f32x4& v0, f32x4& v1) {
;     const f32x4 g0 = *(const f32x4*)(gate + c), g1 = *(const f32x4*)(gate + c + 4);
;     f32x4 x0 = *(const f32x4*)(xs + (size_t)r * DM + c), x1 = *(const f32x4*)(xs + (size_t)r * DM + c + 4);
;     x0 = x0 + g0 * v0; x1 = x1 + g1 * v1;
;     *(f32x4*)(X + (size_t)r * DM + c) = x0; *(f32x4*)(X + (size_t)r * DM + c + 4) = x1;
;   });
	v_pk_fma_f32 v[126:127], v[126:127], v[152:153], v[168:169]
	v_pk_fma_f32 v[128:129], v[128:129], v[154:155], v[170:171]
	v_pk_fma_f32 v[122:123], v[122:123], v[156:157], v[172:173]
	v_pk_fma_f32 v[124:125], v[124:125], v[158:159], v[174:175]
	v_mov_b32_e32 v130, v134
	v_mov_b32_e32 v131, v135
	global_store_dwordx4 v[130:131], v[126:129], off
	global_store_dwordx4 v[130:131], v[122:125], off offset:16
	v_add_co_u32_e32 v146, vcc, 0x30000, v136
	s_nop 1
	v_addc_co_u32_e32 v147, vcc, 0, v137, vcc
	global_load_dwordx4 v[126:129], v[146:147], off offset:512
	global_load_dwordx4 v[122:125], v[146:147], off offset:528
	s_waitcnt vmcnt(12)
	v_pk_fma_f32 v[118:119], v[118:119], v[160:161], v[176:177]
	v_pk_fma_f32 v[120:121], v[120:121], v[162:163], v[178:179]
	v_pk_fma_f32 v[114:115], v[114:115], v[164:165], v[180:181]
	v_pk_fma_f32 v[116:117], v[116:117], v[166:167], v[182:183]
	global_store_dwordx4 v[130:131], v[118:121], off offset:512
	global_store_dwordx4 v[130:131], v[114:117], off offset:528
	v_add_co_u32_e32 v144, vcc, 0x80000, v136
	s_nop 1
	v_addc_co_u32_e32 v145, vcc, 0, v137, vcc
	global_load_dwordx4 v[118:121], v[144:145], off
	global_load_dwordx4 v[114:117], v[144:145], off offset:16
	s_waitcnt vmcnt(12)
	v_pk_fma_f32 v[110:111], v[110:111], v[152:153], v[184:185]
	v_pk_fma_f32 v[112:113], v[112:113], v[154:155], v[186:187]
	v_pk_fma_f32 v[106:107], v[106:107], v[156:157], v[204:205]
	v_pk_fma_f32 v[108:109], v[108:109], v[158:159], v[206:207]
	v_add_co_u32_e32 v132, vcc, 0x10000, v134
	s_nop 1
	v_addc_co_u32_e32 v133, vcc, 0, v135, vcc
	global_store_dwordx4 v[132:133], v[110:113], off
	global_store_dwordx4 v[132:133], v[106:109], off offset:16
	global_load_dwordx4 v[110:113], v[144:145], off offset:512
	global_load_dwordx4 v[106:109], v[144:145], off offset:528
	s_waitcnt vmcnt(12)
	v_pk_fma_f32 v[102:103], v[102:103], v[160:161], v[208:209]
	v_pk_fma_f32 v[104:105], v[104:105], v[162:163], v[210:211]
	v_pk_fma_f32 v[98:99], v[98:99], v[164:165], v[212:213]
	v_pk_fma_f32 v[100:101], v[100:101], v[166:167], v[214:215]
	global_store_dwordx4 v[132:133], v[102:105], off offset:512
	global_store_dwordx4 v[132:133], v[98:101], off offset:528
	v_add_co_u32_e32 v146, vcc, 0x90000, v136
	s_nop 1
	v_addc_co_u32_e32 v147, vcc, 0, v137, vcc
	global_load_dwordx4 v[102:105], v[146:147], off
	global_load_dwordx4 v[98:101], v[146:147], off offset:16
	s_waitcnt vmcnt(12)
	v_pk_fma_f32 v[94:95], v[94:95], v[152:153], v[216:217]
	v_pk_fma_f32 v[96:97], v[96:97], v[154:155], v[218:219]
	v_pk_fma_f32 v[90:91], v[90:91], v[156:157], v[220:221]
	v_pk_fma_f32 v[92:93], v[92:93], v[158:159], v[222:223]
	v_add_co_u32_e32 v130, vcc, 0x20000, v134
	s_nop 1
	v_addc_co_u32_e32 v131, vcc, 0, v135, vcc
	global_store_dwordx4 v[130:131], v[94:97], off
	global_store_dwordx4 v[130:131], v[90:93], off offset:16
	global_load_dwordx4 v[94:97], v[146:147], off offset:512
	global_load_dwordx4 v[90:93], v[146:147], off offset:528
	s_waitcnt vmcnt(12)
	v_pk_fma_f32 v[86:87], v[86:87], v[160:161], v[224:225]
	v_pk_fma_f32 v[88:89], v[88:89], v[162:163], v[226:227]
	v_pk_fma_f32 v[82:83], v[82:83], v[164:165], v[228:229]
	v_pk_fma_f32 v[84:85], v[84:85], v[166:167], v[230:231]
	global_store_dwordx4 v[130:131], v[86:89], off offset:512
	global_store_dwordx4 v[130:131], v[82:85], off offset:528
	v_add_co_u32_e32 v144, vcc, 0xa0000, v136
	s_nop 1
	v_addc_co_u32_e32 v145, vcc, 0, v137, vcc
	global_load_dwordx4 v[86:89], v[144:145], off
	global_load_dwordx4 v[82:85], v[144:145], off offset:16
	s_waitcnt vmcnt(12)
	v_pk_fma_f32 v[78:79], v[78:79], v[152:153], v[232:233]
	v_pk_fma_f32 v[80:81], v[80:81], v[154:155], v[234:235]
	v_pk_fma_f32 v[74:75], v[74:75], v[156:157], v[140:141]
	v_pk_fma_f32 v[76:77], v[76:77], v[158:159], v[142:143]
	v_add_co_u32_e32 v132, vcc, 0x30000, v134
	s_nop 1
	v_addc_co_u32_e32 v133, vcc, 0, v135, vcc
	global_store_dwordx4 v[132:133], v[78:81], off
	global_store_dwordx4 v[132:133], v[74:77], off offset:16
	global_load_dwordx4 v[78:81], v[144:145], off offset:512
	global_load_dwordx4 v[74:77], v[144:145], off offset:528
	s_waitcnt vmcnt(12)
; #define WAIT_V(n) asm volatile("s_waitcnt vmcnt(" #n ")" ::: "memory")
; #define BAR __builtin_amdgcn_s_barrier()
; template <int lda, int ldb, int K, class Gen, class Epi>
; DI void gemm_stream(Gen gen, Epi epi) {
;     ...
;   WAIT_V(0);
;   if (wr == 0) BAR;
;   BAR;
; DI void residual_tile(acc_t& acc, float* X, const float* gate, const float* Xin = nullptr) {
;     ...
;   epi_foreach(acc, [&](int r, int c, f32x4& v0, f32x4& v1) {
;     const f32x4 g0 = *(const f32x4*)(gate + c), g1 = *(const f32x4*)(gate + c + 4);
;     f32x4 x0 = *(const f32x4*)(xs + (size_t)r * DM + c), x1 = *(const f32x4*)(xs + (size_t)r * DM + c + 4);
;     x0 = x0 + g0 * v0; x1 = x1 + g1 * v1;
;     *(f32x4*)(X + (size_t)r * DM + c) = x0; *(f32x4*)(X + (size_t)r * DM + c + 4) = x1;
;   });
	v_pk_fma_f32 v[70:71], v[70:71], v[160:161], v[126:127]
	v_pk_fma_f32 v[72:73], v[72:73], v[162:163], v[128:129]
	v_pk_fma_f32 v[66:67], v[66:67], v[164:165], v[122:123]
	v_pk_fma_f32 v[68:69], v[68:69], v[166:167], v[124:125]
	global_store_dwordx4 v[132:133], v[70:73], off offset:512
	global_store_dwordx4 v[132:133], v[66:69], off offset:528
	v_add_co_u32_e32 v146, vcc, 0xb0000, v136
	s_nop 1
	v_addc_co_u32_e32 v147, vcc, 0, v137, vcc
	global_load_dwordx4 v[70:73], v[146:147], off
	global_load_dwordx4 v[66:69], v[146:147], off offset:16
	s_waitcnt vmcnt(12)
	v_pk_fma_f32 v[62:63], v[62:63], v[152:153], v[118:119]
	v_pk_fma_f32 v[64:65], v[64:65], v[154:155], v[120:121]
	v_pk_fma_f32 v[58:59], v[58:59], v[156:157], v[114:115]
	v_pk_fma_f32 v[60:61], v[60:61], v[158:159], v[116:117]
	v_add_co_u32_e32 v130, vcc, 0x80000, v134
	s_nop 1
	v_addc_co_u32_e32 v131, vcc, 0, v135, vcc
	global_store_dwordx4 v[130:131], v[62:65], off
	global_store_dwordx4 v[130:131], v[58:61], off offset:16
	global_load_dwordx4 v[62:65], v[146:147], off offset:512
	global_load_dwordx4 v[58:61], v[146:147], off offset:528
	s_waitcnt vmcnt(12)
	v_pk_fma_f32 v[54:55], v[54:55], v[160:161], v[110:111]
	v_pk_fma_f32 v[56:57], v[56:57], v[162:163], v[112:113]
	v_pk_fma_f32 v[46:47], v[46:47], v[164:165], v[106:107]
	v_pk_fma_f32 v[48:49], v[48:49], v[166:167], v[108:109]
	global_store_dwordx4 v[130:131], v[54:57], off offset:512
	global_store_dwordx4 v[130:131], v[46:49], off offset:528
	s_waitcnt vmcnt(10)
	v_pk_fma_f32 v[50:51], v[50:51], v[152:153], v[102:103]
	v_pk_fma_f32 v[52:53], v[52:53], v[154:155], v[104:105]
	v_pk_fma_f32 v[42:43], v[42:43], v[156:157], v[98:99]
	v_pk_fma_f32 v[44:45], v[44:45], v[158:159], v[100:101]
	v_add_co_u32_e32 v132, vcc, 0x90000, v134
	s_nop 1
	v_addc_co_u32_e32 v133, vcc, 0, v135, vcc
	global_store_dwordx4 v[132:133], v[50:53], off
	global_store_dwordx4 v[132:133], v[42:45], off offset:16
	s_waitcnt vmcnt(8)
	v_pk_fma_f32 v[38:39], v[38:39], v[160:161], v[94:95]
	v_pk_fma_f32 v[40:41], v[40:41], v[162:163], v[96:97]
	v_pk_fma_f32 v[30:31], v[30:31], v[164:165], v[90:91]
	v_pk_fma_f32 v[32:33], v[32:33], v[166:167], v[92:93]
	global_store_dwordx4 v[132:133], v[38:41], off offset:512
	global_store_dwordx4 v[132:133], v[30:33], off offset:528
	s_waitcnt vmcnt(6)
	v_pk_fma_f32 v[34:35], v[34:35], v[152:153], v[86:87]
	v_pk_fma_f32 v[36:37], v[36:37], v[154:155], v[88:89]
	v_pk_fma_f32 v[26:27], v[26:27], v[156:157], v[82:83]
	v_pk_fma_f32 v[28:29], v[28:29], v[158:159], v[84:85]
	v_add_co_u32_e32 v130, vcc, 0xa0000, v134
	s_nop 1
	v_addc_co_u32_e32 v131, vcc, 0, v135, vcc
	global_store_dwordx4 v[130:131], v[34:37], off
	global_store_dwordx4 v[130:131], v[26:29], off offset:16
	s_waitcnt vmcnt(4)
	v_pk_fma_f32 v[22:23], v[22:23], v[160:161], v[78:79]
	v_pk_fma_f32 v[24:25], v[24:25], v[162:163], v[80:81]
	v_pk_fma_f32 v[14:15], v[14:15], v[164:165], v[74:75]
	v_pk_fma_f32 v[16:17], v[16:17], v[166:167], v[76:77]
	global_store_dwordx4 v[130:131], v[22:25], off offset:512
	global_store_dwordx4 v[130:131], v[14:17], off offset:528
	s_waitcnt vmcnt(2)
	v_pk_fma_f32 v[18:19], v[18:19], v[152:153], v[70:71]
	v_pk_fma_f32 v[20:21], v[20:21], v[154:155], v[72:73]
	v_pk_fma_f32 v[10:11], v[10:11], v[156:157], v[66:67]
	v_pk_fma_f32 v[12:13], v[12:13], v[158:159], v[68:69]
	v_add_co_u32_e32 v132, vcc, 0xb0000, v134
	s_nop 1
	v_addc_co_u32_e32 v133, vcc, 0, v135, vcc
	global_store_dwordx4 v[132:133], v[18:21], off
	global_store_dwordx4 v[132:133], v[10:13], off offset:16
	s_waitcnt vmcnt(0)
	v_pk_fma_f32 v[6:7], v[6:7], v[160:161], v[62:63]
	v_pk_fma_f32 v[8:9], v[8:9], v[162:163], v[64:65]
	v_pk_fma_f32 v[2:3], v[2:3], v[164:165], v[58:59]
	v_pk_fma_f32 v[4:5], v[4:5], v[166:167], v[60:61]
	global_store_dwordx4 v[132:133], v[6:9], off offset:512
	global_store_dwordx4 v[132:133], v[2:5], off offset:528
	s_mov_b64 s[4:5], 0x80000
	s_mov_b64 s[4:5], 0x90000
	s_mov_b64 s[4:5], 0xa0000
	s_mov_b64 s[4:5], 0xb0000
	s_movk_i32 s0, 0x100
	v_cmp_gt_u32_e32 vcc, s0, v138
	s_waitcnt vmcnt(0)
	s_and_saveexec_b64 s[0:1], vcc
	s_cbranch_execz .LBB0_1415
	s_barrier

; #define STG_A(P, ptr) do { const bf16_t* _g = (ptr); \
;     __builtin_amdgcn_global_load_lds((const unsigned*)(_g + oa0), (__attribute__((address_space(3))) unsigned*)((P) + tb0), 16, 0, 0); \
;     __builtin_amdgcn_global_load_lds((const unsigned*)(_g + (size_t)64 * lda + oa0), (__attribute__((address_space(3))) unsigned*)((P) + tb1), 16, 0, 0); } while (0)
; #define STG_B(P, ptr) do { const bf16_t* _g = (ptr); \
;     __builtin_amdgcn_global_load_lds((const unsigned*)(_g + ob0), (__attribute__((address_space(3))) unsigned*)((P) + tb0), 16, 0, 0); \
;     __builtin_amdgcn_global_load_lds((const unsigned*)(_g + (size_t)64 * ldb + ob0), (__attribute__((address_space(3))) unsigned*)((P) + tb1), 16, 0, 0); } while (0)
; #define LDA(dst, b, h) _Pragma("unroll") for (int m = 0; m < 4; ++m) _Pragma("unroll") for (int k = 0; k < 2; ++k) \
;     dst[m][k] = *reinterpret_cast<const bf16x8*>(SA(b, h) + lds_byte(wr * 64 + m * 16 + fr, k * 32 + fq * 8))
; #define LDB(dst, b, h) _Pragma("unroll") for (int n = 0; n < 2; ++n) _Pragma("unroll") for (int k = 0; k < 2; ++k) \
;     dst[n][k] = *reinterpret_cast<const bf16x8*>(SB(b, h) + lds_byte(wc * 32 + n * 16 + fr, k * 32 + fq * 8))
; #define MMA(ai, bj, At_, Bt_) do { __builtin_amdgcn_s_setprio(1); \
;     _Pragma("unroll") for (int m = 0; m < 4; ++m) _Pragma("unroll") for (int n = 0; n < 2; ++n) _Pragma("unroll") for (int k = 0; k < 2; ++k) \
;       acc[ai][bj][m][n] = __builtin_amdgcn_mfma_f32_16x16x32_bf16(Bt_[n][k], At_[m][k], acc[ai][bj][m][n], 0, 0, 0); \
;     __builtin_amdgcn_s_setprio(0); } while (0)
; #define WAIT_L(n) asm volatile("s_waitcnt lgkmcnt(" #n ")" ::: "memory")
; #define BAR __builtin_amdgcn_s_barrier()
; #define SCHED __builtin_amdgcn_sched_barrier(0)
; template <int lda, int ldb, int K, class Gen, class Epi>
; DI void gemm_stream(Gen gen, Epi epi) {
;     ...
;       LDB(B0, 0, 0); SCHED; LDA(At, 0, 0); STG_A(SA(1, 1), a1 + (size_t)128 * lda);
;       WAIT_L(8); BAR; WAIT_L(0); MMA(0, 0, At, B0); BAR; SCHED;
;       LDB(B1, 0, 1); STG_B(SB(0, 0), b2);
;       BAR; WAIT_L(0); MMA(0, 1, At, B1); BAR;
;       LDA(At, 0, 1); STG_A(SA(0, 0), a2);
;       BAR; WAIT_L(0); MMA(1, 0, At, B0); BAR; SCHED;
;       STG_B(SB(0, 1), b2 + (size_t)128 * ldb);
.LBB0_1605:
	s_add_i32 s4, s4, 2
	ds_read_b128 v[158:161], v147
	ds_read_b128 v[162:165], v147 offset:1024
	ds_read_b128 v[166:169], v147 offset:2048
	ds_read_b128 v[170:173], v147 offset:3072
	s_cmp_gt_u32 s4, 61
	s_cselect_b64 s[18:19], -1, 0
	s_and_b64 vcc, s[18:19], exec
	s_cselect_b32 s30, 0, s5
	s_lshl_b64 s[18:19], s[30:31], 1
	s_add_u32 s26, s40, s18
	s_addc_u32 s27, s41, s19
	v_add_u32_e32 v197, 0xc000, v135
	ds_read_b128 v[174:177], v150
	ds_read_b128 v[178:181], v150 offset:1024
	ds_read_b128 v[182:185], v152
	ds_read_b128 v[186:189], v152 offset:1024
	ds_read_b128 v[198:201], v153
	ds_read_b128 v[202:205], v153 offset:1024
	ds_read_b128 v[206:209], v154
	ds_read_b128 v[210:213], v154 offset:1024
	v_readfirstlane_b32 s30, v197
	v_add_u32_e32 v197, 0xe000, v135
	s_mov_b32 m0, s30
	v_readfirstlane_b32 s30, v197
	global_load_lds_dwordx4 v[132:133], off
	v_lshl_add_u64 v[214:215], v[132:133], 0, s[42:43]
	s_mov_b32 m0, s30
	s_nop 0
	global_load_lds_dwordx4 v[214:215], off
	s_waitcnt lgkmcnt(8)
	s_barrier
	s_waitcnt lgkmcnt(0)
	s_setprio 1
	s_waitcnt lgkmcnt(0)
	v_mfma_f32_16x16x32_bf16 v[126:129], v[158:161], v[174:177], v[126:129]
	v_mfma_f32_16x16x32_bf16 v[122:125], v[166:169], v[174:177], v[122:125]
	v_mfma_f32_16x16x32_bf16 v[110:113], v[158:161], v[182:185], v[110:113]
	v_mfma_f32_16x16x32_bf16 v[106:109], v[166:169], v[182:185], v[106:109]
	v_mfma_f32_16x16x32_bf16 v[94:97], v[158:161], v[198:201], v[94:97]
	v_mfma_f32_16x16x32_bf16 v[90:93], v[166:169], v[198:201], v[90:93]
	v_mfma_f32_16x16x32_bf16 v[78:81], v[158:161], v[206:209], v[78:81]
	v_mfma_f32_16x16x32_bf16 v[74:77], v[166:169], v[206:209], v[74:77]
	v_mfma_f32_16x16x32_bf16 v[126:129], v[162:165], v[178:181], v[126:129]
	v_mfma_f32_16x16x32_bf16 v[122:125], v[170:173], v[178:181], v[122:125]
	v_mfma_f32_16x16x32_bf16 v[110:113], v[162:165], v[186:189], v[110:113]
	v_mfma_f32_16x16x32_bf16 v[106:109], v[170:173], v[186:189], v[106:109]
	v_mfma_f32_16x16x32_bf16 v[94:97], v[162:165], v[202:205], v[94:97]
	v_mfma_f32_16x16x32_bf16 v[90:93], v[170:173], v[202:205], v[90:93]
	v_mfma_f32_16x16x32_bf16 v[78:81], v[162:165], v[210:213], v[78:81]
	v_mfma_f32_16x16x32_bf16 v[74:77], v[170:173], v[210:213], v[74:77]
	s_setprio 0
	s_barrier
	s_add_u32 s18, s0, s18
	s_addc_u32 s19, s1, s19
	v_lshl_add_u64 v[230:231], v[0:1], 1, s[18:19]
	v_readfirstlane_b32 s18, v134
	v_add_u32_e32 v197, 0x2000, v134
	s_mov_b32 m0, s18
	v_readfirstlane_b32 s18, v197
	ds_read_b128 v[214:217], v155
	ds_read_b128 v[218:221], v155 offset:1024
	ds_read_b128 v[222:225], v155 offset:2048
	ds_read_b128 v[226:229], v155 offset:3072
	global_load_lds_dwordx4 v[230:231], off
	v_lshl_add_u64 v[232:233], v[230:231], 0, s[52:53]
	s_mov_b32 m0, s18
	s_nop 0
	global_load_lds_dwordx4 v[232:233], off
	s_barrier
	s_waitcnt lgkmcnt(0)
	s_setprio 1
	s_waitcnt lgkmcnt(0)
	v_mfma_f32_16x16x32_bf16 v[118:121], v[214:217], v[174:177], v[118:121]
	v_mfma_f32_16x16x32_bf16 v[114:117], v[222:225], v[174:177], v[114:117]
	v_mfma_f32_16x16x32_bf16 v[102:105], v[214:217], v[182:185], v[102:105]
	v_mfma_f32_16x16x32_bf16 v[98:101], v[222:225], v[182:185], v[98:101]
	v_mfma_f32_16x16x32_bf16 v[86:89], v[214:217], v[198:201], v[86:89]
	v_mfma_f32_16x16x32_bf16 v[82:85], v[222:225], v[198:201], v[82:85]
	v_mfma_f32_16x16x32_bf16 v[70:73], v[214:217], v[206:209], v[70:73]
	v_mfma_f32_16x16x32_bf16 v[66:69], v[222:225], v[206:209], v[66:69]
	v_mfma_f32_16x16x32_bf16 v[118:121], v[218:221], v[178:181], v[118:121]
	v_mfma_f32_16x16x32_bf16 v[114:117], v[226:229], v[178:181], v[114:117]
	v_mfma_f32_16x16x32_bf16 v[102:105], v[218:221], v[186:189], v[102:105]
	v_mfma_f32_16x16x32_bf16 v[98:101], v[226:229], v[186:189], v[98:101]
	v_mfma_f32_16x16x32_bf16 v[86:89], v[218:221], v[202:205], v[86:89]
	v_mfma_f32_16x16x32_bf16 v[82:85], v[226:229], v[202:205], v[82:85]
	v_mfma_f32_16x16x32_bf16 v[70:73], v[218:221], v[210:213], v[70:73]
	v_mfma_f32_16x16x32_bf16 v[66:69], v[226:229], v[210:213], v[66:69]
	s_setprio 0
	v_readfirstlane_b32 s18, v135
	v_lshl_add_u64 v[232:233], v[130:131], 1, s[26:27]
	s_mov_b32 m0, s18
	v_readfirstlane_b32 s18, v136
	s_barrier
	ds_read_b128 v[174:177], v150 offset:16384
	ds_read_b128 v[178:181], v150 offset:17408
	ds_read_b128 v[182:185], v152 offset:16384
	ds_read_b128 v[186:189], v152 offset:17408
	ds_read_b128 v[198:201], v153 offset:16384
	ds_read_b128 v[202:205], v153 offset:17408
	ds_read_b128 v[206:209], v154 offset:16384
	ds_read_b128 v[210:213], v154 offset:17408
	global_load_lds_dwordx4 v[232:233], off
	v_lshl_add_u64 v[234:235], v[232:233], 0, s[42:43]
	s_mov_b32 m0, s18
	s_nop 0
	global_load_lds_dwordx4 v[234:235], off
	s_barrier
	s_waitcnt lgkmcnt(0)
	s_setprio 1
	s_waitcnt lgkmcnt(0)
	v_mfma_f32_16x16x32_bf16 v[62:65], v[158:161], v[174:177], v[62:65]
	v_mfma_f32_16x16x32_bf16 v[58:61], v[166:169], v[174:177], v[58:61]
	v_mfma_f32_16x16x32_bf16 v[46:49], v[158:161], v[182:185], v[46:49]
	v_mfma_f32_16x16x32_bf16 v[42:45], v[166:169], v[182:185], v[42:45]
	v_mfma_f32_16x16x32_bf16 v[30:33], v[158:161], v[198:201], v[30:33]
	v_mfma_f32_16x16x32_bf16 v[26:29], v[166:169], v[198:201], v[26:29]
	v_mfma_f32_16x16x32_bf16 v[14:17], v[158:161], v[206:209], v[14:17]
	v_mfma_f32_16x16x32_bf16 v[10:13], v[166:169], v[206:209], v[10:13]
	v_mfma_f32_16x16x32_bf16 v[62:65], v[162:165], v[178:181], v[62:65]
	v_mfma_f32_16x16x32_bf16 v[58:61], v[170:173], v[178:181], v[58:61]
	v_mfma_f32_16x16x32_bf16 v[46:49], v[162:165], v[186:189], v[46:49]
	v_mfma_f32_16x16x32_bf16 v[42:45], v[170:173], v[186:189], v[42:45]
	v_mfma_f32_16x16x32_bf16 v[30:33], v[162:165], v[202:205], v[30:33]
	v_mfma_f32_16x16x32_bf16 v[26:29], v[170:173], v[202:205], v[26:29]
	v_mfma_f32_16x16x32_bf16 v[14:17], v[162:165], v[210:213], v[14:17]
	v_mfma_f32_16x16x32_bf16 v[10:13], v[170:173], v[210:213], v[10:13]
	s_setprio 0
	s_barrier
; #define STG_A(P, ptr) do { const bf16_t* _g = (ptr); \
;     __builtin_amdgcn_global_load_lds((const unsigned*)(_g + oa0), (__attribute__((address_space(3))) unsigned*)((P) + tb0), 16, 0, 0); \
;     __builtin_amdgcn_global_load_lds((const unsigned*)(_g + (size_t)64 * lda + oa0), (__attribute__((address_space(3))) unsigned*)((P) + tb1), 16, 0, 0); } while (0)
; #define STG_B(P, ptr) do { const bf16_t* _g = (ptr); \
;     __builtin_amdgcn_global_load_lds((const unsigned*)(_g + ob0), (__attribute__((address_space(3))) unsigned*)((P) + tb0), 16, 0, 0); \
;     __builtin_amdgcn_global_load_lds((const unsigned*)(_g + (size_t)64 * ldb + ob0), (__attribute__((address_space(3))) unsigned*)((P) + tb1), 16, 0, 0); } while (0)
; #define LDA(dst, b, h) _Pragma("unroll") for (int m = 0; m < 4; ++m) _Pragma("unroll") for (int k = 0; k < 2; ++k) \
;     dst[m][k] = *reinterpret_cast<const bf16x8*>(SA(b, h) + lds_byte(wr * 64 + m * 16 + fr, k * 32 + fq * 8))
; #define LDB(dst, b, h) _Pragma("unroll") for (int n = 0; n < 2; ++n) _Pragma("unroll") for (int k = 0; k < 2; ++k) \
;     dst[n][k] = *reinterpret_cast<const bf16x8*>(SB(b, h) + lds_byte(wc * 32 + n * 16 + fr, k * 32 + fq * 8))
; #define MMA(ai, bj, At_, Bt_) do { __builtin_amdgcn_s_setprio(1); \
;     _Pragma("unroll") for (int m = 0; m < 4; ++m) _Pragma("unroll") for (int n = 0; n < 2; ++n) _Pragma("unroll") for (int k = 0; k < 2; ++k) \
;       acc[ai][bj][m][n] = __builtin_amdgcn_mfma_f32_16x16x32_bf16(Bt_[n][k], At_[m][k], acc[ai][bj][m][n], 0, 0, 0); \
;     __builtin_amdgcn_s_setprio(0); } while (0)
; #define WAIT_V(n) asm volatile("s_waitcnt vmcnt(" #n ")" ::: "memory")
; #define WAIT_L(n) asm volatile("s_waitcnt lgkmcnt(" #n ")" ::: "memory")
; #define BAR __builtin_amdgcn_s_barrier()
; #define SCHED __builtin_amdgcn_sched_barrier(0)
; template <int lda, int ldb, int K, class Gen, class Epi>
; DI void gemm_stream(Gen gen, Epi epi) {
;     ...
;       STG_B(SB(0, 1), b2 + (size_t)128 * ldb);
;       WAIT_V(6); BAR; MMA(1, 1, At, B1); BAR;
;       LDB(B0, 1, 0); SCHED; LDA(At, 1, 0); STG_A(SA(0, 1), a2 + (size_t)128 * lda);
;       WAIT_L(8); BAR; WAIT_L(0); MMA(0, 0, At, B0); BAR; SCHED;
;       LDB(B1, 1, 1); STG_B(SB(1, 0), b2 + 64);
;       BAR; WAIT_L(0); MMA(0, 1, At, B1); BAR;
;       LDA(At, 1, 1); STG_A(SA(1, 0), a2 + 64);
	v_readfirstlane_b32 s18, v137
	v_add_u32_e32 v160, 0x2000, v137
	v_lshl_add_u64 v[158:159], v[230:231], 0, s[54:55]
	s_mov_b32 m0, s18
	v_readfirstlane_b32 s18, v160
	global_load_lds_dwordx4 v[158:159], off
	v_lshl_add_u64 v[158:159], v[230:231], 0, s[56:57]
	s_mov_b32 m0, s18
	s_nop 0
	global_load_lds_dwordx4 v[158:159], off
	s_waitcnt vmcnt(6)
	s_barrier
	s_setprio 1
	v_mfma_f32_16x16x32_bf16 v[54:57], v[214:217], v[174:177], v[54:57]
	v_mfma_f32_16x16x32_bf16 v[50:53], v[222:225], v[174:177], v[50:53]
	v_mfma_f32_16x16x32_bf16 v[38:41], v[214:217], v[182:185], v[38:41]
	v_mfma_f32_16x16x32_bf16 v[34:37], v[222:225], v[182:185], v[34:37]
	v_mfma_f32_16x16x32_bf16 v[22:25], v[214:217], v[198:201], v[22:25]
	v_mfma_f32_16x16x32_bf16 v[18:21], v[222:225], v[198:201], v[18:21]
	v_mfma_f32_16x16x32_bf16 v[6:9], v[214:217], v[206:209], v[6:9]
	v_mfma_f32_16x16x32_bf16 v[2:5], v[222:225], v[206:209], v[2:5]
	v_mfma_f32_16x16x32_bf16 v[54:57], v[218:221], v[178:181], v[54:57]
	v_mfma_f32_16x16x32_bf16 v[50:53], v[226:229], v[178:181], v[50:53]
	v_mfma_f32_16x16x32_bf16 v[38:41], v[218:221], v[186:189], v[38:41]
	v_mfma_f32_16x16x32_bf16 v[34:37], v[226:229], v[186:189], v[34:37]
	v_mfma_f32_16x16x32_bf16 v[22:25], v[218:221], v[202:205], v[22:25]
	v_mfma_f32_16x16x32_bf16 v[18:21], v[226:229], v[202:205], v[18:21]
	v_mfma_f32_16x16x32_bf16 v[6:9], v[218:221], v[210:213], v[6:9]
	v_mfma_f32_16x16x32_bf16 v[2:5], v[226:229], v[210:213], v[2:5]
	s_setprio 0
	s_barrier
	ds_read_b128 v[158:161], v156
	ds_read_b128 v[162:165], v156 offset:1024
	ds_read_b128 v[166:169], v156 offset:2048
	ds_read_b128 v[170:173], v156 offset:3072
	v_readfirstlane_b32 s18, v139
	v_lshl_add_u64 v[214:215], v[232:233], 0, s[44:45]
	s_mov_b32 m0, s18
	v_readfirstlane_b32 s18, v140
	ds_read_b128 v[174:177], v150 offset:32768
	ds_read_b128 v[178:181], v150 offset:33792
	ds_read_b128 v[182:185], v152 offset:32768
	ds_read_b128 v[186:189], v152 offset:33792
	ds_read_b128 v[198:201], v153 offset:32768
	ds_read_b128 v[202:205], v153 offset:33792
	ds_read_b128 v[206:209], v154 offset:32768
	ds_read_b128 v[210:213], v154 offset:33792
	global_load_lds_dwordx4 v[214:215], off
	v_lshl_add_u64 v[214:215], v[232:233], 0, s[46:47]
	s_mov_b32 m0, s18
	s_nop 0
	global_load_lds_dwordx4 v[214:215], off
	s_waitcnt lgkmcnt(8)
	s_barrier
	s_waitcnt lgkmcnt(0)
	s_setprio 1
	s_waitcnt lgkmcnt(0)
	v_mfma_f32_16x16x32_bf16 v[126:129], v[158:161], v[174:177], v[126:129]
	v_mfma_f32_16x16x32_bf16 v[122:125], v[166:169], v[174:177], v[122:125]
	v_mfma_f32_16x16x32_bf16 v[110:113], v[158:161], v[182:185], v[110:113]
	v_mfma_f32_16x16x32_bf16 v[106:109], v[166:169], v[182:185], v[106:109]
	v_mfma_f32_16x16x32_bf16 v[94:97], v[158:161], v[198:201], v[94:97]
	v_mfma_f32_16x16x32_bf16 v[90:93], v[166:169], v[198:201], v[90:93]
	v_mfma_f32_16x16x32_bf16 v[78:81], v[158:161], v[206:209], v[78:81]
	v_mfma_f32_16x16x32_bf16 v[74:77], v[166:169], v[206:209], v[74:77]
	v_mfma_f32_16x16x32_bf16 v[126:129], v[162:165], v[178:181], v[126:129]
	v_mfma_f32_16x16x32_bf16 v[122:125], v[170:173], v[178:181], v[122:125]
	v_mfma_f32_16x16x32_bf16 v[110:113], v[162:165], v[186:189], v[110:113]
	v_mfma_f32_16x16x32_bf16 v[106:109], v[170:173], v[186:189], v[106:109]
	v_mfma_f32_16x16x32_bf16 v[94:97], v[162:165], v[202:205], v[94:97]
	v_mfma_f32_16x16x32_bf16 v[90:93], v[170:173], v[202:205], v[90:93]
	v_mfma_f32_16x16x32_bf16 v[78:81], v[162:165], v[210:213], v[78:81]
	v_mfma_f32_16x16x32_bf16 v[74:77], v[170:173], v[210:213], v[74:77]
	s_setprio 0
	s_barrier
	v_readfirstlane_b32 s18, v141
	v_lshl_add_u64 v[234:235], v[230:231], 0, s[34:35]
	s_mov_b32 m0, s18
	v_readfirstlane_b32 s18, v142
	ds_read_b128 v[214:217], v157
	ds_read_b128 v[218:221], v157 offset:1024
	ds_read_b128 v[222:225], v157 offset:2048
	ds_read_b128 v[226:229], v157 offset:3072
	global_load_lds_dwordx4 v[234:235], off
	v_lshl_add_u64 v[234:235], v[230:231], 0, s[58:59]
	s_mov_b32 m0, s18
	s_nop 0
	global_load_lds_dwordx4 v[234:235], off
	s_barrier
	s_waitcnt lgkmcnt(0)
	s_setprio 1
	s_waitcnt lgkmcnt(0)
	v_mfma_f32_16x16x32_bf16 v[118:121], v[214:217], v[174:177], v[118:121]
	v_mfma_f32_16x16x32_bf16 v[114:117], v[222:225], v[174:177], v[114:117]
	v_mfma_f32_16x16x32_bf16 v[102:105], v[214:217], v[182:185], v[102:105]
	v_mfma_f32_16x16x32_bf16 v[98:101], v[222:225], v[182:185], v[98:101]
	v_mfma_f32_16x16x32_bf16 v[86:89], v[214:217], v[198:201], v[86:89]
	v_mfma_f32_16x16x32_bf16 v[82:85], v[222:225], v[198:201], v[82:85]
	v_mfma_f32_16x16x32_bf16 v[70:73], v[214:217], v[206:209], v[70:73]
	v_mfma_f32_16x16x32_bf16 v[66:69], v[222:225], v[206:209], v[66:69]
	v_mfma_f32_16x16x32_bf16 v[118:121], v[218:221], v[178:181], v[118:121]
	v_mfma_f32_16x16x32_bf16 v[114:117], v[226:229], v[178:181], v[114:117]
	v_mfma_f32_16x16x32_bf16 v[102:105], v[218:221], v[186:189], v[102:105]
	v_mfma_f32_16x16x32_bf16 v[98:101], v[226:229], v[186:189], v[98:101]
	v_mfma_f32_16x16x32_bf16 v[86:89], v[218:221], v[202:205], v[86:89]
	v_mfma_f32_16x16x32_bf16 v[82:85], v[226:229], v[202:205], v[82:85]
	v_mfma_f32_16x16x32_bf16 v[70:73], v[218:221], v[210:213], v[70:73]
	v_mfma_f32_16x16x32_bf16 v[66:69], v[226:229], v[210:213], v[66:69]
	s_setprio 0
	v_readfirstlane_b32 s18, v143
	v_lshl_add_u64 v[234:235], v[232:233], 0, s[34:35]
	s_mov_b32 m0, s18
	v_readfirstlane_b32 s18, v144
	s_barrier
	ds_read_b128 v[174:177], v150 offset:49152
	ds_read_b128 v[178:181], v150 offset:50176
	ds_read_b128 v[182:185], v152 offset:49152
	ds_read_b128 v[186:189], v152 offset:50176
	ds_read_b128 v[198:201], v153 offset:49152
	ds_read_b128 v[202:205], v153 offset:50176
	ds_read_b128 v[206:209], v154 offset:49152
	ds_read_b128 v[210:213], v154 offset:50176
	global_load_lds_dwordx4 v[234:235], off
	v_lshl_add_u64 v[232:233], v[232:233], 0, s[48:49]
	s_mov_b32 m0, s18
	s_nop 0
	global_load_lds_dwordx4 v[232:233], off
	s_barrier
; #define STG_A(P, ptr) do { const bf16_t* _g = (ptr); \
;     __builtin_amdgcn_global_load_lds((const unsigned*)(_g + oa0), (__attribute__((address_space(3))) unsigned*)((P) + tb0), 16, 0, 0); \
;     __builtin_amdgcn_global_load_lds((const unsigned*)(_g + (size_t)64 * lda + oa0), (__attribute__((address_space(3))) unsigned*)((P) + tb1), 16, 0, 0); } while (0)
; #define STG_B(P, ptr) do { const bf16_t* _g = (ptr); \
;     __builtin_amdgcn_global_load_lds((const unsigned*)(_g + ob0), (__attribute__((address_space(3))) unsigned*)((P) + tb0), 16, 0, 0); \
;     __builtin_amdgcn_global_load_lds((const unsigned*)(_g + (size_t)64 * ldb + ob0), (__attribute__((address_space(3))) unsigned*)((P) + tb1), 16, 0, 0); } while (0)
; #define LDA(dst, b, h) _Pragma("unroll") for (int m = 0; m < 4; ++m) _Pragma("unroll") for (int k = 0; k < 2; ++k) \
;     dst[m][k] = *reinterpret_cast<const bf16x8*>(SA(b, h) + lds_byte(wr * 64 + m * 16 + fr, k * 32 + fq * 8))
; #define MMA(ai, bj, At_, Bt_) do { __builtin_amdgcn_s_setprio(1); \
;     _Pragma("unroll") for (int m = 0; m < 4; ++m) _Pragma("unroll") for (int n = 0; n < 2; ++n) _Pragma("unroll") for (int k = 0; k < 2; ++k) \
;       acc[ai][bj][m][n] = __builtin_amdgcn_mfma_f32_16x16x32_bf16(Bt_[n][k], At_[m][k], acc[ai][bj][m][n], 0, 0, 0); \
;     __builtin_amdgcn_s_setprio(0); } while (0)
; #define WAIT_V(n) asm volatile("s_waitcnt vmcnt(" #n ")" ::: "memory")
; #define WAIT_L(n) asm volatile("s_waitcnt lgkmcnt(" #n ")" ::: "memory")
; #define BAR __builtin_amdgcn_s_barrier()
; template <int lda, int ldb, int K, class Gen, class Epi>
; DI void gemm_stream(Gen gen, Epi epi) {
;     ...
;       LDA(At, 1, 1); STG_A(SA(1, 0), a2 + 64);
;       BAR; WAIT_L(0); MMA(1, 0, At, B0); BAR; SCHED;
;       STG_B(SB(1, 1), b2 + (size_t)128 * ldb + 64);
;       WAIT_V(6); BAR; MMA(1, 1, At, B1); BAR;
; DI void residual_tile(acc_t& acc, float* X, const float* gate, const float* Xin = nullptr) {
;   const float* xs = Xin ? Xin : X;
;   epi_foreach(acc, [&](int r, int c, f32x4& v0, f32x4& v1) {
;     const f32x4 g0 = *(const f32x4*)(gate + c), g1 = *(const f32x4*)(gate + c + 4);
;     f32x4 x0 = *(const f32x4*)(xs + (size_t)r * DM + c), x1 = *(const f32x4*)(xs + (size_t)r * DM + c + 4);
;     x0 = x0 + g0 * v0; x1 = x1 + g1 * v1;
;     *(f32x4*)(X + (size_t)r * DM + c) = x0; *(f32x4*)(X + (size_t)r * DM + c + 4) = x1;
;   });
; }
	s_waitcnt lgkmcnt(0)
	s_setprio 1
	s_waitcnt lgkmcnt(0)
	v_mfma_f32_16x16x32_bf16 v[62:65], v[158:161], v[174:177], v[62:65]
	v_mfma_f32_16x16x32_bf16 v[58:61], v[166:169], v[174:177], v[58:61]
	v_mfma_f32_16x16x32_bf16 v[46:49], v[158:161], v[182:185], v[46:49]
	v_mfma_f32_16x16x32_bf16 v[42:45], v[166:169], v[182:185], v[42:45]
	v_mfma_f32_16x16x32_bf16 v[30:33], v[158:161], v[198:201], v[30:33]
	v_mfma_f32_16x16x32_bf16 v[26:29], v[166:169], v[198:201], v[26:29]
	v_mfma_f32_16x16x32_bf16 v[14:17], v[158:161], v[206:209], v[14:17]
	v_mfma_f32_16x16x32_bf16 v[10:13], v[166:169], v[206:209], v[10:13]
	v_mfma_f32_16x16x32_bf16 v[62:65], v[162:165], v[178:181], v[62:65]
	v_mfma_f32_16x16x32_bf16 v[58:61], v[170:173], v[178:181], v[58:61]
	v_mfma_f32_16x16x32_bf16 v[46:49], v[162:165], v[186:189], v[46:49]
	v_mfma_f32_16x16x32_bf16 v[42:45], v[170:173], v[186:189], v[42:45]
	v_mfma_f32_16x16x32_bf16 v[30:33], v[162:165], v[202:205], v[30:33]
	v_mfma_f32_16x16x32_bf16 v[26:29], v[170:173], v[202:205], v[26:29]
	v_mfma_f32_16x16x32_bf16 v[14:17], v[162:165], v[210:213], v[14:17]
	v_mfma_f32_16x16x32_bf16 v[10:13], v[170:173], v[210:213], v[10:13]
	s_setprio 0
	s_barrier
	v_readfirstlane_b32 s18, v145
	v_lshl_add_u64 v[158:159], v[230:231], 0, s[60:61]
	s_mov_b32 m0, s18
	v_readfirstlane_b32 s18, v146
	global_load_lds_dwordx4 v[158:159], off
	v_lshl_add_u64 v[158:159], v[230:231], 0, s[64:65]
	s_mov_b32 m0, s18
	s_nop 0
	global_load_lds_dwordx4 v[158:159], off
	s_waitcnt vmcnt(6)
	s_barrier
	s_setprio 1
	v_mfma_f32_16x16x32_bf16 v[54:57], v[214:217], v[174:177], v[54:57]
	v_mfma_f32_16x16x32_bf16 v[50:53], v[222:225], v[174:177], v[50:53]
	v_mfma_f32_16x16x32_bf16 v[38:41], v[214:217], v[182:185], v[38:41]
	v_mfma_f32_16x16x32_bf16 v[34:37], v[222:225], v[182:185], v[34:37]
	v_mfma_f32_16x16x32_bf16 v[22:25], v[214:217], v[198:201], v[22:25]
	v_mfma_f32_16x16x32_bf16 v[18:21], v[222:225], v[198:201], v[18:21]
	v_mfma_f32_16x16x32_bf16 v[6:9], v[214:217], v[206:209], v[6:9]
	v_mfma_f32_16x16x32_bf16 v[2:5], v[222:225], v[206:209], v[2:5]
	v_mfma_f32_16x16x32_bf16 v[54:57], v[218:221], v[178:181], v[54:57]
	v_mfma_f32_16x16x32_bf16 v[50:53], v[226:229], v[178:181], v[50:53]
	v_mfma_f32_16x16x32_bf16 v[38:41], v[218:221], v[186:189], v[38:41]
	v_mfma_f32_16x16x32_bf16 v[34:37], v[226:229], v[186:189], v[34:37]
	v_mfma_f32_16x16x32_bf16 v[22:25], v[218:221], v[202:205], v[22:25]
	v_mfma_f32_16x16x32_bf16 v[18:21], v[226:229], v[202:205], v[18:21]
	v_mfma_f32_16x16x32_bf16 v[6:9], v[218:221], v[210:213], v[6:9]
	v_mfma_f32_16x16x32_bf16 v[2:5], v[226:229], v[210:213], v[2:5]
	s_setprio 0
	v_lshl_add_u64 v[132:133], v[132:133], 0, s[50:51]
	s_addk_i32 s5, 0x80
	s_barrier
	s_cbranch_vccz .LBB0_1605
	v_readlane_b32 s0, v248, 6
	s_add_u32 s0, s20, s0
	v_readlane_b32 s4, v251, 54
	v_mov_b32_e32 v0, v149
	s_addc_u32 s1, s21, 0
	s_lshl_b32 s4, s4, 2
	s_add_u32 s0, s0, s4
	v_and_b32_e32 v130, 15, v0
	v_ashrrev_i32_e32 v131, 2, v0
	v_lshlrev_b32_e32 v0, 1, v0
	s_addc_u32 s1, s1, 0
	v_and_b32_e32 v0, 0x1e0, v0
	s_movk_i32 s4, 0xffc0
	v_lshl_add_u64 v[132:133], s[0:1], 0, v[0:1]
	s_mov_b64 s[0:1], 0x1f55000
	v_and_or_b32 v136, v131, s4, v130
	v_lshl_add_u64 v[130:131], v[132:133], 0, s[0:1]
	s_mov_b32 s0, 0x1f55000
	v_ashrrev_i32_e32 v137, 31, v136
	v_add_co_u32_e32 v134, vcc, s0, v132
	v_readlane_b32 s0, v252, 6
	s_nop 0
	v_addc_co_u32_e32 v135, vcc, 0, v133, vcc
	v_lshlrev_b64 v[132:133], 12, v[136:137]
	v_readlane_b32 s1, v252, 7
	v_lshl_add_u64 v[132:133], s[0:1], 0, v[132:133]
	v_lshl_add_u64 v[132:133], v[132:133], 0, v[0:1]
	v_mov_b32_e32 v188, v130
	v_mov_b32_e32 v189, v131
	v_mov_b32_e32 v136, v132
	v_mov_b32_e32 v137, v133
	v_mov_b32_e32 v134, v136
	v_mov_b32_e32 v135, v137
	s_nop 0
	global_load_dwordx4 v[152:155], v[188:189], off
	global_load_dwordx4 v[156:159], v[188:189], off offset:16
	global_load_dwordx4 v[160:163], v[188:189], off offset:512
	global_load_dwordx4 v[164:167], v[188:189], off offset:528
	v_mov_b32_e32 v144, v136
	v_mov_b32_e32 v145, v137
	global_load_dwordx4 v[168:171], v[144:145], off
	global_load_dwordx4 v[172:175], v[144:145], off offset:16
	global_load_dwordx4 v[176:179], v[144:145], off offset:512
	global_load_dwordx4 v[180:183], v[144:145], off offset:528
	v_add_co_u32_e32 v146, vcc, 0x10000, v136
	s_nop 1
	v_addc_co_u32_e32 v147, vcc, 0, v137, vcc
	global_load_dwordx4 v[184:187], v[146:147], off
	global_load_dwordx4 v[204:207], v[146:147], off offset:16
	global_load_dwordx4 v[208:211], v[146:147], off offset:512
	global_load_dwordx4 v[212:215], v[146:147], off offset:528
	v_add_co_u32_e32 v144, vcc, 0x20000, v136
	s_nop 1
	v_addc_co_u32_e32 v145, vcc, 0, v137, vcc
	global_load_dwordx4 v[216:219], v[144:145], off
	global_load_dwordx4 v[220:223], v[144:145], off offset:16
	global_load_dwordx4 v[224:227], v[144:145], off offset:512
	global_load_dwordx4 v[228:231], v[144:145], off offset:528
	v_add_co_u32_e32 v146, vcc, 0x30000, v136
	s_nop 1
	v_addc_co_u32_e32 v147, vcc, 0, v137, vcc
	global_load_dwordx4 v[232:235], v[146:147], off
	global_load_dwordx4 v[140:143], v[146:147], off offset:16
	s_waitcnt vmcnt(12)
	v_pk_fma_f32 v[126:127], v[126:127], v[152:153], v[168:169]
	v_pk_fma_f32 v[128:129], v[128:129], v[154:155], v[170:171]
	v_pk_fma_f32 v[122:123], v[122:123], v[156:157], v[172:173]
	v_pk_fma_f32 v[124:125], v[124:125], v[158:159], v[174:175]
	v_mov_b32_e32 v130, v134
	v_mov_b32_e32 v131, v135
	global_store_dwordx4 v[130:131], v[126:129], off
	global_store_dwordx4 v[130:131], v[122:125], off offset:16
	v_add_co_u32_e32 v146, vcc, 0x30000, v136
	s_nop 1
	v_addc_co_u32_e32 v147, vcc, 0, v137, vcc
	global_load_dwordx4 v[126:129], v[146:147], off offset:512
	global_load_dwordx4 v[122:125], v[146:147], off offset:528
	s_waitcnt vmcnt(12)
; DI int otid() { int t = threadIdx.x; asm volatile("" : "+v"(t)); return t; }
; template <class F>
; DI void epi_foreach(acc_t& acc, F f) {
;   const int tid = otid(), wid = tid >> 6, lane = tid & 63, wr = wid >> 2, wc = wid & 3, fr = lane & 15, fq = lane >> 4;
; #pragma unroll
;   for (int ai = 0; ai < 2; ++ai)
; #pragma unroll
;     for (int m = 0; m < 4; ++m) {
; #pragma unroll
;       for (int bj = 0; bj < 2; ++bj) f(ai * 128 + wr * 64 + m * 16 + fr, bj * 128 + wc * 32 + 8 * fq, acc[ai][bj][m][0], acc[ai][bj][m][1]);
;       if (m == 3 && ai == 0) __builtin_amdgcn_sched_barrier(0);
;     }
; DI void residual_tile(acc_t& acc, float* X, const float* gate, const float* Xin = nullptr) {
;   const float* xs = Xin ? Xin : X;
;   epi_foreach(acc, [&](int r, int c, f32x4& v0, f32x4& v1) {
;     const f32x4 g0 = *(const f32x4*)(gate + c), g1 = *(const f32x4*)(gate + c + 4);
;     f32x4 x0 = *(const f32x4*)(xs + (size_t)r * DM + c), x1 = *(const f32x4*)(xs + (size_t)r * DM + c + 4);
;     x0 = x0 + g0 * v0; x1 = x1 + g1 * v1;
;     *(f32x4*)(X + (size_t)r * DM + c) = x0; *(f32x4*)(X + (size_t)r * DM + c + 4) = x1;
;   });
; }
	v_pk_fma_f32 v[118:119], v[118:119], v[160:161], v[176:177]
	v_pk_fma_f32 v[120:121], v[120:121], v[162:163], v[178:179]
	v_pk_fma_f32 v[114:115], v[114:115], v[164:165], v[180:181]
	v_pk_fma_f32 v[116:117], v[116:117], v[166:167], v[182:183]
	global_store_dwordx4 v[130:131], v[118:121], off offset:512
	global_store_dwordx4 v[130:131], v[114:117], off offset:528
	v_add_co_u32_e32 v144, vcc, 0x80000, v136
	s_nop 1
	v_addc_co_u32_e32 v145, vcc, 0, v137, vcc
	global_load_dwordx4 v[118:121], v[144:145], off
	global_load_dwordx4 v[114:117], v[144:145], off offset:16
	s_waitcnt vmcnt(12)
	v_pk_fma_f32 v[110:111], v[110:111], v[152:153], v[184:185]
	v_pk_fma_f32 v[112:113], v[112:113], v[154:155], v[186:187]
	v_pk_fma_f32 v[106:107], v[106:107], v[156:157], v[204:205]
	v_pk_fma_f32 v[108:109], v[108:109], v[158:159], v[206:207]
	v_add_co_u32_e32 v132, vcc, 0x10000, v134
	s_nop 1
	v_addc_co_u32_e32 v133, vcc, 0, v135, vcc
	global_store_dwordx4 v[132:133], v[110:113], off
	global_store_dwordx4 v[132:133], v[106:109], off offset:16
	global_load_dwordx4 v[110:113], v[144:145], off offset:512
	global_load_dwordx4 v[106:109], v[144:145], off offset:528
	s_waitcnt vmcnt(12)
	v_pk_fma_f32 v[102:103], v[102:103], v[160:161], v[208:209]
	v_pk_fma_f32 v[104:105], v[104:105], v[162:163], v[210:211]
	v_pk_fma_f32 v[98:99], v[98:99], v[164:165], v[212:213]
	v_pk_fma_f32 v[100:101], v[100:101], v[166:167], v[214:215]
	global_store_dwordx4 v[132:133], v[102:105], off offset:512
	global_store_dwordx4 v[132:133], v[98:101], off offset:528
	v_add_co_u32_e32 v146, vcc, 0x90000, v136
	s_nop 1
	v_addc_co_u32_e32 v147, vcc, 0, v137, vcc
	global_load_dwordx4 v[102:105], v[146:147], off
	global_load_dwordx4 v[98:101], v[146:147], off offset:16
	s_waitcnt vmcnt(12)
	v_pk_fma_f32 v[94:95], v[94:95], v[152:153], v[216:217]
	v_pk_fma_f32 v[96:97], v[96:97], v[154:155], v[218:219]
	v_pk_fma_f32 v[90:91], v[90:91], v[156:157], v[220:221]
	v_pk_fma_f32 v[92:93], v[92:93], v[158:159], v[222:223]
	v_add_co_u32_e32 v130, vcc, 0x20000, v134
	s_nop 1
	v_addc_co_u32_e32 v131, vcc, 0, v135, vcc
	global_store_dwordx4 v[130:131], v[94:97], off
	global_store_dwordx4 v[130:131], v[90:93], off offset:16
	global_load_dwordx4 v[94:97], v[146:147], off offset:512
	global_load_dwordx4 v[90:93], v[146:147], off offset:528
	s_waitcnt vmcnt(12)
	v_pk_fma_f32 v[86:87], v[86:87], v[160:161], v[224:225]
	v_pk_fma_f32 v[88:89], v[88:89], v[162:163], v[226:227]
	v_pk_fma_f32 v[82:83], v[82:83], v[164:165], v[228:229]
	v_pk_fma_f32 v[84:85], v[84:85], v[166:167], v[230:231]
	global_store_dwordx4 v[130:131], v[86:89], off offset:512
	global_store_dwordx4 v[130:131], v[82:85], off offset:528
	v_add_co_u32_e32 v144, vcc, 0xa0000, v136
	s_nop 1
	v_addc_co_u32_e32 v145, vcc, 0, v137, vcc
	global_load_dwordx4 v[86:89], v[144:145], off
	global_load_dwordx4 v[82:85], v[144:145], off offset:16
	s_waitcnt vmcnt(12)
	v_pk_fma_f32 v[78:79], v[78:79], v[152:153], v[232:233]
	v_pk_fma_f32 v[80:81], v[80:81], v[154:155], v[234:235]
	v_pk_fma_f32 v[74:75], v[74:75], v[156:157], v[140:141]
	v_pk_fma_f32 v[76:77], v[76:77], v[158:159], v[142:143]
	v_add_co_u32_e32 v132, vcc, 0x30000, v134
	s_nop 1
	v_addc_co_u32_e32 v133, vcc, 0, v135, vcc
	global_store_dwordx4 v[132:133], v[78:81], off
	global_store_dwordx4 v[132:133], v[74:77], off offset:16
	global_load_dwordx4 v[78:81], v[144:145], off offset:512
	global_load_dwordx4 v[74:77], v[144:145], off offset:528
	s_waitcnt vmcnt(12)
; #define WAIT_V(n) asm volatile("s_waitcnt vmcnt(" #n ")" ::: "memory")
; #define BAR __builtin_amdgcn_s_barrier()
; template <int lda, int ldb, int K, class Gen, class Epi>
; DI void gemm_stream(Gen gen, Epi epi) {
;     ...
;   WAIT_V(0);
;   if (wr == 0) BAR;
;   BAR;
; DI void residual_tile(acc_t& acc, float* X, const float* gate, const float* Xin = nullptr) {
;   const float* xs = Xin ? Xin : X;
;   epi_foreach(acc, [&](int r, int c, f32x4& v0, f32x4& v1) {
;     const f32x4 g0 = *(const f32x4*)(gate + c), g1 = *(const f32x4*)(gate + c + 4);
;     f32x4 x0 = *(const f32x4*)(xs + (size_t)r * DM + c), x1 = *(const f32x4*)(xs + (size_t)r * DM + c + 4);
;     x0 = x0 + g0 * v0; x1 = x1 + g1 * v1;
;     *(f32x4*)(X + (size_t)r * DM + c) = x0; *(f32x4*)(X + (size_t)r * DM + c + 4) = x1;
;   });
; }
	v_pk_fma_f32 v[70:71], v[70:71], v[160:161], v[126:127]
	v_pk_fma_f32 v[72:73], v[72:73], v[162:163], v[128:129]
	v_pk_fma_f32 v[66:67], v[66:67], v[164:165], v[122:123]
	v_pk_fma_f32 v[68:69], v[68:69], v[166:167], v[124:125]
	global_store_dwordx4 v[132:133], v[70:73], off offset:512
	global_store_dwordx4 v[132:133], v[66:69], off offset:528
	v_add_co_u32_e32 v146, vcc, 0xb0000, v136
	s_nop 1
	v_addc_co_u32_e32 v147, vcc, 0, v137, vcc
	global_load_dwordx4 v[70:73], v[146:147], off
	global_load_dwordx4 v[66:69], v[146:147], off offset:16
	s_waitcnt vmcnt(12)
	v_pk_fma_f32 v[62:63], v[62:63], v[152:153], v[118:119]
	v_pk_fma_f32 v[64:65], v[64:65], v[154:155], v[120:121]
	v_pk_fma_f32 v[58:59], v[58:59], v[156:157], v[114:115]
	v_pk_fma_f32 v[60:61], v[60:61], v[158:159], v[116:117]
	v_add_co_u32_e32 v130, vcc, 0x80000, v134
	s_nop 1
	v_addc_co_u32_e32 v131, vcc, 0, v135, vcc
	global_store_dwordx4 v[130:131], v[62:65], off
	global_store_dwordx4 v[130:131], v[58:61], off offset:16
	global_load_dwordx4 v[62:65], v[146:147], off offset:512
	global_load_dwordx4 v[58:61], v[146:147], off offset:528
	s_waitcnt vmcnt(12)
	v_pk_fma_f32 v[54:55], v[54:55], v[160:161], v[110:111]
	v_pk_fma_f32 v[56:57], v[56:57], v[162:163], v[112:113]
	v_pk_fma_f32 v[50:51], v[50:51], v[164:165], v[106:107]
	v_pk_fma_f32 v[52:53], v[52:53], v[166:167], v[108:109]
	global_store_dwordx4 v[130:131], v[54:57], off offset:512
	global_store_dwordx4 v[130:131], v[50:53], off offset:528
	s_waitcnt vmcnt(10)
	v_pk_fma_f32 v[46:47], v[46:47], v[152:153], v[102:103]
	v_pk_fma_f32 v[48:49], v[48:49], v[154:155], v[104:105]
	v_pk_fma_f32 v[42:43], v[42:43], v[156:157], v[98:99]
	v_pk_fma_f32 v[44:45], v[44:45], v[158:159], v[100:101]
	v_add_co_u32_e32 v132, vcc, 0x90000, v134
	s_nop 1
	v_addc_co_u32_e32 v133, vcc, 0, v135, vcc
	global_store_dwordx4 v[132:133], v[46:49], off
	global_store_dwordx4 v[132:133], v[42:45], off offset:16
	s_waitcnt vmcnt(8)
	v_pk_fma_f32 v[38:39], v[38:39], v[160:161], v[94:95]
	v_pk_fma_f32 v[40:41], v[40:41], v[162:163], v[96:97]
	v_pk_fma_f32 v[34:35], v[34:35], v[164:165], v[90:91]
	v_pk_fma_f32 v[36:37], v[36:37], v[166:167], v[92:93]
	global_store_dwordx4 v[132:133], v[38:41], off offset:512
	global_store_dwordx4 v[132:133], v[34:37], off offset:528
	s_waitcnt vmcnt(6)
	v_pk_fma_f32 v[30:31], v[30:31], v[152:153], v[86:87]
	v_pk_fma_f32 v[32:33], v[32:33], v[154:155], v[88:89]
	v_pk_fma_f32 v[26:27], v[26:27], v[156:157], v[82:83]
	v_pk_fma_f32 v[28:29], v[28:29], v[158:159], v[84:85]
	v_add_co_u32_e32 v130, vcc, 0xa0000, v134
	s_nop 1
	v_addc_co_u32_e32 v131, vcc, 0, v135, vcc
	global_store_dwordx4 v[130:131], v[30:33], off
	global_store_dwordx4 v[130:131], v[26:29], off offset:16
	s_waitcnt vmcnt(4)
	v_pk_fma_f32 v[22:23], v[22:23], v[160:161], v[78:79]
	v_pk_fma_f32 v[24:25], v[24:25], v[162:163], v[80:81]
	v_pk_fma_f32 v[18:19], v[18:19], v[164:165], v[74:75]
	v_pk_fma_f32 v[20:21], v[20:21], v[166:167], v[76:77]
	global_store_dwordx4 v[130:131], v[22:25], off offset:512
	global_store_dwordx4 v[130:131], v[18:21], off offset:528
	s_waitcnt vmcnt(2)
	v_pk_fma_f32 v[14:15], v[14:15], v[152:153], v[70:71]
	v_pk_fma_f32 v[16:17], v[16:17], v[154:155], v[72:73]
	v_pk_fma_f32 v[10:11], v[10:11], v[156:157], v[66:67]
	v_pk_fma_f32 v[12:13], v[12:13], v[158:159], v[68:69]
	v_add_co_u32_e32 v132, vcc, 0xb0000, v134
	s_nop 1
	v_addc_co_u32_e32 v133, vcc, 0, v135, vcc
	global_store_dwordx4 v[132:133], v[14:17], off
	global_store_dwordx4 v[132:133], v[10:13], off offset:16
	s_waitcnt vmcnt(0)
	v_pk_fma_f32 v[6:7], v[6:7], v[160:161], v[62:63]
	v_pk_fma_f32 v[8:9], v[8:9], v[162:163], v[64:65]
	v_pk_fma_f32 v[2:3], v[2:3], v[164:165], v[58:59]
	v_pk_fma_f32 v[4:5], v[4:5], v[166:167], v[60:61]
	global_store_dwordx4 v[132:133], v[6:9], off offset:512
	global_store_dwordx4 v[132:133], v[2:5], off offset:528
	s_movk_i32 s0, 0x100
	v_cmp_gt_u32_e32 vcc, s0, v138
	s_waitcnt vmcnt(0)
	s_and_saveexec_b64 s[0:1], vcc
	s_cbranch_execz .LBB0_1608
	s_barrier

; #define STG_A(P, ptr) do { const bf16_t* _g = (ptr); \
;     __builtin_amdgcn_global_load_lds((const unsigned*)(_g + oa0), (__attribute__((address_space(3))) unsigned*)((P) + tb0), 16, 0, 0); \
;     __builtin_amdgcn_global_load_lds((const unsigned*)(_g + (size_t)64 * lda + oa0), (__attribute__((address_space(3))) unsigned*)((P) + tb1), 16, 0, 0); } while (0)
; #define STG_B(P, ptr) do { const bf16_t* _g = (ptr); \
;     __builtin_amdgcn_global_load_lds((const unsigned*)(_g + ob0), (__attribute__((address_space(3))) unsigned*)((P) + tb0), 16, 0, 0); \
;     __builtin_amdgcn_global_load_lds((const unsigned*)(_g + (size_t)64 * ldb + ob0), (__attribute__((address_space(3))) unsigned*)((P) + tb1), 16, 0, 0); } while (0)
; #define LDA(dst, b, h) _Pragma("unroll") for (int m = 0; m < 4; ++m) _Pragma("unroll") for (int k = 0; k < 2; ++k) \
;     dst[m][k] = *reinterpret_cast<const bf16x8*>(SA(b, h) + lds_byte(wr * 64 + m * 16 + fr, k * 32 + fq * 8))
; #define LDB(dst, b, h) _Pragma("unroll") for (int n = 0; n < 2; ++n) _Pragma("unroll") for (int k = 0; k < 2; ++k) \
;     dst[n][k] = *reinterpret_cast<const bf16x8*>(SB(b, h) + lds_byte(wc * 32 + n * 16 + fr, k * 32 + fq * 8))
; #define MMA(ai, bj, At_, Bt_) do { __builtin_amdgcn_s_setprio(1); \
;     _Pragma("unroll") for (int m = 0; m < 4; ++m) _Pragma("unroll") for (int n = 0; n < 2; ++n) _Pragma("unroll") for (int k = 0; k < 2; ++k) \
;       acc[ai][bj][m][n] = __builtin_amdgcn_mfma_f32_16x16x32_bf16(Bt_[n][k], At_[m][k], acc[ai][bj][m][n], 0, 0, 0); \
;     __builtin_amdgcn_s_setprio(0); } while (0)
; #define WAIT_L(n) asm volatile("s_waitcnt lgkmcnt(" #n ")" ::: "memory")
; #define BAR __builtin_amdgcn_s_barrier()
; #define SCHED __builtin_amdgcn_sched_barrier(0)
; template <int lda, int ldb, int K, class Gen, class Epi>
; DI void gemm_stream(Gen gen, Epi epi) {
;     ...
;       LDB(B0, 0, 0); SCHED; LDA(At, 0, 0); STG_A(SA(1, 1), a1 + (size_t)128 * lda);
;       WAIT_L(8); BAR; WAIT_L(0); MMA(0, 0, At, B0); BAR; SCHED;
;       LDB(B1, 0, 1); STG_B(SB(0, 0), b2);
;       BAR; WAIT_L(0); MMA(0, 1, At, B1); BAR;
;       LDA(At, 0, 1); STG_A(SA(0, 0), a2);
;       BAR; WAIT_L(0); MMA(1, 0, At, B0); BAR; SCHED;
;       STG_B(SB(0, 1), b2 + (size_t)128 * ldb);
.LBB0_1674:
	s_add_i32 s5, s5, 2
	ds_read_b128 v[158:161], v147
	ds_read_b128 v[162:165], v147 offset:1024
	ds_read_b128 v[166:169], v147 offset:2048
	ds_read_b128 v[170:173], v147 offset:3072
	s_cmp_gt_u32 s5, 61
	s_cselect_b64 s[48:49], -1, 0
	s_and_b64 vcc, s[48:49], exec
	s_cselect_b32 s30, 0, s44
	s_lshl_b64 s[48:49], s[30:31], 1
	s_add_u32 s50, s40, s48
	s_addc_u32 s51, s41, s49
	v_add_u32_e32 v197, 0xc000, v135
	ds_read_b128 v[174:177], v150
	ds_read_b128 v[178:181], v150 offset:1024
	ds_read_b128 v[182:185], v152
	ds_read_b128 v[186:189], v152 offset:1024
	ds_read_b128 v[198:201], v153
	ds_read_b128 v[202:205], v153 offset:1024
	ds_read_b128 v[206:209], v154
	ds_read_b128 v[210:213], v154 offset:1024
	v_readfirstlane_b32 s30, v197
	v_add_u32_e32 v197, 0xe000, v135
	s_mov_b32 m0, s30
	v_readfirstlane_b32 s30, v197
	global_load_lds_dwordx4 v[132:133], off
	v_lshl_add_u64 v[214:215], v[132:133], 0, s[52:53]
	s_mov_b32 m0, s30
	s_nop 0
	global_load_lds_dwordx4 v[214:215], off
	s_waitcnt lgkmcnt(8)
	s_barrier
	s_waitcnt lgkmcnt(0)
	s_setprio 1
	s_waitcnt lgkmcnt(0)
	v_mfma_f32_16x16x32_bf16 v[126:129], v[158:161], v[174:177], v[126:129]
	v_mfma_f32_16x16x32_bf16 v[122:125], v[166:169], v[174:177], v[122:125]
	v_mfma_f32_16x16x32_bf16 v[118:121], v[158:161], v[182:185], v[118:121]
	v_mfma_f32_16x16x32_bf16 v[110:113], v[166:169], v[182:185], v[110:113]
	v_mfma_f32_16x16x32_bf16 v[102:105], v[158:161], v[198:201], v[102:105]
	v_mfma_f32_16x16x32_bf16 v[94:97], v[166:169], v[198:201], v[94:97]
	v_mfma_f32_16x16x32_bf16 v[86:89], v[158:161], v[206:209], v[86:89]
	v_mfma_f32_16x16x32_bf16 v[78:81], v[166:169], v[206:209], v[78:81]
	v_mfma_f32_16x16x32_bf16 v[126:129], v[162:165], v[178:181], v[126:129]
	v_mfma_f32_16x16x32_bf16 v[122:125], v[170:173], v[178:181], v[122:125]
	v_mfma_f32_16x16x32_bf16 v[118:121], v[162:165], v[186:189], v[118:121]
	v_mfma_f32_16x16x32_bf16 v[110:113], v[170:173], v[186:189], v[110:113]
	v_mfma_f32_16x16x32_bf16 v[102:105], v[162:165], v[202:205], v[102:105]
	v_mfma_f32_16x16x32_bf16 v[94:97], v[170:173], v[202:205], v[94:97]
	v_mfma_f32_16x16x32_bf16 v[86:89], v[162:165], v[210:213], v[86:89]
	v_mfma_f32_16x16x32_bf16 v[78:81], v[170:173], v[210:213], v[78:81]
	s_setprio 0
	s_barrier
	s_add_u32 s48, s42, s48
	s_addc_u32 s49, s43, s49
	v_readfirstlane_b32 s30, v134
	v_add_u32_e32 v197, 0x2000, v134
	v_lshl_add_u64 v[230:231], v[0:1], 1, s[48:49]
	s_mov_b32 m0, s30
	v_readfirstlane_b32 s30, v197
	ds_read_b128 v[214:217], v155
	ds_read_b128 v[218:221], v155 offset:1024
	ds_read_b128 v[222:225], v155 offset:2048
	ds_read_b128 v[226:229], v155 offset:3072
	global_load_lds_dwordx4 v[230:231], off
	v_lshl_add_u64 v[232:233], v[230:231], 0, s[64:65]
	s_mov_b32 m0, s30
	s_nop 0
	global_load_lds_dwordx4 v[232:233], off
	s_barrier
	s_waitcnt lgkmcnt(0)
	s_setprio 1
	s_waitcnt lgkmcnt(0)
	v_mfma_f32_16x16x32_bf16 v[114:117], v[214:217], v[174:177], v[114:117]
	v_mfma_f32_16x16x32_bf16 v[106:109], v[222:225], v[174:177], v[106:109]
	v_mfma_f32_16x16x32_bf16 v[98:101], v[214:217], v[182:185], v[98:101]
	v_mfma_f32_16x16x32_bf16 v[90:93], v[222:225], v[182:185], v[90:93]
	v_mfma_f32_16x16x32_bf16 v[82:85], v[214:217], v[198:201], v[82:85]
	v_mfma_f32_16x16x32_bf16 v[74:77], v[222:225], v[198:201], v[74:77]
	v_mfma_f32_16x16x32_bf16 v[70:73], v[214:217], v[206:209], v[70:73]
	v_mfma_f32_16x16x32_bf16 v[66:69], v[222:225], v[206:209], v[66:69]
	v_mfma_f32_16x16x32_bf16 v[114:117], v[218:221], v[178:181], v[114:117]
	v_mfma_f32_16x16x32_bf16 v[106:109], v[226:229], v[178:181], v[106:109]
	v_mfma_f32_16x16x32_bf16 v[98:101], v[218:221], v[186:189], v[98:101]
	v_mfma_f32_16x16x32_bf16 v[90:93], v[226:229], v[186:189], v[90:93]
	v_mfma_f32_16x16x32_bf16 v[82:85], v[218:221], v[202:205], v[82:85]
	v_mfma_f32_16x16x32_bf16 v[74:77], v[226:229], v[202:205], v[74:77]
	v_mfma_f32_16x16x32_bf16 v[70:73], v[218:221], v[210:213], v[70:73]
	v_mfma_f32_16x16x32_bf16 v[66:69], v[226:229], v[210:213], v[66:69]
	s_setprio 0
	v_readfirstlane_b32 s30, v135
	v_lshl_add_u64 v[232:233], v[130:131], 1, s[50:51]
	s_mov_b32 m0, s30
	v_readfirstlane_b32 s30, v136
	s_barrier
	ds_read_b128 v[174:177], v150 offset:16384
	ds_read_b128 v[178:181], v150 offset:17408
	ds_read_b128 v[182:185], v152 offset:16384
	ds_read_b128 v[186:189], v152 offset:17408
	ds_read_b128 v[198:201], v153 offset:16384
	ds_read_b128 v[202:205], v153 offset:17408
	ds_read_b128 v[206:209], v154 offset:16384
	ds_read_b128 v[210:213], v154 offset:17408
	global_load_lds_dwordx4 v[232:233], off
	v_lshl_add_u64 v[234:235], v[232:233], 0, s[52:53]
	s_mov_b32 m0, s30
	s_nop 0
	global_load_lds_dwordx4 v[234:235], off
	s_barrier
	s_waitcnt lgkmcnt(0)
	s_setprio 1
	s_waitcnt lgkmcnt(0)
	v_mfma_f32_16x16x32_bf16 v[62:65], v[158:161], v[174:177], v[62:65]
	v_mfma_f32_16x16x32_bf16 v[58:61], v[166:169], v[174:177], v[58:61]
	v_mfma_f32_16x16x32_bf16 v[46:49], v[158:161], v[182:185], v[46:49]
	v_mfma_f32_16x16x32_bf16 v[42:45], v[166:169], v[182:185], v[42:45]
	v_mfma_f32_16x16x32_bf16 v[30:33], v[158:161], v[198:201], v[30:33]
	v_mfma_f32_16x16x32_bf16 v[26:29], v[166:169], v[198:201], v[26:29]
	v_mfma_f32_16x16x32_bf16 v[14:17], v[158:161], v[206:209], v[14:17]
	v_mfma_f32_16x16x32_bf16 v[10:13], v[166:169], v[206:209], v[10:13]
	v_mfma_f32_16x16x32_bf16 v[62:65], v[162:165], v[178:181], v[62:65]
	v_mfma_f32_16x16x32_bf16 v[58:61], v[170:173], v[178:181], v[58:61]
	v_mfma_f32_16x16x32_bf16 v[46:49], v[162:165], v[186:189], v[46:49]
	v_mfma_f32_16x16x32_bf16 v[42:45], v[170:173], v[186:189], v[42:45]
	v_mfma_f32_16x16x32_bf16 v[30:33], v[162:165], v[202:205], v[30:33]
	v_mfma_f32_16x16x32_bf16 v[26:29], v[170:173], v[202:205], v[26:29]
	v_mfma_f32_16x16x32_bf16 v[14:17], v[162:165], v[210:213], v[14:17]
	v_mfma_f32_16x16x32_bf16 v[10:13], v[170:173], v[210:213], v[10:13]
	s_setprio 0
	s_barrier
; #define STG_A(P, ptr) do { const bf16_t* _g = (ptr); \
;     __builtin_amdgcn_global_load_lds((const unsigned*)(_g + oa0), (__attribute__((address_space(3))) unsigned*)((P) + tb0), 16, 0, 0); \
;     __builtin_amdgcn_global_load_lds((const unsigned*)(_g + (size_t)64 * lda + oa0), (__attribute__((address_space(3))) unsigned*)((P) + tb1), 16, 0, 0); } while (0)
; #define STG_B(P, ptr) do { const bf16_t* _g = (ptr); \
;     __builtin_amdgcn_global_load_lds((const unsigned*)(_g + ob0), (__attribute__((address_space(3))) unsigned*)((P) + tb0), 16, 0, 0); \
;     __builtin_amdgcn_global_load_lds((const unsigned*)(_g + (size_t)64 * ldb + ob0), (__attribute__((address_space(3))) unsigned*)((P) + tb1), 16, 0, 0); } while (0)
; #define LDA(dst, b, h) _Pragma("unroll") for (int m = 0; m < 4; ++m) _Pragma("unroll") for (int k = 0; k < 2; ++k) \
;     dst[m][k] = *reinterpret_cast<const bf16x8*>(SA(b, h) + lds_byte(wr * 64 + m * 16 + fr, k * 32 + fq * 8))
; #define LDB(dst, b, h) _Pragma("unroll") for (int n = 0; n < 2; ++n) _Pragma("unroll") for (int k = 0; k < 2; ++k) \
;     dst[n][k] = *reinterpret_cast<const bf16x8*>(SB(b, h) + lds_byte(wc * 32 + n * 16 + fr, k * 32 + fq * 8))
; #define MMA(ai, bj, At_, Bt_) do { __builtin_amdgcn_s_setprio(1); \
;     _Pragma("unroll") for (int m = 0; m < 4; ++m) _Pragma("unroll") for (int n = 0; n < 2; ++n) _Pragma("unroll") for (int k = 0; k < 2; ++k) \
;       acc[ai][bj][m][n] = __builtin_amdgcn_mfma_f32_16x16x32_bf16(Bt_[n][k], At_[m][k], acc[ai][bj][m][n], 0, 0, 0); \
;     __builtin_amdgcn_s_setprio(0); } while (0)
; #define WAIT_V(n) asm volatile("s_waitcnt vmcnt(" #n ")" ::: "memory")
; #define WAIT_L(n) asm volatile("s_waitcnt lgkmcnt(" #n ")" ::: "memory")
; #define BAR __builtin_amdgcn_s_barrier()
; #define SCHED __builtin_amdgcn_sched_barrier(0)
; template <int lda, int ldb, int K, class Gen, class Epi>
; DI void gemm_stream(Gen gen, Epi epi) {
;     ...
;       STG_B(SB(0, 1), b2 + (size_t)128 * ldb);
;       WAIT_V(6); BAR; MMA(1, 1, At, B1); BAR;
;       LDB(B0, 1, 0); SCHED; LDA(At, 1, 0); STG_A(SA(0, 1), a2 + (size_t)128 * lda);
;       WAIT_L(8); BAR; WAIT_L(0); MMA(0, 0, At, B0); BAR; SCHED;
;       LDB(B1, 1, 1); STG_B(SB(1, 0), b2 + 64);
;       BAR; WAIT_L(0); MMA(0, 1, At, B1); BAR;
;       LDA(At, 1, 1); STG_A(SA(1, 0), a2 + 64);
	v_readfirstlane_b32 s30, v137
	v_add_u32_e32 v160, 0x2000, v137
	v_lshl_add_u64 v[158:159], v[230:231], 0, s[66:67]
	s_mov_b32 m0, s30
	v_readfirstlane_b32 s30, v160
	global_load_lds_dwordx4 v[158:159], off
	v_lshl_add_u64 v[158:159], v[230:231], 0, s[68:69]
	s_mov_b32 m0, s30
	s_nop 0
	global_load_lds_dwordx4 v[158:159], off
	s_waitcnt vmcnt(6)
	s_barrier
	s_setprio 1
	v_mfma_f32_16x16x32_bf16 v[54:57], v[214:217], v[174:177], v[54:57]
	v_mfma_f32_16x16x32_bf16 v[50:53], v[222:225], v[174:177], v[50:53]
	v_mfma_f32_16x16x32_bf16 v[38:41], v[214:217], v[182:185], v[38:41]
	v_mfma_f32_16x16x32_bf16 v[34:37], v[222:225], v[182:185], v[34:37]
	v_mfma_f32_16x16x32_bf16 v[22:25], v[214:217], v[198:201], v[22:25]
	v_mfma_f32_16x16x32_bf16 v[18:21], v[222:225], v[198:201], v[18:21]
	v_mfma_f32_16x16x32_bf16 v[6:9], v[214:217], v[206:209], v[6:9]
	v_mfma_f32_16x16x32_bf16 v[2:5], v[222:225], v[206:209], v[2:5]
	v_mfma_f32_16x16x32_bf16 v[54:57], v[218:221], v[178:181], v[54:57]
	v_mfma_f32_16x16x32_bf16 v[50:53], v[226:229], v[178:181], v[50:53]
	v_mfma_f32_16x16x32_bf16 v[38:41], v[218:221], v[186:189], v[38:41]
	v_mfma_f32_16x16x32_bf16 v[34:37], v[226:229], v[186:189], v[34:37]
	v_mfma_f32_16x16x32_bf16 v[22:25], v[218:221], v[202:205], v[22:25]
	v_mfma_f32_16x16x32_bf16 v[18:21], v[226:229], v[202:205], v[18:21]
	v_mfma_f32_16x16x32_bf16 v[6:9], v[218:221], v[210:213], v[6:9]
	v_mfma_f32_16x16x32_bf16 v[2:5], v[226:229], v[210:213], v[2:5]
	s_setprio 0
	s_barrier
	ds_read_b128 v[158:161], v156
	ds_read_b128 v[162:165], v156 offset:1024
	ds_read_b128 v[166:169], v156 offset:2048
	ds_read_b128 v[170:173], v156 offset:3072
	v_readfirstlane_b32 s30, v139
	v_lshl_add_u64 v[214:215], v[232:233], 0, s[54:55]
	s_mov_b32 m0, s30
	v_readfirstlane_b32 s30, v140
	ds_read_b128 v[174:177], v150 offset:32768
	ds_read_b128 v[178:181], v150 offset:33792
	ds_read_b128 v[182:185], v152 offset:32768
	ds_read_b128 v[186:189], v152 offset:33792
	ds_read_b128 v[198:201], v153 offset:32768
	ds_read_b128 v[202:205], v153 offset:33792
	ds_read_b128 v[206:209], v154 offset:32768
	ds_read_b128 v[210:213], v154 offset:33792
	global_load_lds_dwordx4 v[214:215], off
	v_lshl_add_u64 v[214:215], v[232:233], 0, s[56:57]
	s_mov_b32 m0, s30
	s_nop 0
	global_load_lds_dwordx4 v[214:215], off
	s_waitcnt lgkmcnt(8)
	s_barrier
	s_waitcnt lgkmcnt(0)
	s_setprio 1
	s_waitcnt lgkmcnt(0)
	v_mfma_f32_16x16x32_bf16 v[126:129], v[158:161], v[174:177], v[126:129]
	v_mfma_f32_16x16x32_bf16 v[122:125], v[166:169], v[174:177], v[122:125]
	v_mfma_f32_16x16x32_bf16 v[118:121], v[158:161], v[182:185], v[118:121]
	v_mfma_f32_16x16x32_bf16 v[110:113], v[166:169], v[182:185], v[110:113]
	v_mfma_f32_16x16x32_bf16 v[102:105], v[158:161], v[198:201], v[102:105]
	v_mfma_f32_16x16x32_bf16 v[94:97], v[166:169], v[198:201], v[94:97]
	v_mfma_f32_16x16x32_bf16 v[86:89], v[158:161], v[206:209], v[86:89]
	v_mfma_f32_16x16x32_bf16 v[78:81], v[166:169], v[206:209], v[78:81]
	v_mfma_f32_16x16x32_bf16 v[126:129], v[162:165], v[178:181], v[126:129]
	v_mfma_f32_16x16x32_bf16 v[122:125], v[170:173], v[178:181], v[122:125]
	v_mfma_f32_16x16x32_bf16 v[118:121], v[162:165], v[186:189], v[118:121]
	v_mfma_f32_16x16x32_bf16 v[110:113], v[170:173], v[186:189], v[110:113]
	v_mfma_f32_16x16x32_bf16 v[102:105], v[162:165], v[202:205], v[102:105]
	v_mfma_f32_16x16x32_bf16 v[94:97], v[170:173], v[202:205], v[94:97]
	v_mfma_f32_16x16x32_bf16 v[86:89], v[162:165], v[210:213], v[86:89]
	v_mfma_f32_16x16x32_bf16 v[78:81], v[170:173], v[210:213], v[78:81]
	s_setprio 0
	s_barrier
	v_readfirstlane_b32 s30, v141
	v_lshl_add_u64 v[234:235], v[230:231], 0, s[34:35]
	s_mov_b32 m0, s30
	v_readfirstlane_b32 s30, v142
	ds_read_b128 v[214:217], v157
	ds_read_b128 v[218:221], v157 offset:1024
	ds_read_b128 v[222:225], v157 offset:2048
	ds_read_b128 v[226:229], v157 offset:3072
	global_load_lds_dwordx4 v[234:235], off
	v_lshl_add_u64 v[234:235], v[230:231], 0, s[70:71]
	s_mov_b32 m0, s30
	s_nop 0
	global_load_lds_dwordx4 v[234:235], off
	s_barrier
	s_waitcnt lgkmcnt(0)
	s_setprio 1
	s_waitcnt lgkmcnt(0)
	v_mfma_f32_16x16x32_bf16 v[114:117], v[214:217], v[174:177], v[114:117]
	v_mfma_f32_16x16x32_bf16 v[106:109], v[222:225], v[174:177], v[106:109]
	v_mfma_f32_16x16x32_bf16 v[98:101], v[214:217], v[182:185], v[98:101]
	v_mfma_f32_16x16x32_bf16 v[90:93], v[222:225], v[182:185], v[90:93]
	v_mfma_f32_16x16x32_bf16 v[82:85], v[214:217], v[198:201], v[82:85]
	v_mfma_f32_16x16x32_bf16 v[74:77], v[222:225], v[198:201], v[74:77]
	v_mfma_f32_16x16x32_bf16 v[70:73], v[214:217], v[206:209], v[70:73]
	v_mfma_f32_16x16x32_bf16 v[66:69], v[222:225], v[206:209], v[66:69]
	v_mfma_f32_16x16x32_bf16 v[114:117], v[218:221], v[178:181], v[114:117]
	v_mfma_f32_16x16x32_bf16 v[106:109], v[226:229], v[178:181], v[106:109]
	v_mfma_f32_16x16x32_bf16 v[98:101], v[218:221], v[186:189], v[98:101]
	v_mfma_f32_16x16x32_bf16 v[90:93], v[226:229], v[186:189], v[90:93]
	v_mfma_f32_16x16x32_bf16 v[82:85], v[218:221], v[202:205], v[82:85]
	v_mfma_f32_16x16x32_bf16 v[74:77], v[226:229], v[202:205], v[74:77]
	v_mfma_f32_16x16x32_bf16 v[70:73], v[218:221], v[210:213], v[70:73]
	v_mfma_f32_16x16x32_bf16 v[66:69], v[226:229], v[210:213], v[66:69]
	s_setprio 0
	v_readfirstlane_b32 s30, v143
	v_lshl_add_u64 v[234:235], v[232:233], 0, s[34:35]
	s_mov_b32 m0, s30
	v_readfirstlane_b32 s30, v144
	s_barrier
	ds_read_b128 v[174:177], v150 offset:49152
	ds_read_b128 v[178:181], v150 offset:50176
	ds_read_b128 v[182:185], v152 offset:49152
	ds_read_b128 v[186:189], v152 offset:50176
	ds_read_b128 v[198:201], v153 offset:49152
	ds_read_b128 v[202:205], v153 offset:50176
	ds_read_b128 v[206:209], v154 offset:49152
	ds_read_b128 v[210:213], v154 offset:50176
	global_load_lds_dwordx4 v[234:235], off
	v_lshl_add_u64 v[232:233], v[232:233], 0, s[58:59]
	s_mov_b32 m0, s30
	s_nop 0
	global_load_lds_dwordx4 v[232:233], off
	s_barrier
; #define STG_A(P, ptr) do { const bf16_t* _g = (ptr); \
;     __builtin_amdgcn_global_load_lds((const unsigned*)(_g + oa0), (__attribute__((address_space(3))) unsigned*)((P) + tb0), 16, 0, 0); \
;     __builtin_amdgcn_global_load_lds((const unsigned*)(_g + (size_t)64 * lda + oa0), (__attribute__((address_space(3))) unsigned*)((P) + tb1), 16, 0, 0); } while (0)
; #define STG_B(P, ptr) do { const bf16_t* _g = (ptr); \
;     __builtin_amdgcn_global_load_lds((const unsigned*)(_g + ob0), (__attribute__((address_space(3))) unsigned*)((P) + tb0), 16, 0, 0); \
;     __builtin_amdgcn_global_load_lds((const unsigned*)(_g + (size_t)64 * ldb + ob0), (__attribute__((address_space(3))) unsigned*)((P) + tb1), 16, 0, 0); } while (0)
; #define LDA(dst, b, h) _Pragma("unroll") for (int m = 0; m < 4; ++m) _Pragma("unroll") for (int k = 0; k < 2; ++k) \
;     dst[m][k] = *reinterpret_cast<const bf16x8*>(SA(b, h) + lds_byte(wr * 64 + m * 16 + fr, k * 32 + fq * 8))
; #define MMA(ai, bj, At_, Bt_) do { __builtin_amdgcn_s_setprio(1); \
;     _Pragma("unroll") for (int m = 0; m < 4; ++m) _Pragma("unroll") for (int n = 0; n < 2; ++n) _Pragma("unroll") for (int k = 0; k < 2; ++k) \
;       acc[ai][bj][m][n] = __builtin_amdgcn_mfma_f32_16x16x32_bf16(Bt_[n][k], At_[m][k], acc[ai][bj][m][n], 0, 0, 0); \
;     __builtin_amdgcn_s_setprio(0); } while (0)
; #define WAIT_V(n) asm volatile("s_waitcnt vmcnt(" #n ")" ::: "memory")
; #define WAIT_L(n) asm volatile("s_waitcnt lgkmcnt(" #n ")" ::: "memory")
; #define BAR __builtin_amdgcn_s_barrier()
; template <int lda, int ldb, int K, class Gen, class Epi>
; DI void gemm_stream(Gen gen, Epi epi) {
;     ...
;       LDA(At, 1, 1); STG_A(SA(1, 0), a2 + 64);
;       BAR; WAIT_L(0); MMA(1, 0, At, B0); BAR; SCHED;
;       STG_B(SB(1, 1), b2 + (size_t)128 * ldb + 64);
;       WAIT_V(6); BAR; MMA(1, 1, At, B1); BAR;
; DI void residual_tile(acc_t& acc, float* X, const float* gate, const float* Xin = nullptr) {
;   const float* xs = Xin ? Xin : X;
;   epi_foreach(acc, [&](int r, int c, f32x4& v0, f32x4& v1) {
;     const f32x4 g0 = *(const f32x4*)(gate + c), g1 = *(const f32x4*)(gate + c + 4);
;     f32x4 x0 = *(const f32x4*)(xs + (size_t)r * DM + c), x1 = *(const f32x4*)(xs + (size_t)r * DM + c + 4);
;     x0 = x0 + g0 * v0; x1 = x1 + g1 * v1;
;     *(f32x4*)(X + (size_t)r * DM + c) = x0; *(f32x4*)(X + (size_t)r * DM + c + 4) = x1;
;   });
; }
	s_waitcnt lgkmcnt(0)
	s_setprio 1
	s_waitcnt lgkmcnt(0)
	v_mfma_f32_16x16x32_bf16 v[62:65], v[158:161], v[174:177], v[62:65]
	v_mfma_f32_16x16x32_bf16 v[58:61], v[166:169], v[174:177], v[58:61]
	v_mfma_f32_16x16x32_bf16 v[46:49], v[158:161], v[182:185], v[46:49]
	v_mfma_f32_16x16x32_bf16 v[42:45], v[166:169], v[182:185], v[42:45]
	v_mfma_f32_16x16x32_bf16 v[30:33], v[158:161], v[198:201], v[30:33]
	v_mfma_f32_16x16x32_bf16 v[26:29], v[166:169], v[198:201], v[26:29]
	v_mfma_f32_16x16x32_bf16 v[14:17], v[158:161], v[206:209], v[14:17]
	v_mfma_f32_16x16x32_bf16 v[10:13], v[166:169], v[206:209], v[10:13]
	v_mfma_f32_16x16x32_bf16 v[62:65], v[162:165], v[178:181], v[62:65]
	v_mfma_f32_16x16x32_bf16 v[58:61], v[170:173], v[178:181], v[58:61]
	v_mfma_f32_16x16x32_bf16 v[46:49], v[162:165], v[186:189], v[46:49]
	v_mfma_f32_16x16x32_bf16 v[42:45], v[170:173], v[186:189], v[42:45]
	v_mfma_f32_16x16x32_bf16 v[30:33], v[162:165], v[202:205], v[30:33]
	v_mfma_f32_16x16x32_bf16 v[26:29], v[170:173], v[202:205], v[26:29]
	v_mfma_f32_16x16x32_bf16 v[14:17], v[162:165], v[210:213], v[14:17]
	v_mfma_f32_16x16x32_bf16 v[10:13], v[170:173], v[210:213], v[10:13]
	s_setprio 0
	s_barrier
	v_readfirstlane_b32 s30, v145
	v_lshl_add_u64 v[158:159], v[230:231], 0, s[72:73]
	s_mov_b32 m0, s30
	v_readfirstlane_b32 s30, v146
	global_load_lds_dwordx4 v[158:159], off
	v_lshl_add_u64 v[158:159], v[230:231], 0, s[74:75]
	s_mov_b32 m0, s30
	s_nop 0
	global_load_lds_dwordx4 v[158:159], off
	s_waitcnt vmcnt(6)
	s_barrier
	s_setprio 1
	v_mfma_f32_16x16x32_bf16 v[54:57], v[214:217], v[174:177], v[54:57]
	v_mfma_f32_16x16x32_bf16 v[50:53], v[222:225], v[174:177], v[50:53]
	v_mfma_f32_16x16x32_bf16 v[38:41], v[214:217], v[182:185], v[38:41]
	v_mfma_f32_16x16x32_bf16 v[34:37], v[222:225], v[182:185], v[34:37]
	v_mfma_f32_16x16x32_bf16 v[22:25], v[214:217], v[198:201], v[22:25]
	v_mfma_f32_16x16x32_bf16 v[18:21], v[222:225], v[198:201], v[18:21]
	v_mfma_f32_16x16x32_bf16 v[6:9], v[214:217], v[206:209], v[6:9]
	v_mfma_f32_16x16x32_bf16 v[2:5], v[222:225], v[206:209], v[2:5]
	v_mfma_f32_16x16x32_bf16 v[54:57], v[218:221], v[178:181], v[54:57]
	v_mfma_f32_16x16x32_bf16 v[50:53], v[226:229], v[178:181], v[50:53]
	v_mfma_f32_16x16x32_bf16 v[38:41], v[218:221], v[186:189], v[38:41]
	v_mfma_f32_16x16x32_bf16 v[34:37], v[226:229], v[186:189], v[34:37]
	v_mfma_f32_16x16x32_bf16 v[22:25], v[218:221], v[202:205], v[22:25]
	v_mfma_f32_16x16x32_bf16 v[18:21], v[226:229], v[202:205], v[18:21]
	v_mfma_f32_16x16x32_bf16 v[6:9], v[218:221], v[210:213], v[6:9]
	v_mfma_f32_16x16x32_bf16 v[2:5], v[226:229], v[210:213], v[2:5]
	s_setprio 0
	v_lshl_add_u64 v[132:133], v[132:133], 0, s[60:61]
	s_addk_i32 s44, 0x80
	s_barrier
	s_cbranch_vccz .LBB0_1674
	s_ashr_i32 s5, s4, 31
	s_lshl_b64 s[4:5], s[4:5], 12
	s_add_u32 s30, s26, s4
	s_addc_u32 s40, s27, s5
	v_readlane_b32 s4, v254, 37
	v_readlane_b32 s5, v254, 38
	s_lshl_b32 s4, s4, 8
	s_ashr_i32 s5, s4, 31
	s_lshl_b64 s[26:27], s[4:5], 2
	s_add_u32 s4, s30, s26
	s_addc_u32 s5, s40, s27
	s_add_u32 s0, s33, s0
	s_addc_u32 s1, s46, s1
	v_mov_b32_e32 v0, v149
	s_add_u32 s0, s0, s26
	s_movk_i32 s26, 0xffc0
	v_and_b32_e32 v130, 15, v0
	v_ashrrev_i32_e32 v131, 2, v0
	v_and_or_b32 v136, v131, s26, v130
	v_lshlrev_b32_e32 v0, 1, v0
	s_addc_u32 s1, s1, s27
	v_ashrrev_i32_e32 v137, 31, v136
	v_and_b32_e32 v0, 0x1e0, v0
	v_lshl_add_u64 v[130:131], s[0:1], 0, v[0:1]
	s_mov_b32 s0, 0x1f25000
	v_lshlrev_b64 v[132:133], 12, v[136:137]
	v_add_co_u32_e32 v134, vcc, s0, v130
	v_lshl_add_u64 v[132:133], s[4:5], 0, v[132:133]
	s_nop 0
	v_addc_co_u32_e32 v135, vcc, 0, v131, vcc
	v_lshl_add_u64 v[132:133], v[132:133], 0, v[0:1]
	s_mov_b64 s[0:1], 0x1f25000
	v_mov_b32_e32 v188, v134
	v_mov_b32_e32 v189, v135
	v_mov_b32_e32 v136, v132
	v_mov_b32_e32 v137, v133
	v_mov_b32_e32 v134, v136
	v_mov_b32_e32 v135, v137
	s_nop 0
	global_load_dwordx4 v[152:155], v[188:189], off
	global_load_dwordx4 v[156:159], v[188:189], off offset:16
	global_load_dwordx4 v[160:163], v[188:189], off offset:512
	global_load_dwordx4 v[164:167], v[188:189], off offset:528
	v_mov_b32_e32 v144, v136
	v_mov_b32_e32 v145, v137
	global_load_dwordx4 v[168:171], v[144:145], off
	global_load_dwordx4 v[172:175], v[144:145], off offset:16
	global_load_dwordx4 v[176:179], v[144:145], off offset:512
	global_load_dwordx4 v[180:183], v[144:145], off offset:528
	v_add_co_u32_e32 v146, vcc, 0x10000, v136
	s_nop 1
	v_addc_co_u32_e32 v147, vcc, 0, v137, vcc
	global_load_dwordx4 v[184:187], v[146:147], off
	global_load_dwordx4 v[204:207], v[146:147], off offset:16
	global_load_dwordx4 v[208:211], v[146:147], off offset:512
	global_load_dwordx4 v[212:215], v[146:147], off offset:528
	v_add_co_u32_e32 v144, vcc, 0x20000, v136
	s_nop 1
	v_addc_co_u32_e32 v145, vcc, 0, v137, vcc
	global_load_dwordx4 v[216:219], v[144:145], off
	global_load_dwordx4 v[220:223], v[144:145], off offset:16
	global_load_dwordx4 v[224:227], v[144:145], off offset:512
	global_load_dwordx4 v[228:231], v[144:145], off offset:528
	v_add_co_u32_e32 v146, vcc, 0x30000, v136
	s_nop 1
	v_addc_co_u32_e32 v147, vcc, 0, v137, vcc
	global_load_dwordx4 v[232:235], v[146:147], off
	global_load_dwordx4 v[140:143], v[146:147], off offset:16
	s_waitcnt vmcnt(12)
	v_pk_fma_f32 v[126:127], v[126:127], v[152:153], v[168:169]
	v_pk_fma_f32 v[128:129], v[128:129], v[154:155], v[170:171]
	v_pk_fma_f32 v[122:123], v[122:123], v[156:157], v[172:173]
	v_pk_fma_f32 v[124:125], v[124:125], v[158:159], v[174:175]
	v_mov_b32_e32 v130, v134
	v_mov_b32_e32 v131, v135
	global_store_dwordx4 v[130:131], v[126:129], off
	global_store_dwordx4 v[130:131], v[122:125], off offset:16
	v_add_co_u32_e32 v146, vcc, 0x30000, v136
	s_nop 1
	v_addc_co_u32_e32 v147, vcc, 0, v137, vcc
	global_load_dwordx4 v[126:129], v[146:147], off offset:512
	global_load_dwordx4 v[122:125], v[146:147], off offset:528
	s_waitcnt vmcnt(12)
; DI int otid() { int t = threadIdx.x; asm volatile("" : "+v"(t)); return t; }
; template <class F>
; DI void epi_foreach(acc_t& acc, F f) {
;   const int tid = otid(), wid = tid >> 6, lane = tid & 63, wr = wid >> 2, wc = wid & 3, fr = lane & 15, fq = lane >> 4;
; #pragma unroll
;   for (int ai = 0; ai < 2; ++ai)
; #pragma unroll
;     for (int m = 0; m < 4; ++m) {
; #pragma unroll
;       for (int bj = 0; bj < 2; ++bj) f(ai * 128 + wr * 64 + m * 16 + fr, bj * 128 + wc * 32 + 8 * fq, acc[ai][bj][m][0], acc[ai][bj][m][1]);
;       if (m == 3 && ai == 0) __builtin_amdgcn_sched_barrier(0);
;     }
; DI void residual_tile(acc_t& acc, float* X, const float* gate, const float* Xin = nullptr) {
;   const float* xs = Xin ? Xin : X;
;   epi_foreach(acc, [&](int r, int c, f32x4& v0, f32x4& v1) {
;     const f32x4 g0 = *(const f32x4*)(gate + c), g1 = *(const f32x4*)(gate + c + 4);
;     f32x4 x0 = *(const f32x4*)(xs + (size_t)r * DM + c), x1 = *(const f32x4*)(xs + (size_t)r * DM + c + 4);
;     x0 = x0 + g0 * v0; x1 = x1 + g1 * v1;
;     *(f32x4*)(X + (size_t)r * DM + c) = x0; *(f32x4*)(X + (size_t)r * DM + c + 4) = x1;
;   });
; }
	v_pk_fma_f32 v[114:115], v[114:115], v[160:161], v[176:177]
	v_pk_fma_f32 v[116:117], v[116:117], v[162:163], v[178:179]
	v_pk_fma_f32 v[106:107], v[106:107], v[164:165], v[180:181]
	v_pk_fma_f32 v[108:109], v[108:109], v[166:167], v[182:183]
	global_store_dwordx4 v[130:131], v[114:117], off offset:512
	global_store_dwordx4 v[130:131], v[106:109], off offset:528
	v_add_co_u32_e32 v144, vcc, 0x80000, v136
	s_nop 1
	v_addc_co_u32_e32 v145, vcc, 0, v137, vcc
	global_load_dwordx4 v[114:117], v[144:145], off
	global_load_dwordx4 v[106:109], v[144:145], off offset:16
	s_waitcnt vmcnt(12)
	v_pk_fma_f32 v[118:119], v[118:119], v[152:153], v[184:185]
	v_pk_fma_f32 v[120:121], v[120:121], v[154:155], v[186:187]
	v_pk_fma_f32 v[110:111], v[110:111], v[156:157], v[204:205]
	v_pk_fma_f32 v[112:113], v[112:113], v[158:159], v[206:207]
	v_add_co_u32_e32 v132, vcc, 0x10000, v134
	s_nop 1
	v_addc_co_u32_e32 v133, vcc, 0, v135, vcc
	global_store_dwordx4 v[132:133], v[118:121], off
	global_store_dwordx4 v[132:133], v[110:113], off offset:16
	global_load_dwordx4 v[118:121], v[144:145], off offset:512
	global_load_dwordx4 v[110:113], v[144:145], off offset:528
	s_waitcnt vmcnt(12)
	v_pk_fma_f32 v[98:99], v[98:99], v[160:161], v[208:209]
	v_pk_fma_f32 v[100:101], v[100:101], v[162:163], v[210:211]
	v_pk_fma_f32 v[90:91], v[90:91], v[164:165], v[212:213]
	v_pk_fma_f32 v[92:93], v[92:93], v[166:167], v[214:215]
	global_store_dwordx4 v[132:133], v[98:101], off offset:512
	global_store_dwordx4 v[132:133], v[90:93], off offset:528
	v_add_co_u32_e32 v146, vcc, 0x90000, v136
	s_nop 1
	v_addc_co_u32_e32 v147, vcc, 0, v137, vcc
	global_load_dwordx4 v[98:101], v[146:147], off
	global_load_dwordx4 v[90:93], v[146:147], off offset:16
	s_waitcnt vmcnt(12)
	v_pk_fma_f32 v[102:103], v[102:103], v[152:153], v[216:217]
	v_pk_fma_f32 v[104:105], v[104:105], v[154:155], v[218:219]
	v_pk_fma_f32 v[94:95], v[94:95], v[156:157], v[220:221]
	v_pk_fma_f32 v[96:97], v[96:97], v[158:159], v[222:223]
	v_add_co_u32_e32 v130, vcc, 0x20000, v134
	s_nop 1
	v_addc_co_u32_e32 v131, vcc, 0, v135, vcc
	global_store_dwordx4 v[130:131], v[102:105], off
	global_store_dwordx4 v[130:131], v[94:97], off offset:16
	global_load_dwordx4 v[102:105], v[146:147], off offset:512
	global_load_dwordx4 v[94:97], v[146:147], off offset:528
	s_waitcnt vmcnt(12)
	v_pk_fma_f32 v[82:83], v[82:83], v[160:161], v[224:225]
	v_pk_fma_f32 v[84:85], v[84:85], v[162:163], v[226:227]
	v_pk_fma_f32 v[74:75], v[74:75], v[164:165], v[228:229]
	v_pk_fma_f32 v[76:77], v[76:77], v[166:167], v[230:231]
	global_store_dwordx4 v[130:131], v[82:85], off offset:512
	global_store_dwordx4 v[130:131], v[74:77], off offset:528
	v_add_co_u32_e32 v144, vcc, 0xa0000, v136
	s_nop 1
	v_addc_co_u32_e32 v145, vcc, 0, v137, vcc
	global_load_dwordx4 v[82:85], v[144:145], off
	global_load_dwordx4 v[74:77], v[144:145], off offset:16
	s_waitcnt vmcnt(12)
	v_pk_fma_f32 v[86:87], v[86:87], v[152:153], v[232:233]
	v_pk_fma_f32 v[88:89], v[88:89], v[154:155], v[234:235]
	v_pk_fma_f32 v[78:79], v[78:79], v[156:157], v[140:141]
	v_pk_fma_f32 v[80:81], v[80:81], v[158:159], v[142:143]
	v_add_co_u32_e32 v132, vcc, 0x30000, v134
	s_nop 1
	v_addc_co_u32_e32 v133, vcc, 0, v135, vcc
	global_store_dwordx4 v[132:133], v[86:89], off
	global_store_dwordx4 v[132:133], v[78:81], off offset:16
	global_load_dwordx4 v[86:89], v[144:145], off offset:512
	global_load_dwordx4 v[78:81], v[144:145], off offset:528
	s_waitcnt vmcnt(12)
; #define WAIT_V(n) asm volatile("s_waitcnt vmcnt(" #n ")" ::: "memory")
; #define BAR __builtin_amdgcn_s_barrier()
; template <int lda, int ldb, int K, class Gen, class Epi>
; DI void gemm_stream(Gen gen, Epi epi) {
;     ...
;   WAIT_V(0);
;   if (wr == 0) BAR;
;   BAR;
; DI void residual_tile(acc_t& acc, float* X, const float* gate, const float* Xin = nullptr) {
;   const float* xs = Xin ? Xin : X;
;   epi_foreach(acc, [&](int r, int c, f32x4& v0, f32x4& v1) {
;     const f32x4 g0 = *(const f32x4*)(gate + c), g1 = *(const f32x4*)(gate + c + 4);
;     f32x4 x0 = *(const f32x4*)(xs + (size_t)r * DM + c), x1 = *(const f32x4*)(xs + (size_t)r * DM + c + 4);
;     x0 = x0 + g0 * v0; x1 = x1 + g1 * v1;
;     *(f32x4*)(X + (size_t)r * DM + c) = x0; *(f32x4*)(X + (size_t)r * DM + c + 4) = x1;
;   });
; }
	v_pk_fma_f32 v[70:71], v[70:71], v[160:161], v[126:127]
	v_pk_fma_f32 v[72:73], v[72:73], v[162:163], v[128:129]
	v_pk_fma_f32 v[66:67], v[66:67], v[164:165], v[122:123]
	v_pk_fma_f32 v[68:69], v[68:69], v[166:167], v[124:125]
	global_store_dwordx4 v[132:133], v[70:73], off offset:512
	global_store_dwordx4 v[132:133], v[66:69], off offset:528
	v_add_co_u32_e32 v146, vcc, 0xb0000, v136
	s_nop 1
	v_addc_co_u32_e32 v147, vcc, 0, v137, vcc
	global_load_dwordx4 v[70:73], v[146:147], off
	global_load_dwordx4 v[66:69], v[146:147], off offset:16
	s_waitcnt vmcnt(12)
	v_pk_fma_f32 v[62:63], v[62:63], v[152:153], v[114:115]
	v_pk_fma_f32 v[64:65], v[64:65], v[154:155], v[116:117]
	v_pk_fma_f32 v[58:59], v[58:59], v[156:157], v[106:107]
	v_pk_fma_f32 v[60:61], v[60:61], v[158:159], v[108:109]
	v_add_co_u32_e32 v130, vcc, 0x80000, v134
	s_nop 1
	v_addc_co_u32_e32 v131, vcc, 0, v135, vcc
	global_store_dwordx4 v[130:131], v[62:65], off
	global_store_dwordx4 v[130:131], v[58:61], off offset:16
	global_load_dwordx4 v[62:65], v[146:147], off offset:512
	global_load_dwordx4 v[58:61], v[146:147], off offset:528
	s_waitcnt vmcnt(12)
	v_pk_fma_f32 v[54:55], v[54:55], v[160:161], v[118:119]
	v_pk_fma_f32 v[56:57], v[56:57], v[162:163], v[120:121]
	v_pk_fma_f32 v[50:51], v[50:51], v[164:165], v[110:111]
	v_pk_fma_f32 v[52:53], v[52:53], v[166:167], v[112:113]
	global_store_dwordx4 v[130:131], v[54:57], off offset:512
	global_store_dwordx4 v[130:131], v[50:53], off offset:528
	s_waitcnt vmcnt(10)
	v_pk_fma_f32 v[46:47], v[46:47], v[152:153], v[98:99]
	v_pk_fma_f32 v[48:49], v[48:49], v[154:155], v[100:101]
	v_pk_fma_f32 v[42:43], v[42:43], v[156:157], v[90:91]
	v_pk_fma_f32 v[44:45], v[44:45], v[158:159], v[92:93]
	v_add_co_u32_e32 v132, vcc, 0x90000, v134
	s_nop 1
	v_addc_co_u32_e32 v133, vcc, 0, v135, vcc
	global_store_dwordx4 v[132:133], v[46:49], off
	global_store_dwordx4 v[132:133], v[42:45], off offset:16
	s_waitcnt vmcnt(8)
	v_pk_fma_f32 v[38:39], v[38:39], v[160:161], v[102:103]
	v_pk_fma_f32 v[40:41], v[40:41], v[162:163], v[104:105]
	v_pk_fma_f32 v[34:35], v[34:35], v[164:165], v[94:95]
	v_pk_fma_f32 v[36:37], v[36:37], v[166:167], v[96:97]
	global_store_dwordx4 v[132:133], v[38:41], off offset:512
	global_store_dwordx4 v[132:133], v[34:37], off offset:528
	s_waitcnt vmcnt(6)
	v_pk_fma_f32 v[30:31], v[30:31], v[152:153], v[82:83]
	v_pk_fma_f32 v[32:33], v[32:33], v[154:155], v[84:85]
	v_pk_fma_f32 v[26:27], v[26:27], v[156:157], v[74:75]
	v_pk_fma_f32 v[28:29], v[28:29], v[158:159], v[76:77]
	v_add_co_u32_e32 v130, vcc, 0xa0000, v134
	s_nop 1
	v_addc_co_u32_e32 v131, vcc, 0, v135, vcc
	global_store_dwordx4 v[130:131], v[30:33], off
	global_store_dwordx4 v[130:131], v[26:29], off offset:16
	s_waitcnt vmcnt(4)
	v_pk_fma_f32 v[22:23], v[22:23], v[160:161], v[86:87]
	v_pk_fma_f32 v[24:25], v[24:25], v[162:163], v[88:89]
	v_pk_fma_f32 v[18:19], v[18:19], v[164:165], v[78:79]
	v_pk_fma_f32 v[20:21], v[20:21], v[166:167], v[80:81]
	global_store_dwordx4 v[130:131], v[22:25], off offset:512
	global_store_dwordx4 v[130:131], v[18:21], off offset:528
	s_waitcnt vmcnt(2)
	v_pk_fma_f32 v[14:15], v[14:15], v[152:153], v[70:71]
	v_pk_fma_f32 v[16:17], v[16:17], v[154:155], v[72:73]
	v_pk_fma_f32 v[10:11], v[10:11], v[156:157], v[66:67]
	v_pk_fma_f32 v[12:13], v[12:13], v[158:159], v[68:69]
	v_add_co_u32_e32 v132, vcc, 0xb0000, v134
	s_nop 1
	v_addc_co_u32_e32 v133, vcc, 0, v135, vcc
	global_store_dwordx4 v[132:133], v[14:17], off
	global_store_dwordx4 v[132:133], v[10:13], off offset:16
	s_waitcnt vmcnt(0)
	v_pk_fma_f32 v[6:7], v[6:7], v[160:161], v[62:63]
	v_pk_fma_f32 v[8:9], v[8:9], v[162:163], v[64:65]
	v_pk_fma_f32 v[2:3], v[2:3], v[164:165], v[58:59]
	v_pk_fma_f32 v[4:5], v[4:5], v[166:167], v[60:61]
	global_store_dwordx4 v[132:133], v[6:9], off offset:512
	global_store_dwordx4 v[132:133], v[2:5], off offset:528
	s_movk_i32 s0, 0x100
	v_cmp_gt_u32_e32 vcc, s0, v138
	s_waitcnt vmcnt(0)
	s_and_saveexec_b64 s[0:1], vcc
	s_cbranch_execz .LBB0_1662
	s_barrier
	s_branch .LBB0_1662
